# out-proj and MLP-down epilogues: residual loads hoisted and (n=0,n=1) dwordx2 pairs merged into dwordx4 accesses via v_permlane16_swap (8 sites)
# speedup vs baseline: 1.0279x; 1.0123x over previous
.LBB0_609:
	v_lshl_add_u32 v142, s26, 8, v144
	v_ashrrev_i32_e32 v143, 31, v142
	v_lshl_or_b32 v140, s8, 8, v146
	v_lshlrev_b64 v[150:151], 11, v[142:143]
	v_ashrrev_i32_e32 v141, 31, v140
	v_lshl_add_u64 v[150:151], s[2:3], 0, v[150:151]
	v_lshl_add_u64 v[150:151], v[140:141], 1, v[150:151]
	s_mov_b64 s[98:99], 0x8000
	s_mov_b64 s[100:101], 0x28000
	v_bfe_u32 v248, v206, 4, 1
	v_mul_u32_u24_e32 v248, 24, v248
	v_mov_b32_e32 v249, 0
	v_lshl_add_u64 v[250:251], v[150:151], 0, v[248:249]
	global_load_dwordx4 v[156:159], v[250:251], off
	global_load_dwordx4 v[160:163], v[250:251], off offset:256
	v_lshl_add_u64 v[250:251], v[250:251], 0, s[98:99]
	global_load_dwordx4 v[164:167], v[250:251], off
	global_load_dwordx4 v[184:187], v[250:251], off offset:256
	v_lshl_add_u64 v[250:251], v[250:251], 0, s[98:99]
	global_load_dwordx4 v[188:191], v[250:251], off
	global_load_dwordx4 v[192:195], v[250:251], off offset:256
	v_lshl_add_u64 v[250:251], v[250:251], 0, s[98:99]
	global_load_dwordx4 v[196:199], v[250:251], off
	global_load_dwordx4 v[200:203], v[250:251], off offset:256
	v_lshl_add_u64 v[250:251], v[250:251], 0, s[100:101]
	global_load_dwordx4 v[208:211], v[250:251], off
	global_load_dwordx4 v[212:215], v[250:251], off offset:256
	v_lshl_add_u64 v[250:251], v[250:251], 0, s[98:99]
	global_load_dwordx4 v[216:219], v[250:251], off
	global_load_dwordx4 v[220:223], v[250:251], off offset:256
	v_lshl_add_u64 v[250:251], v[250:251], 0, s[98:99]
	global_load_dwordx4 v[224:227], v[250:251], off
	global_load_dwordx4 v[228:231], v[250:251], off offset:256
	v_lshl_add_u64 v[250:251], v[250:251], 0, s[98:99]
	global_load_dwordx4 v[232:235], v[250:251], off
	global_load_dwordx4 v[236:239], v[250:251], off offset:256
	s_lshl_b32 s26, s8, 2
	s_ashr_i32 s27, s26, 31
	s_waitcnt vmcnt(15)
	v_permlane16_swap_b32_e32 v156, v158
	v_permlane16_swap_b32_e32 v157, v159
	v_lshlrev_b32_e32 v154, 16, v156
	v_and_b32_e32 v155, 0xffff0000, v156
	v_lshlrev_b32_e32 v152, 16, v157
	v_and_b32_e32 v153, 0xffff0000, v157
	v_pk_add_f32 v[126:127], v[126:127], v[152:153]
	v_pk_add_f32 v[124:125], v[124:125], v[154:155]
	s_nop 0
	v_cvt_pk_bf16_f32 v152, v124, v125
	v_cvt_pk_bf16_f32 v153, v126, v127
	v_mul_f32_e32 v125, v125, v125
	v_mov_b32_e32 v240, v152
	v_mov_b32_e32 v241, v153
	v_mul_f32_e32 v127, v127, v127
	v_fmac_f32_e32 v125, v124, v124
	v_fmac_f32_e32 v127, v126, v126
	v_add_f32_e32 v124, v125, v127
	s_waitcnt vmcnt(15)
	v_lshlrev_b32_e32 v152, 16, v158
	v_and_b32_e32 v153, 0xffff0000, v158
	v_lshlrev_b32_e32 v154, 16, v159
	v_and_b32_e32 v155, 0xffff0000, v159
	v_pk_add_f32 v[122:123], v[122:123], v[154:155]
	v_pk_add_f32 v[120:121], v[120:121], v[152:153]
	s_nop 0
	v_cvt_pk_bf16_f32 v152, v120, v121
	v_cvt_pk_bf16_f32 v153, v122, v123
	v_mul_f32_e32 v121, v121, v121
	v_mov_b32_e32 v242, v152
	v_mov_b32_e32 v243, v153
	v_lshl_add_u64 v[250:251], v[150:151], 0, v[248:249]
	s_nop 0
	v_permlane16_swap_b32_e32 v240, v242
	v_permlane16_swap_b32_e32 v241, v243
	global_store_dwordx4 v[250:251], v[240:243], off
	v_mul_f32_e32 v123, v123, v123
	v_fmac_f32_e32 v121, v120, v120
	v_fmac_f32_e32 v123, v122, v122
	v_add_f32_e32 v120, v121, v123
	v_add_f32_e32 v120, v124, v120
	s_waitcnt vmcnt(15)
	v_permlane16_swap_b32_e32 v160, v162
	v_permlane16_swap_b32_e32 v161, v163
	v_lshlrev_b32_e32 v152, 16, v160
	v_and_b32_e32 v153, 0xffff0000, v160
	v_lshlrev_b32_e32 v154, 16, v161
	v_and_b32_e32 v155, 0xffff0000, v161
	v_pk_add_f32 v[118:119], v[118:119], v[154:155]
	v_pk_add_f32 v[116:117], v[116:117], v[152:153]
	s_nop 0
	v_cvt_pk_bf16_f32 v152, v116, v117
	v_cvt_pk_bf16_f32 v153, v118, v119
	v_mul_f32_e32 v117, v117, v117
	v_mul_f32_e32 v119, v119, v119
	v_fmac_f32_e32 v117, v116, v116
	v_fmac_f32_e32 v119, v118, v118
	v_add_f32_e32 v116, v117, v119
	v_add_f32_e32 v120, v120, v116
	v_mov_b32_e32 v244, v152
	v_mov_b32_e32 v245, v153
	s_waitcnt vmcnt(15)
	v_lshlrev_b32_e32 v116, 16, v162
	v_and_b32_e32 v117, 0xffff0000, v162
	v_lshlrev_b32_e32 v118, 16, v163
	v_and_b32_e32 v119, 0xffff0000, v163
	v_pk_add_f32 v[114:115], v[114:115], v[118:119]
	v_pk_add_f32 v[112:113], v[112:113], v[116:117]
	v_mul_f32_e32 v117, v115, v115
	v_mul_f32_e32 v116, v113, v113
	v_fmac_f32_e32 v116, v112, v112
	v_fmac_f32_e32 v117, v114, v114
	v_add_f32_e32 v116, v116, v117
	v_add_f32_e32 v116, v120, v116
	ds_swizzle_b32 v117, v116 offset:swizzle(SWAP,16)
	v_cvt_pk_bf16_f32 v112, v112, v113
	v_cvt_pk_bf16_f32 v113, v114, v115
	v_mov_b32_e32 v246, v112
	v_mov_b32_e32 v247, v113
	v_lshl_add_u64 v[250:251], v[150:151], 0, v[248:249]
	s_nop 0
	v_permlane16_swap_b32_e32 v244, v246
	v_permlane16_swap_b32_e32 v245, v247
	global_store_dwordx4 v[250:251], v[244:247], off offset:256
	s_waitcnt lgkmcnt(0)
	v_add_f32_e32 v112, v116, v117
	v_mov_b32_e32 v113, v112
	s_nop 1
	v_permlane32_swap_b32_e32 v112, v113
	s_and_saveexec_b64 s[28:29], s[4:5]
	s_cbranch_execz .LBB0_611
	v_add_f32_e32 v114, v112, v113
	v_lshlrev_b64 v[112:113], 6, v[142:143]
	v_lshl_add_u64 v[112:113], s[12:13], 0, v[112:113]
	v_lshl_add_u64 v[112:113], s[26:27], 2, v[112:113]
	s_lshl_b32 s8, s48, 2
	v_lshl_add_u64 v[112:113], v[112:113], 0, s[8:9]
	global_store_dword v[112:113], v114, off
.LBB0_611:
	s_or_b64 exec, exec, s[28:29]
	v_or_b32_e32 v112, 16, v142
	v_ashrrev_i32_e32 v113, 31, v112
	v_lshlrev_b64 v[114:115], 11, v[112:113]
	v_lshl_add_u64 v[114:115], s[2:3], 0, v[114:115]
	v_lshl_add_u64 v[114:115], v[140:141], 1, v[114:115]
	s_waitcnt vmcnt(15)
	v_permlane16_swap_b32_e32 v164, v166
	v_permlane16_swap_b32_e32 v165, v167
	v_lshlrev_b32_e32 v118, 16, v164
	v_and_b32_e32 v119, 0xffff0000, v164
	v_lshlrev_b32_e32 v116, 16, v165
	v_and_b32_e32 v117, 0xffff0000, v165
	v_pk_add_f32 v[110:111], v[110:111], v[116:117]
	v_pk_add_f32 v[108:109], v[108:109], v[118:119]
	s_nop 0
	v_cvt_pk_bf16_f32 v116, v108, v109
	v_cvt_pk_bf16_f32 v117, v110, v111
	v_mul_f32_e32 v109, v109, v109
	v_mov_b32_e32 v240, v116
	v_mov_b32_e32 v241, v117
	v_mul_f32_e32 v111, v111, v111
	v_fmac_f32_e32 v109, v108, v108
	v_fmac_f32_e32 v111, v110, v110
	v_add_f32_e32 v108, v109, v111
	s_waitcnt vmcnt(15)
	v_lshlrev_b32_e32 v116, 16, v166
	v_and_b32_e32 v117, 0xffff0000, v166
	v_lshlrev_b32_e32 v118, 16, v167
	v_and_b32_e32 v119, 0xffff0000, v167
	v_pk_add_f32 v[106:107], v[106:107], v[118:119]
	v_pk_add_f32 v[104:105], v[104:105], v[116:117]
	s_nop 0
	v_cvt_pk_bf16_f32 v116, v104, v105
	v_cvt_pk_bf16_f32 v117, v106, v107
	v_mul_f32_e32 v105, v105, v105
	v_mov_b32_e32 v242, v116
	v_mov_b32_e32 v243, v117
	v_lshl_add_u64 v[250:251], v[114:115], 0, v[248:249]
	s_nop 0
	v_permlane16_swap_b32_e32 v240, v242
	v_permlane16_swap_b32_e32 v241, v243
	global_store_dwordx4 v[250:251], v[240:243], off
	v_mul_f32_e32 v107, v107, v107
	v_fmac_f32_e32 v105, v104, v104
	v_fmac_f32_e32 v107, v106, v106
	v_add_f32_e32 v104, v105, v107
	v_add_f32_e32 v104, v108, v104
	s_waitcnt vmcnt(15)
	v_permlane16_swap_b32_e32 v184, v186
	v_permlane16_swap_b32_e32 v185, v187
	v_lshlrev_b32_e32 v116, 16, v184
	v_and_b32_e32 v117, 0xffff0000, v184
	v_lshlrev_b32_e32 v118, 16, v185
	v_and_b32_e32 v119, 0xffff0000, v185
	v_pk_add_f32 v[102:103], v[102:103], v[118:119]
	v_pk_add_f32 v[100:101], v[100:101], v[116:117]
	s_nop 0
	v_cvt_pk_bf16_f32 v116, v100, v101
	v_cvt_pk_bf16_f32 v117, v102, v103
	v_mul_f32_e32 v101, v101, v101
	v_mul_f32_e32 v103, v103, v103
	v_fmac_f32_e32 v101, v100, v100
	v_fmac_f32_e32 v103, v102, v102
	v_add_f32_e32 v100, v101, v103
	v_add_f32_e32 v104, v104, v100
	v_mov_b32_e32 v244, v116
	v_mov_b32_e32 v245, v117
	s_waitcnt vmcnt(15)
	v_lshlrev_b32_e32 v100, 16, v186
	v_and_b32_e32 v101, 0xffff0000, v186
	v_lshlrev_b32_e32 v102, 16, v187
	v_and_b32_e32 v103, 0xffff0000, v187
	v_pk_add_f32 v[98:99], v[98:99], v[102:103]
	v_pk_add_f32 v[96:97], v[96:97], v[100:101]
	v_mul_f32_e32 v101, v99, v99
	v_mul_f32_e32 v100, v97, v97
	v_fmac_f32_e32 v100, v96, v96
	v_fmac_f32_e32 v101, v98, v98
	v_add_f32_e32 v100, v100, v101
	v_add_f32_e32 v100, v104, v100
	ds_swizzle_b32 v101, v100 offset:swizzle(SWAP,16)
	v_cvt_pk_bf16_f32 v96, v96, v97
	v_cvt_pk_bf16_f32 v97, v98, v99
	v_mov_b32_e32 v246, v96
	v_mov_b32_e32 v247, v97
	v_lshl_add_u64 v[250:251], v[114:115], 0, v[248:249]
	s_nop 0
	v_permlane16_swap_b32_e32 v244, v246
	v_permlane16_swap_b32_e32 v245, v247
	global_store_dwordx4 v[250:251], v[244:247], off offset:256
	s_waitcnt lgkmcnt(0)
	v_add_f32_e32 v96, v100, v101
	v_mov_b32_e32 v97, v96
	s_nop 1
	v_permlane32_swap_b32_e32 v96, v97
	s_and_saveexec_b64 s[28:29], s[4:5]
	s_cbranch_execz .LBB0_613
	v_add_f32_e32 v98, v96, v97
	v_lshlrev_b64 v[96:97], 6, v[112:113]
	v_lshl_add_u64 v[96:97], s[12:13], 0, v[96:97]
	v_lshl_add_u64 v[96:97], s[26:27], 2, v[96:97]
	s_lshl_b32 s8, s48, 2
	v_lshl_add_u64 v[96:97], v[96:97], 0, s[8:9]
	global_store_dword v[96:97], v98, off
.LBB0_613:
	s_or_b64 exec, exec, s[28:29]
	v_or_b32_e32 v96, 32, v142
	v_ashrrev_i32_e32 v97, 31, v96
	v_lshlrev_b64 v[98:99], 11, v[96:97]
	v_lshl_add_u64 v[98:99], s[2:3], 0, v[98:99]
	v_lshl_add_u64 v[98:99], v[140:141], 1, v[98:99]
	s_waitcnt vmcnt(15)
	v_permlane16_swap_b32_e32 v188, v190
	v_permlane16_swap_b32_e32 v189, v191
	v_lshlrev_b32_e32 v102, 16, v188
	v_and_b32_e32 v103, 0xffff0000, v188
	v_lshlrev_b32_e32 v100, 16, v189
	v_and_b32_e32 v101, 0xffff0000, v189
	v_pk_add_f32 v[94:95], v[94:95], v[100:101]
	v_pk_add_f32 v[92:93], v[92:93], v[102:103]
	s_nop 0
	v_cvt_pk_bf16_f32 v100, v92, v93
	v_cvt_pk_bf16_f32 v101, v94, v95
	v_mul_f32_e32 v93, v93, v93
	v_mov_b32_e32 v240, v100
	v_mov_b32_e32 v241, v101
	v_mul_f32_e32 v95, v95, v95
	v_fmac_f32_e32 v93, v92, v92
	v_fmac_f32_e32 v95, v94, v94
	v_add_f32_e32 v92, v93, v95
	s_waitcnt vmcnt(15)
	v_lshlrev_b32_e32 v100, 16, v190
	v_and_b32_e32 v101, 0xffff0000, v190
	v_lshlrev_b32_e32 v102, 16, v191
	v_and_b32_e32 v103, 0xffff0000, v191
	v_pk_add_f32 v[90:91], v[90:91], v[102:103]
	v_pk_add_f32 v[88:89], v[88:89], v[100:101]
	s_nop 0
	v_cvt_pk_bf16_f32 v100, v88, v89
	v_cvt_pk_bf16_f32 v101, v90, v91
	v_mul_f32_e32 v89, v89, v89
	v_mov_b32_e32 v242, v100
	v_mov_b32_e32 v243, v101
	v_lshl_add_u64 v[250:251], v[98:99], 0, v[248:249]
	s_nop 0
	v_permlane16_swap_b32_e32 v240, v242
	v_permlane16_swap_b32_e32 v241, v243
	global_store_dwordx4 v[250:251], v[240:243], off
	v_mul_f32_e32 v91, v91, v91
	v_fmac_f32_e32 v89, v88, v88
	v_fmac_f32_e32 v91, v90, v90
	v_add_f32_e32 v88, v89, v91
	v_add_f32_e32 v88, v92, v88
	s_waitcnt vmcnt(15)
	v_permlane16_swap_b32_e32 v192, v194
	v_permlane16_swap_b32_e32 v193, v195
	v_lshlrev_b32_e32 v100, 16, v192
	v_and_b32_e32 v101, 0xffff0000, v192
	v_lshlrev_b32_e32 v102, 16, v193
	v_and_b32_e32 v103, 0xffff0000, v193
	v_pk_add_f32 v[86:87], v[86:87], v[102:103]
	v_pk_add_f32 v[84:85], v[84:85], v[100:101]
	s_nop 0
	v_cvt_pk_bf16_f32 v100, v84, v85
	v_cvt_pk_bf16_f32 v101, v86, v87
	v_mul_f32_e32 v85, v85, v85
	v_mul_f32_e32 v87, v87, v87
	v_fmac_f32_e32 v85, v84, v84
	v_fmac_f32_e32 v87, v86, v86
	v_add_f32_e32 v84, v85, v87
	v_add_f32_e32 v88, v88, v84
	v_mov_b32_e32 v244, v100
	v_mov_b32_e32 v245, v101
	s_waitcnt vmcnt(15)
	v_lshlrev_b32_e32 v84, 16, v194
	v_and_b32_e32 v85, 0xffff0000, v194
	v_lshlrev_b32_e32 v86, 16, v195
	v_and_b32_e32 v87, 0xffff0000, v195
	v_pk_add_f32 v[82:83], v[82:83], v[86:87]
	v_pk_add_f32 v[80:81], v[80:81], v[84:85]
	v_mul_f32_e32 v85, v83, v83
	v_mul_f32_e32 v84, v81, v81
	v_fmac_f32_e32 v84, v80, v80
	v_fmac_f32_e32 v85, v82, v82
	v_add_f32_e32 v84, v84, v85
	v_add_f32_e32 v84, v88, v84
	ds_swizzle_b32 v85, v84 offset:swizzle(SWAP,16)
	v_cvt_pk_bf16_f32 v80, v80, v81
	v_cvt_pk_bf16_f32 v81, v82, v83
	v_mov_b32_e32 v246, v80
	v_mov_b32_e32 v247, v81
	v_lshl_add_u64 v[250:251], v[98:99], 0, v[248:249]
	s_nop 0
	v_permlane16_swap_b32_e32 v244, v246
	v_permlane16_swap_b32_e32 v245, v247
	global_store_dwordx4 v[250:251], v[244:247], off offset:256
	s_waitcnt lgkmcnt(0)
	v_add_f32_e32 v80, v84, v85
	v_mov_b32_e32 v81, v80
	s_nop 1
	v_permlane32_swap_b32_e32 v80, v81
	s_and_saveexec_b64 s[28:29], s[4:5]
	s_cbranch_execz .LBB0_615
	v_add_f32_e32 v82, v80, v81
	v_lshlrev_b64 v[80:81], 6, v[96:97]
	v_lshl_add_u64 v[80:81], s[12:13], 0, v[80:81]
	v_lshl_add_u64 v[80:81], s[26:27], 2, v[80:81]
	s_lshl_b32 s8, s48, 2
	v_lshl_add_u64 v[80:81], v[80:81], 0, s[8:9]
	global_store_dword v[80:81], v82, off
.LBB0_615:
	s_or_b64 exec, exec, s[28:29]
	v_or_b32_e32 v80, 48, v142
	v_ashrrev_i32_e32 v81, 31, v80
	v_lshlrev_b64 v[82:83], 11, v[80:81]
	v_lshl_add_u64 v[82:83], s[2:3], 0, v[82:83]
	v_lshl_add_u64 v[82:83], v[140:141], 1, v[82:83]
	s_waitcnt vmcnt(15)
	v_permlane16_swap_b32_e32 v196, v198
	v_permlane16_swap_b32_e32 v197, v199
	v_lshlrev_b32_e32 v86, 16, v196
	v_and_b32_e32 v87, 0xffff0000, v196
	v_lshlrev_b32_e32 v84, 16, v197
	v_and_b32_e32 v85, 0xffff0000, v197
	v_pk_add_f32 v[78:79], v[78:79], v[84:85]
	v_pk_add_f32 v[76:77], v[76:77], v[86:87]
	s_nop 0
	v_cvt_pk_bf16_f32 v84, v76, v77
	v_cvt_pk_bf16_f32 v85, v78, v79
	v_mul_f32_e32 v77, v77, v77
	v_mov_b32_e32 v240, v84
	v_mov_b32_e32 v241, v85
	v_mul_f32_e32 v79, v79, v79
	v_fmac_f32_e32 v77, v76, v76
	v_fmac_f32_e32 v79, v78, v78
	v_add_f32_e32 v76, v77, v79
	s_waitcnt vmcnt(15)
	v_lshlrev_b32_e32 v84, 16, v198
	v_and_b32_e32 v85, 0xffff0000, v198
	v_lshlrev_b32_e32 v86, 16, v199
	v_and_b32_e32 v87, 0xffff0000, v199
	v_pk_add_f32 v[74:75], v[74:75], v[86:87]
	v_pk_add_f32 v[72:73], v[72:73], v[84:85]
	s_nop 0
	v_cvt_pk_bf16_f32 v84, v72, v73
	v_cvt_pk_bf16_f32 v85, v74, v75
	v_mul_f32_e32 v73, v73, v73
	v_mov_b32_e32 v242, v84
	v_mov_b32_e32 v243, v85
	v_lshl_add_u64 v[250:251], v[82:83], 0, v[248:249]
	s_nop 0
	v_permlane16_swap_b32_e32 v240, v242
	v_permlane16_swap_b32_e32 v241, v243
	global_store_dwordx4 v[250:251], v[240:243], off
	v_mul_f32_e32 v75, v75, v75
	v_fmac_f32_e32 v73, v72, v72
	v_fmac_f32_e32 v75, v74, v74
	v_add_f32_e32 v72, v73, v75
	v_add_f32_e32 v72, v76, v72
	s_waitcnt vmcnt(15)
	v_permlane16_swap_b32_e32 v200, v202
	v_permlane16_swap_b32_e32 v201, v203
	v_lshlrev_b32_e32 v84, 16, v200
	v_and_b32_e32 v85, 0xffff0000, v200
	v_lshlrev_b32_e32 v86, 16, v201
	v_and_b32_e32 v87, 0xffff0000, v201
	v_pk_add_f32 v[70:71], v[70:71], v[86:87]
	v_pk_add_f32 v[68:69], v[68:69], v[84:85]
	s_nop 0
	v_cvt_pk_bf16_f32 v84, v68, v69
	v_cvt_pk_bf16_f32 v85, v70, v71
	v_mul_f32_e32 v69, v69, v69
	v_mul_f32_e32 v71, v71, v71
	v_fmac_f32_e32 v69, v68, v68
	v_fmac_f32_e32 v71, v70, v70
	v_add_f32_e32 v68, v69, v71
	v_add_f32_e32 v72, v72, v68
	v_mov_b32_e32 v244, v84
	v_mov_b32_e32 v245, v85
	s_waitcnt vmcnt(15)
	v_lshlrev_b32_e32 v68, 16, v202
	v_and_b32_e32 v69, 0xffff0000, v202
	v_lshlrev_b32_e32 v70, 16, v203
	v_and_b32_e32 v71, 0xffff0000, v203
	v_pk_add_f32 v[66:67], v[66:67], v[70:71]
	v_pk_add_f32 v[64:65], v[64:65], v[68:69]
	v_mul_f32_e32 v69, v67, v67
	v_mul_f32_e32 v68, v65, v65
	v_fmac_f32_e32 v68, v64, v64
	v_fmac_f32_e32 v69, v66, v66
	v_add_f32_e32 v68, v68, v69
	v_add_f32_e32 v68, v72, v68
	ds_swizzle_b32 v69, v68 offset:swizzle(SWAP,16)
	v_cvt_pk_bf16_f32 v64, v64, v65
	v_cvt_pk_bf16_f32 v65, v66, v67
	v_mov_b32_e32 v246, v64
	v_mov_b32_e32 v247, v65
	v_lshl_add_u64 v[250:251], v[82:83], 0, v[248:249]
	s_nop 0
	v_permlane16_swap_b32_e32 v244, v246
	v_permlane16_swap_b32_e32 v245, v247
	global_store_dwordx4 v[250:251], v[244:247], off offset:256
	s_waitcnt lgkmcnt(0)
	v_add_f32_e32 v64, v68, v69
	v_mov_b32_e32 v65, v64
	s_nop 1
	v_permlane32_swap_b32_e32 v64, v65
	s_and_saveexec_b64 s[28:29], s[4:5]
	s_cbranch_execz .LBB0_617
	v_add_f32_e32 v66, v64, v65
	v_lshlrev_b64 v[64:65], 6, v[80:81]
	v_lshl_add_u64 v[64:65], s[12:13], 0, v[64:65]
	v_lshl_add_u64 v[64:65], s[26:27], 2, v[64:65]
	s_lshl_b32 s8, s48, 2
	v_lshl_add_u64 v[64:65], v[64:65], 0, s[8:9]
	global_store_dword v[64:65], v66, off
.LBB0_617:
	s_or_b64 exec, exec, s[28:29]
	v_add_u32_e32 v64, 0x80, v142
	v_ashrrev_i32_e32 v65, 31, v64
	v_lshlrev_b64 v[66:67], 11, v[64:65]
	v_lshl_add_u64 v[66:67], s[2:3], 0, v[66:67]
	v_lshl_add_u64 v[66:67], v[140:141], 1, v[66:67]
	s_waitcnt vmcnt(15)
	v_permlane16_swap_b32_e32 v208, v210
	v_permlane16_swap_b32_e32 v209, v211
	v_lshlrev_b32_e32 v70, 16, v208
	v_and_b32_e32 v71, 0xffff0000, v208
	v_lshlrev_b32_e32 v68, 16, v209
	v_and_b32_e32 v69, 0xffff0000, v209
	v_pk_add_f32 v[62:63], v[62:63], v[68:69]
	v_pk_add_f32 v[60:61], v[60:61], v[70:71]
	s_nop 0
	v_cvt_pk_bf16_f32 v68, v60, v61
	v_cvt_pk_bf16_f32 v69, v62, v63
	v_mul_f32_e32 v61, v61, v61
	v_mov_b32_e32 v240, v68
	v_mov_b32_e32 v241, v69
	v_mul_f32_e32 v63, v63, v63
	v_fmac_f32_e32 v61, v60, v60
	v_fmac_f32_e32 v63, v62, v62
	v_add_f32_e32 v60, v61, v63
	s_waitcnt vmcnt(15)
	v_lshlrev_b32_e32 v68, 16, v210
	v_and_b32_e32 v69, 0xffff0000, v210
	v_lshlrev_b32_e32 v70, 16, v211
	v_and_b32_e32 v71, 0xffff0000, v211
	v_pk_add_f32 v[58:59], v[58:59], v[70:71]
	v_pk_add_f32 v[56:57], v[56:57], v[68:69]
	s_nop 0
	v_cvt_pk_bf16_f32 v68, v56, v57
	v_cvt_pk_bf16_f32 v69, v58, v59
	v_mul_f32_e32 v57, v57, v57
	v_mov_b32_e32 v242, v68
	v_mov_b32_e32 v243, v69
	v_lshl_add_u64 v[250:251], v[66:67], 0, v[248:249]
	s_nop 0
	v_permlane16_swap_b32_e32 v240, v242
	v_permlane16_swap_b32_e32 v241, v243
	global_store_dwordx4 v[250:251], v[240:243], off
	v_mul_f32_e32 v59, v59, v59
	v_fmac_f32_e32 v57, v56, v56
	v_fmac_f32_e32 v59, v58, v58
	v_add_f32_e32 v56, v57, v59
	v_add_f32_e32 v56, v60, v56
	s_waitcnt vmcnt(15)
	v_permlane16_swap_b32_e32 v212, v214
	v_permlane16_swap_b32_e32 v213, v215
	v_lshlrev_b32_e32 v68, 16, v212
	v_and_b32_e32 v69, 0xffff0000, v212
	v_lshlrev_b32_e32 v70, 16, v213
	v_and_b32_e32 v71, 0xffff0000, v213
	v_pk_add_f32 v[54:55], v[54:55], v[70:71]
	v_pk_add_f32 v[52:53], v[52:53], v[68:69]
	s_nop 0
	v_cvt_pk_bf16_f32 v68, v52, v53
	v_cvt_pk_bf16_f32 v69, v54, v55
	v_mul_f32_e32 v53, v53, v53
	v_mul_f32_e32 v55, v55, v55
	v_fmac_f32_e32 v53, v52, v52
	v_fmac_f32_e32 v55, v54, v54
	v_add_f32_e32 v52, v53, v55
	v_add_f32_e32 v56, v56, v52
	v_mov_b32_e32 v244, v68
	v_mov_b32_e32 v245, v69
	s_waitcnt vmcnt(15)
	v_lshlrev_b32_e32 v52, 16, v214
	v_and_b32_e32 v53, 0xffff0000, v214
	v_lshlrev_b32_e32 v54, 16, v215
	v_and_b32_e32 v55, 0xffff0000, v215
	v_pk_add_f32 v[50:51], v[50:51], v[54:55]
	v_pk_add_f32 v[48:49], v[48:49], v[52:53]
	v_mul_f32_e32 v53, v51, v51
	v_mul_f32_e32 v52, v49, v49
	v_fmac_f32_e32 v52, v48, v48
	v_fmac_f32_e32 v53, v50, v50
	v_add_f32_e32 v52, v52, v53
	v_add_f32_e32 v52, v56, v52
	ds_swizzle_b32 v53, v52 offset:swizzle(SWAP,16)
	v_cvt_pk_bf16_f32 v48, v48, v49
	v_cvt_pk_bf16_f32 v49, v50, v51
	v_mov_b32_e32 v246, v48
	v_mov_b32_e32 v247, v49
	v_lshl_add_u64 v[250:251], v[66:67], 0, v[248:249]
	s_nop 0
	v_permlane16_swap_b32_e32 v244, v246
	v_permlane16_swap_b32_e32 v245, v247
	global_store_dwordx4 v[250:251], v[244:247], off offset:256
	s_waitcnt lgkmcnt(0)
	v_add_f32_e32 v48, v52, v53
	v_mov_b32_e32 v49, v48
	s_nop 1
	v_permlane32_swap_b32_e32 v48, v49
	s_and_saveexec_b64 s[28:29], s[4:5]
	s_cbranch_execz .LBB0_619
	v_add_f32_e32 v50, v48, v49
	v_lshlrev_b64 v[48:49], 6, v[64:65]
	v_lshl_add_u64 v[48:49], s[12:13], 0, v[48:49]
	v_lshl_add_u64 v[48:49], s[26:27], 2, v[48:49]
	s_lshl_b32 s8, s48, 2
	v_lshl_add_u64 v[48:49], v[48:49], 0, s[8:9]
	global_store_dword v[48:49], v50, off
.LBB0_619:
	s_or_b64 exec, exec, s[28:29]
	v_add_u32_e32 v48, 0x90, v142
	v_ashrrev_i32_e32 v49, 31, v48
	v_lshlrev_b64 v[50:51], 11, v[48:49]
	v_lshl_add_u64 v[50:51], s[2:3], 0, v[50:51]
	v_lshl_add_u64 v[50:51], v[140:141], 1, v[50:51]
	s_waitcnt vmcnt(15)
	v_permlane16_swap_b32_e32 v216, v218
	v_permlane16_swap_b32_e32 v217, v219
	v_lshlrev_b32_e32 v54, 16, v216
	v_and_b32_e32 v55, 0xffff0000, v216
	v_lshlrev_b32_e32 v52, 16, v217
	v_and_b32_e32 v53, 0xffff0000, v217
	v_pk_add_f32 v[46:47], v[46:47], v[52:53]
	v_pk_add_f32 v[44:45], v[44:45], v[54:55]
	s_nop 0
	v_cvt_pk_bf16_f32 v52, v44, v45
	v_cvt_pk_bf16_f32 v53, v46, v47
	v_mul_f32_e32 v45, v45, v45
	v_mov_b32_e32 v240, v52
	v_mov_b32_e32 v241, v53
	v_mul_f32_e32 v47, v47, v47
	v_fmac_f32_e32 v45, v44, v44
	v_fmac_f32_e32 v47, v46, v46
	v_add_f32_e32 v44, v45, v47
	s_waitcnt vmcnt(15)
	v_lshlrev_b32_e32 v52, 16, v218
	v_and_b32_e32 v53, 0xffff0000, v218
	v_lshlrev_b32_e32 v54, 16, v219
	v_and_b32_e32 v55, 0xffff0000, v219
	v_pk_add_f32 v[42:43], v[42:43], v[54:55]
	v_pk_add_f32 v[40:41], v[40:41], v[52:53]
	s_nop 0
	v_cvt_pk_bf16_f32 v52, v40, v41
	v_cvt_pk_bf16_f32 v53, v42, v43
	v_mul_f32_e32 v41, v41, v41
	v_mov_b32_e32 v242, v52
	v_mov_b32_e32 v243, v53
	v_lshl_add_u64 v[250:251], v[50:51], 0, v[248:249]
	s_nop 0
	v_permlane16_swap_b32_e32 v240, v242
	v_permlane16_swap_b32_e32 v241, v243
	global_store_dwordx4 v[250:251], v[240:243], off
	v_mul_f32_e32 v43, v43, v43
	v_fmac_f32_e32 v41, v40, v40
	v_fmac_f32_e32 v43, v42, v42
	v_add_f32_e32 v40, v41, v43
	v_add_f32_e32 v40, v44, v40
	s_waitcnt vmcnt(15)
	v_permlane16_swap_b32_e32 v220, v222
	v_permlane16_swap_b32_e32 v221, v223
	v_lshlrev_b32_e32 v52, 16, v220
	v_and_b32_e32 v53, 0xffff0000, v220
	v_lshlrev_b32_e32 v54, 16, v221
	v_and_b32_e32 v55, 0xffff0000, v221
	v_pk_add_f32 v[38:39], v[38:39], v[54:55]
	v_pk_add_f32 v[36:37], v[36:37], v[52:53]
	s_nop 0
	v_cvt_pk_bf16_f32 v52, v36, v37
	v_cvt_pk_bf16_f32 v53, v38, v39
	v_mul_f32_e32 v37, v37, v37
	v_mul_f32_e32 v39, v39, v39
	v_fmac_f32_e32 v37, v36, v36
	v_fmac_f32_e32 v39, v38, v38
	v_add_f32_e32 v36, v37, v39
	v_add_f32_e32 v40, v40, v36
	v_mov_b32_e32 v244, v52
	v_mov_b32_e32 v245, v53
	s_waitcnt vmcnt(15)
	v_lshlrev_b32_e32 v36, 16, v222
	v_and_b32_e32 v37, 0xffff0000, v222
	v_lshlrev_b32_e32 v38, 16, v223
	v_and_b32_e32 v39, 0xffff0000, v223
	v_pk_add_f32 v[34:35], v[34:35], v[38:39]
	v_pk_add_f32 v[32:33], v[32:33], v[36:37]
	v_mul_f32_e32 v37, v35, v35
	v_mul_f32_e32 v36, v33, v33
	v_fmac_f32_e32 v36, v32, v32
	v_fmac_f32_e32 v37, v34, v34
	v_add_f32_e32 v36, v36, v37
	v_add_f32_e32 v36, v40, v36
	ds_swizzle_b32 v37, v36 offset:swizzle(SWAP,16)
	v_cvt_pk_bf16_f32 v32, v32, v33
	v_cvt_pk_bf16_f32 v33, v34, v35
	v_mov_b32_e32 v246, v32
	v_mov_b32_e32 v247, v33
	v_lshl_add_u64 v[250:251], v[50:51], 0, v[248:249]
	s_nop 0
	v_permlane16_swap_b32_e32 v244, v246
	v_permlane16_swap_b32_e32 v245, v247
	global_store_dwordx4 v[250:251], v[244:247], off offset:256
	s_waitcnt lgkmcnt(0)
	v_add_f32_e32 v32, v36, v37
	v_mov_b32_e32 v33, v32
	s_nop 1
	v_permlane32_swap_b32_e32 v32, v33
	s_and_saveexec_b64 s[28:29], s[4:5]
	s_cbranch_execz .LBB0_621
	v_add_f32_e32 v34, v32, v33
	v_lshlrev_b64 v[32:33], 6, v[48:49]
	v_lshl_add_u64 v[32:33], s[12:13], 0, v[32:33]
	v_lshl_add_u64 v[32:33], s[26:27], 2, v[32:33]
	s_lshl_b32 s8, s48, 2
	v_lshl_add_u64 v[32:33], v[32:33], 0, s[8:9]
	global_store_dword v[32:33], v34, off
.LBB0_621:
	s_or_b64 exec, exec, s[28:29]
	v_add_u32_e32 v32, 0xa0, v142
	v_ashrrev_i32_e32 v33, 31, v32
	v_lshlrev_b64 v[34:35], 11, v[32:33]
	v_lshl_add_u64 v[34:35], s[2:3], 0, v[34:35]
	v_lshl_add_u64 v[34:35], v[140:141], 1, v[34:35]
	s_waitcnt vmcnt(15)
	v_permlane16_swap_b32_e32 v224, v226
	v_permlane16_swap_b32_e32 v225, v227
	v_lshlrev_b32_e32 v38, 16, v224
	v_and_b32_e32 v39, 0xffff0000, v224
	v_lshlrev_b32_e32 v36, 16, v225
	v_and_b32_e32 v37, 0xffff0000, v225
	v_pk_add_f32 v[30:31], v[30:31], v[36:37]
	v_pk_add_f32 v[28:29], v[28:29], v[38:39]
	s_nop 0
	v_cvt_pk_bf16_f32 v36, v28, v29
	v_cvt_pk_bf16_f32 v37, v30, v31
	v_mul_f32_e32 v29, v29, v29
	v_mov_b32_e32 v240, v36
	v_mov_b32_e32 v241, v37
	v_mul_f32_e32 v31, v31, v31
	v_fmac_f32_e32 v29, v28, v28
	v_fmac_f32_e32 v31, v30, v30
	v_add_f32_e32 v28, v29, v31
	s_waitcnt vmcnt(15)
	v_lshlrev_b32_e32 v36, 16, v226
	v_and_b32_e32 v37, 0xffff0000, v226
	v_lshlrev_b32_e32 v38, 16, v227
	v_and_b32_e32 v39, 0xffff0000, v227
	v_pk_add_f32 v[26:27], v[26:27], v[38:39]
	v_pk_add_f32 v[24:25], v[24:25], v[36:37]
	s_nop 0
	v_cvt_pk_bf16_f32 v36, v24, v25
	v_cvt_pk_bf16_f32 v37, v26, v27
	v_mul_f32_e32 v25, v25, v25
	v_mov_b32_e32 v242, v36
	v_mov_b32_e32 v243, v37
	v_lshl_add_u64 v[250:251], v[34:35], 0, v[248:249]
	s_nop 0
	v_permlane16_swap_b32_e32 v240, v242
	v_permlane16_swap_b32_e32 v241, v243
	global_store_dwordx4 v[250:251], v[240:243], off
	v_mul_f32_e32 v27, v27, v27
	v_fmac_f32_e32 v25, v24, v24
	v_fmac_f32_e32 v27, v26, v26
	v_add_f32_e32 v24, v25, v27
	v_add_f32_e32 v24, v28, v24
	s_waitcnt vmcnt(15)
	v_permlane16_swap_b32_e32 v228, v230
	v_permlane16_swap_b32_e32 v229, v231
	v_lshlrev_b32_e32 v36, 16, v228
	v_and_b32_e32 v37, 0xffff0000, v228
	v_lshlrev_b32_e32 v38, 16, v229
	v_and_b32_e32 v39, 0xffff0000, v229
	v_pk_add_f32 v[22:23], v[22:23], v[38:39]
	v_pk_add_f32 v[20:21], v[20:21], v[36:37]
	s_nop 0
	v_cvt_pk_bf16_f32 v36, v20, v21
	v_cvt_pk_bf16_f32 v37, v22, v23
	v_mul_f32_e32 v21, v21, v21
	v_mul_f32_e32 v23, v23, v23
	v_fmac_f32_e32 v21, v20, v20
	v_fmac_f32_e32 v23, v22, v22
	v_add_f32_e32 v20, v21, v23
	v_add_f32_e32 v24, v24, v20
	v_mov_b32_e32 v244, v36
	v_mov_b32_e32 v245, v37
	s_waitcnt vmcnt(15)
	v_lshlrev_b32_e32 v20, 16, v230
	v_and_b32_e32 v21, 0xffff0000, v230
	v_lshlrev_b32_e32 v22, 16, v231
	v_and_b32_e32 v23, 0xffff0000, v231
	v_pk_add_f32 v[18:19], v[18:19], v[22:23]
	v_pk_add_f32 v[16:17], v[16:17], v[20:21]
	v_mul_f32_e32 v21, v19, v19
	v_mul_f32_e32 v20, v17, v17
	v_fmac_f32_e32 v20, v16, v16
	v_fmac_f32_e32 v21, v18, v18
	v_add_f32_e32 v20, v20, v21
	v_add_f32_e32 v20, v24, v20
	ds_swizzle_b32 v21, v20 offset:swizzle(SWAP,16)
	v_cvt_pk_bf16_f32 v16, v16, v17
	v_cvt_pk_bf16_f32 v17, v18, v19
	v_mov_b32_e32 v246, v16
	v_mov_b32_e32 v247, v17
	v_lshl_add_u64 v[250:251], v[34:35], 0, v[248:249]
	s_nop 0
	v_permlane16_swap_b32_e32 v244, v246
	v_permlane16_swap_b32_e32 v245, v247
	global_store_dwordx4 v[250:251], v[244:247], off offset:256
	s_waitcnt lgkmcnt(0)
	v_add_f32_e32 v16, v20, v21
	v_mov_b32_e32 v17, v16
	s_nop 1
	v_permlane32_swap_b32_e32 v16, v17
	s_and_saveexec_b64 s[28:29], s[4:5]
	s_cbranch_execz .LBB0_623
	v_add_f32_e32 v18, v16, v17
	v_lshlrev_b64 v[16:17], 6, v[32:33]
	v_lshl_add_u64 v[16:17], s[12:13], 0, v[16:17]
	v_lshl_add_u64 v[16:17], s[26:27], 2, v[16:17]
	s_lshl_b32 s8, s48, 2
	v_lshl_add_u64 v[16:17], v[16:17], 0, s[8:9]
	global_store_dword v[16:17], v18, off
.LBB0_623:
	s_or_b64 exec, exec, s[28:29]
	v_add_u32_e32 v16, 0xb0, v142
	v_ashrrev_i32_e32 v17, 31, v16
	v_lshlrev_b64 v[18:19], 11, v[16:17]
	v_lshl_add_u64 v[18:19], s[2:3], 0, v[18:19]
	v_lshl_add_u64 v[18:19], v[140:141], 1, v[18:19]
	s_waitcnt vmcnt(15)
	v_permlane16_swap_b32_e32 v232, v234
	v_permlane16_swap_b32_e32 v233, v235
	v_lshlrev_b32_e32 v22, 16, v232
	v_and_b32_e32 v23, 0xffff0000, v232
	v_lshlrev_b32_e32 v20, 16, v233
	v_and_b32_e32 v21, 0xffff0000, v233
	v_pk_add_f32 v[14:15], v[14:15], v[20:21]
	v_pk_add_f32 v[12:13], v[12:13], v[22:23]
	s_nop 0
	v_cvt_pk_bf16_f32 v20, v12, v13
	v_cvt_pk_bf16_f32 v21, v14, v15
	v_mul_f32_e32 v13, v13, v13
	v_mov_b32_e32 v240, v20
	v_mov_b32_e32 v241, v21
	v_mul_f32_e32 v15, v15, v15
	v_fmac_f32_e32 v13, v12, v12
	v_fmac_f32_e32 v15, v14, v14
	v_add_f32_e32 v12, v13, v15
	s_waitcnt vmcnt(15)
	v_lshlrev_b32_e32 v20, 16, v234
	v_and_b32_e32 v21, 0xffff0000, v234
	v_lshlrev_b32_e32 v22, 16, v235
	v_and_b32_e32 v23, 0xffff0000, v235
	v_pk_add_f32 v[10:11], v[10:11], v[22:23]
	v_pk_add_f32 v[8:9], v[8:9], v[20:21]
	s_nop 0
	v_cvt_pk_bf16_f32 v20, v8, v9
	v_cvt_pk_bf16_f32 v21, v10, v11
	v_mul_f32_e32 v9, v9, v9
	v_mov_b32_e32 v242, v20
	v_mov_b32_e32 v243, v21
	v_lshl_add_u64 v[250:251], v[18:19], 0, v[248:249]
	s_nop 0
	v_permlane16_swap_b32_e32 v240, v242
	v_permlane16_swap_b32_e32 v241, v243
	global_store_dwordx4 v[250:251], v[240:243], off
	v_mul_f32_e32 v11, v11, v11
	v_fmac_f32_e32 v9, v8, v8
	v_fmac_f32_e32 v11, v10, v10
	v_add_f32_e32 v8, v9, v11
	v_add_f32_e32 v8, v12, v8
	s_waitcnt vmcnt(15)
	v_permlane16_swap_b32_e32 v236, v238
	v_permlane16_swap_b32_e32 v237, v239
	v_lshlrev_b32_e32 v20, 16, v236
	v_and_b32_e32 v21, 0xffff0000, v236
	v_lshlrev_b32_e32 v22, 16, v237
	v_and_b32_e32 v23, 0xffff0000, v237
	v_pk_add_f32 v[6:7], v[6:7], v[22:23]
	v_pk_add_f32 v[4:5], v[4:5], v[20:21]
	s_nop 0
	v_cvt_pk_bf16_f32 v20, v4, v5
	v_cvt_pk_bf16_f32 v21, v6, v7
	v_mul_f32_e32 v5, v5, v5
	v_mul_f32_e32 v7, v7, v7
	v_fmac_f32_e32 v5, v4, v4
	v_fmac_f32_e32 v7, v6, v6
	v_add_f32_e32 v4, v5, v7
	v_add_f32_e32 v8, v8, v4
	v_mov_b32_e32 v244, v20
	v_mov_b32_e32 v245, v21
	s_waitcnt vmcnt(15)
	v_lshlrev_b32_e32 v4, 16, v238
	v_and_b32_e32 v5, 0xffff0000, v238
	v_lshlrev_b32_e32 v6, 16, v239
	v_and_b32_e32 v7, 0xffff0000, v239
	v_pk_add_f32 v[2:3], v[2:3], v[6:7]
	v_pk_add_f32 v[0:1], v[0:1], v[4:5]
	v_mul_f32_e32 v5, v3, v3
	v_mul_f32_e32 v4, v1, v1
	v_fmac_f32_e32 v4, v0, v0
	v_fmac_f32_e32 v5, v2, v2
	v_add_f32_e32 v4, v4, v5
	v_add_f32_e32 v4, v8, v4
	ds_swizzle_b32 v5, v4 offset:swizzle(SWAP,16)
	v_cvt_pk_bf16_f32 v0, v0, v1
	v_cvt_pk_bf16_f32 v1, v2, v3
	v_mov_b32_e32 v246, v0
	v_mov_b32_e32 v247, v1
	v_lshl_add_u64 v[250:251], v[18:19], 0, v[248:249]
	s_nop 0
	v_permlane16_swap_b32_e32 v244, v246
	v_permlane16_swap_b32_e32 v245, v247
	global_store_dwordx4 v[250:251], v[244:247], off offset:256
	s_waitcnt lgkmcnt(0)
	v_add_f32_e32 v0, v4, v5
	v_mov_b32_e32 v1, v0
	s_nop 1
	v_permlane32_swap_b32_e32 v0, v1
	s_and_saveexec_b64 s[28:29], s[4:5]
	s_cbranch_execz .LBB0_625
	v_add_f32_e32 v2, v0, v1
	v_lshlrev_b64 v[0:1], 6, v[16:17]
	v_lshl_add_u64 v[0:1], s[12:13], 0, v[0:1]
	v_lshl_add_u64 v[0:1], s[26:27], 2, v[0:1]
	s_lshl_b32 s8, s48, 2
	v_lshl_add_u64 v[0:1], v[0:1], 0, s[8:9]
	global_store_dword v[0:1], v2, off

.LBB0_781:
	v_lshl_add_u32 v142, s26, 8, v144
	v_ashrrev_i32_e32 v143, 31, v142
	v_lshl_or_b32 v140, s10, 8, v146
	v_lshlrev_b64 v[150:151], 11, v[142:143]
	v_ashrrev_i32_e32 v141, 31, v140
	v_lshl_add_u64 v[150:151], s[8:9], 0, v[150:151]
	v_lshl_add_u64 v[150:151], v[140:141], 1, v[150:151]
	s_mov_b64 s[98:99], 0x8000
	s_mov_b64 s[100:101], 0x28000
	v_bfe_u32 v248, v206, 4, 1
	v_mul_u32_u24_e32 v248, 24, v248
	v_mov_b32_e32 v249, 0
	v_lshl_add_u64 v[250:251], v[150:151], 0, v[248:249]
	global_load_dwordx4 v[156:159], v[250:251], off
	global_load_dwordx4 v[160:163], v[250:251], off offset:256
	v_lshl_add_u64 v[250:251], v[250:251], 0, s[98:99]
	global_load_dwordx4 v[164:167], v[250:251], off
	global_load_dwordx4 v[184:187], v[250:251], off offset:256
	v_lshl_add_u64 v[250:251], v[250:251], 0, s[98:99]
	global_load_dwordx4 v[188:191], v[250:251], off
	global_load_dwordx4 v[192:195], v[250:251], off offset:256
	v_lshl_add_u64 v[250:251], v[250:251], 0, s[98:99]
	global_load_dwordx4 v[196:199], v[250:251], off
	global_load_dwordx4 v[200:203], v[250:251], off offset:256
	v_lshl_add_u64 v[250:251], v[250:251], 0, s[100:101]
	global_load_dwordx4 v[208:211], v[250:251], off
	global_load_dwordx4 v[212:215], v[250:251], off offset:256
	v_lshl_add_u64 v[250:251], v[250:251], 0, s[98:99]
	global_load_dwordx4 v[216:219], v[250:251], off
	global_load_dwordx4 v[220:223], v[250:251], off offset:256
	v_lshl_add_u64 v[250:251], v[250:251], 0, s[98:99]
	global_load_dwordx4 v[224:227], v[250:251], off
	global_load_dwordx4 v[228:231], v[250:251], off offset:256
	v_lshl_add_u64 v[250:251], v[250:251], 0, s[98:99]
	global_load_dwordx4 v[232:235], v[250:251], off
	global_load_dwordx4 v[236:239], v[250:251], off offset:256
	s_lshl_b32 s26, s10, 2
	s_ashr_i32 s27, s26, 31
	s_waitcnt vmcnt(15)
	v_permlane16_swap_b32_e32 v156, v158
	v_permlane16_swap_b32_e32 v157, v159
	v_lshlrev_b32_e32 v154, 16, v156
	v_and_b32_e32 v155, 0xffff0000, v156
	v_lshlrev_b32_e32 v152, 16, v157
	v_and_b32_e32 v153, 0xffff0000, v157
	v_pk_add_f32 v[126:127], v[126:127], v[152:153]
	v_pk_add_f32 v[124:125], v[124:125], v[154:155]
	s_nop 0
	v_cvt_pk_bf16_f32 v152, v124, v125
	v_cvt_pk_bf16_f32 v153, v126, v127
	v_mul_f32_e32 v125, v125, v125
	v_mov_b32_e32 v240, v152
	v_mov_b32_e32 v241, v153
	v_mul_f32_e32 v127, v127, v127
	v_fmac_f32_e32 v125, v124, v124
	v_fmac_f32_e32 v127, v126, v126
	v_add_f32_e32 v124, v125, v127
	s_waitcnt vmcnt(15)
	v_lshlrev_b32_e32 v152, 16, v158
	v_and_b32_e32 v153, 0xffff0000, v158
	v_lshlrev_b32_e32 v154, 16, v159
	v_and_b32_e32 v155, 0xffff0000, v159
	v_pk_add_f32 v[122:123], v[122:123], v[154:155]
	v_pk_add_f32 v[120:121], v[120:121], v[152:153]
	s_nop 0
	v_cvt_pk_bf16_f32 v152, v120, v121
	v_cvt_pk_bf16_f32 v153, v122, v123
	v_mul_f32_e32 v121, v121, v121
	v_mov_b32_e32 v242, v152
	v_mov_b32_e32 v243, v153
	v_lshl_add_u64 v[250:251], v[150:151], 0, v[248:249]
	s_nop 0
	v_permlane16_swap_b32_e32 v240, v242
	v_permlane16_swap_b32_e32 v241, v243
	global_store_dwordx4 v[250:251], v[240:243], off
	v_mul_f32_e32 v123, v123, v123
	v_fmac_f32_e32 v121, v120, v120
	v_fmac_f32_e32 v123, v122, v122
	v_add_f32_e32 v120, v121, v123
	v_add_f32_e32 v120, v124, v120
	s_waitcnt vmcnt(15)
	v_permlane16_swap_b32_e32 v160, v162
	v_permlane16_swap_b32_e32 v161, v163
	v_lshlrev_b32_e32 v152, 16, v160
	v_and_b32_e32 v153, 0xffff0000, v160
	v_lshlrev_b32_e32 v154, 16, v161
	v_and_b32_e32 v155, 0xffff0000, v161
	v_pk_add_f32 v[118:119], v[118:119], v[154:155]
	v_pk_add_f32 v[116:117], v[116:117], v[152:153]
	s_nop 0
	v_cvt_pk_bf16_f32 v152, v116, v117
	v_cvt_pk_bf16_f32 v153, v118, v119
	v_mul_f32_e32 v117, v117, v117
	v_mul_f32_e32 v119, v119, v119
	v_fmac_f32_e32 v117, v116, v116
	v_fmac_f32_e32 v119, v118, v118
	v_add_f32_e32 v116, v117, v119
	v_add_f32_e32 v120, v120, v116
	v_mov_b32_e32 v244, v152
	v_mov_b32_e32 v245, v153
	s_waitcnt vmcnt(15)
	v_lshlrev_b32_e32 v116, 16, v162
	v_and_b32_e32 v117, 0xffff0000, v162
	v_lshlrev_b32_e32 v118, 16, v163
	v_and_b32_e32 v119, 0xffff0000, v163
	v_pk_add_f32 v[114:115], v[114:115], v[118:119]
	v_pk_add_f32 v[112:113], v[112:113], v[116:117]
	v_mul_f32_e32 v117, v115, v115
	v_mul_f32_e32 v116, v113, v113
	v_fmac_f32_e32 v116, v112, v112
	v_fmac_f32_e32 v117, v114, v114
	v_add_f32_e32 v116, v116, v117
	v_add_f32_e32 v116, v120, v116
	ds_swizzle_b32 v117, v116 offset:swizzle(SWAP,16)
	v_cvt_pk_bf16_f32 v112, v112, v113
	v_cvt_pk_bf16_f32 v113, v114, v115
	v_mov_b32_e32 v246, v112
	v_mov_b32_e32 v247, v113
	v_lshl_add_u64 v[250:251], v[150:151], 0, v[248:249]
	s_nop 0
	v_permlane16_swap_b32_e32 v244, v246
	v_permlane16_swap_b32_e32 v245, v247
	global_store_dwordx4 v[250:251], v[244:247], off offset:256
	s_waitcnt lgkmcnt(0)
	v_add_f32_e32 v112, v116, v117
	v_mov_b32_e32 v113, v112
	s_nop 1
	v_permlane32_swap_b32_e32 v112, v113
	s_and_saveexec_b64 s[28:29], s[4:5]
	s_cbranch_execz .LBB0_783
	v_add_f32_e32 v114, v112, v113
	v_lshlrev_b64 v[112:113], 6, v[142:143]
	v_lshl_add_u64 v[112:113], s[2:3], 0, v[112:113]
	v_lshl_add_u64 v[112:113], s[26:27], 2, v[112:113]
	s_lshl_b32 s10, s48, 2
	v_lshl_add_u64 v[112:113], v[112:113], 0, s[10:11]
	global_store_dword v[112:113], v114, off
.LBB0_783:
	s_or_b64 exec, exec, s[28:29]
	v_or_b32_e32 v112, 16, v142
	v_ashrrev_i32_e32 v113, 31, v112
	v_lshlrev_b64 v[114:115], 11, v[112:113]
	v_lshl_add_u64 v[114:115], s[8:9], 0, v[114:115]
	v_lshl_add_u64 v[114:115], v[140:141], 1, v[114:115]
	s_waitcnt vmcnt(15)
	v_permlane16_swap_b32_e32 v164, v166
	v_permlane16_swap_b32_e32 v165, v167
	v_lshlrev_b32_e32 v118, 16, v164
	v_and_b32_e32 v119, 0xffff0000, v164
	v_lshlrev_b32_e32 v116, 16, v165
	v_and_b32_e32 v117, 0xffff0000, v165
	v_pk_add_f32 v[110:111], v[110:111], v[116:117]
	v_pk_add_f32 v[108:109], v[108:109], v[118:119]
	s_nop 0
	v_cvt_pk_bf16_f32 v116, v108, v109
	v_cvt_pk_bf16_f32 v117, v110, v111
	v_mul_f32_e32 v109, v109, v109
	v_mov_b32_e32 v240, v116
	v_mov_b32_e32 v241, v117
	v_mul_f32_e32 v111, v111, v111
	v_fmac_f32_e32 v109, v108, v108
	v_fmac_f32_e32 v111, v110, v110
	v_add_f32_e32 v108, v109, v111
	s_waitcnt vmcnt(15)
	v_lshlrev_b32_e32 v116, 16, v166
	v_and_b32_e32 v117, 0xffff0000, v166
	v_lshlrev_b32_e32 v118, 16, v167
	v_and_b32_e32 v119, 0xffff0000, v167
	v_pk_add_f32 v[106:107], v[106:107], v[118:119]
	v_pk_add_f32 v[104:105], v[104:105], v[116:117]
	s_nop 0
	v_cvt_pk_bf16_f32 v116, v104, v105
	v_cvt_pk_bf16_f32 v117, v106, v107
	v_mul_f32_e32 v105, v105, v105
	v_mov_b32_e32 v242, v116
	v_mov_b32_e32 v243, v117
	v_lshl_add_u64 v[250:251], v[114:115], 0, v[248:249]
	s_nop 0
	v_permlane16_swap_b32_e32 v240, v242
	v_permlane16_swap_b32_e32 v241, v243
	global_store_dwordx4 v[250:251], v[240:243], off
	v_mul_f32_e32 v107, v107, v107
	v_fmac_f32_e32 v105, v104, v104
	v_fmac_f32_e32 v107, v106, v106
	v_add_f32_e32 v104, v105, v107
	v_add_f32_e32 v104, v108, v104
	s_waitcnt vmcnt(15)
	v_permlane16_swap_b32_e32 v184, v186
	v_permlane16_swap_b32_e32 v185, v187
	v_lshlrev_b32_e32 v116, 16, v184
	v_and_b32_e32 v117, 0xffff0000, v184
	v_lshlrev_b32_e32 v118, 16, v185
	v_and_b32_e32 v119, 0xffff0000, v185
	v_pk_add_f32 v[102:103], v[102:103], v[118:119]
	v_pk_add_f32 v[100:101], v[100:101], v[116:117]
	s_nop 0
	v_cvt_pk_bf16_f32 v116, v100, v101
	v_cvt_pk_bf16_f32 v117, v102, v103
	v_mul_f32_e32 v101, v101, v101
	v_mul_f32_e32 v103, v103, v103
	v_fmac_f32_e32 v101, v100, v100
	v_fmac_f32_e32 v103, v102, v102
	v_add_f32_e32 v100, v101, v103
	v_add_f32_e32 v104, v104, v100
	v_mov_b32_e32 v244, v116
	v_mov_b32_e32 v245, v117
	s_waitcnt vmcnt(15)
	v_lshlrev_b32_e32 v100, 16, v186
	v_and_b32_e32 v101, 0xffff0000, v186
	v_lshlrev_b32_e32 v102, 16, v187
	v_and_b32_e32 v103, 0xffff0000, v187
	v_pk_add_f32 v[98:99], v[98:99], v[102:103]
	v_pk_add_f32 v[96:97], v[96:97], v[100:101]
	v_mul_f32_e32 v101, v99, v99
	v_mul_f32_e32 v100, v97, v97
	v_fmac_f32_e32 v100, v96, v96
	v_fmac_f32_e32 v101, v98, v98
	v_add_f32_e32 v100, v100, v101
	v_add_f32_e32 v100, v104, v100
	ds_swizzle_b32 v101, v100 offset:swizzle(SWAP,16)
	v_cvt_pk_bf16_f32 v96, v96, v97
	v_cvt_pk_bf16_f32 v97, v98, v99
	v_mov_b32_e32 v246, v96
	v_mov_b32_e32 v247, v97
	v_lshl_add_u64 v[250:251], v[114:115], 0, v[248:249]
	s_nop 0
	v_permlane16_swap_b32_e32 v244, v246
	v_permlane16_swap_b32_e32 v245, v247
	global_store_dwordx4 v[250:251], v[244:247], off offset:256
	s_waitcnt lgkmcnt(0)
	v_add_f32_e32 v96, v100, v101
	v_mov_b32_e32 v97, v96
	s_nop 1
	v_permlane32_swap_b32_e32 v96, v97
	s_and_saveexec_b64 s[28:29], s[4:5]
	s_cbranch_execz .LBB0_785
	v_add_f32_e32 v98, v96, v97
	v_lshlrev_b64 v[96:97], 6, v[112:113]
	v_lshl_add_u64 v[96:97], s[2:3], 0, v[96:97]
	v_lshl_add_u64 v[96:97], s[26:27], 2, v[96:97]
	s_lshl_b32 s10, s48, 2
	v_lshl_add_u64 v[96:97], v[96:97], 0, s[10:11]
	global_store_dword v[96:97], v98, off
.LBB0_785:
	s_or_b64 exec, exec, s[28:29]
	v_or_b32_e32 v96, 32, v142
	v_ashrrev_i32_e32 v97, 31, v96
	v_lshlrev_b64 v[98:99], 11, v[96:97]
	v_lshl_add_u64 v[98:99], s[8:9], 0, v[98:99]
	v_lshl_add_u64 v[98:99], v[140:141], 1, v[98:99]
	s_waitcnt vmcnt(15)
	v_permlane16_swap_b32_e32 v188, v190
	v_permlane16_swap_b32_e32 v189, v191
	v_lshlrev_b32_e32 v102, 16, v188
	v_and_b32_e32 v103, 0xffff0000, v188
	v_lshlrev_b32_e32 v100, 16, v189
	v_and_b32_e32 v101, 0xffff0000, v189
	v_pk_add_f32 v[94:95], v[94:95], v[100:101]
	v_pk_add_f32 v[92:93], v[92:93], v[102:103]
	s_nop 0
	v_cvt_pk_bf16_f32 v100, v92, v93
	v_cvt_pk_bf16_f32 v101, v94, v95
	v_mul_f32_e32 v93, v93, v93
	v_mov_b32_e32 v240, v100
	v_mov_b32_e32 v241, v101
	v_mul_f32_e32 v95, v95, v95
	v_fmac_f32_e32 v93, v92, v92
	v_fmac_f32_e32 v95, v94, v94
	v_add_f32_e32 v92, v93, v95
	s_waitcnt vmcnt(15)
	v_lshlrev_b32_e32 v100, 16, v190
	v_and_b32_e32 v101, 0xffff0000, v190
	v_lshlrev_b32_e32 v102, 16, v191
	v_and_b32_e32 v103, 0xffff0000, v191
	v_pk_add_f32 v[90:91], v[90:91], v[102:103]
	v_pk_add_f32 v[88:89], v[88:89], v[100:101]
	s_nop 0
	v_cvt_pk_bf16_f32 v100, v88, v89
	v_cvt_pk_bf16_f32 v101, v90, v91
	v_mul_f32_e32 v89, v89, v89
	v_mov_b32_e32 v242, v100
	v_mov_b32_e32 v243, v101
	v_lshl_add_u64 v[250:251], v[98:99], 0, v[248:249]
	s_nop 0
	v_permlane16_swap_b32_e32 v240, v242
	v_permlane16_swap_b32_e32 v241, v243
	global_store_dwordx4 v[250:251], v[240:243], off
	v_mul_f32_e32 v91, v91, v91
	v_fmac_f32_e32 v89, v88, v88
	v_fmac_f32_e32 v91, v90, v90
	v_add_f32_e32 v88, v89, v91
	v_add_f32_e32 v88, v92, v88
	s_waitcnt vmcnt(15)
	v_permlane16_swap_b32_e32 v192, v194
	v_permlane16_swap_b32_e32 v193, v195
	v_lshlrev_b32_e32 v100, 16, v192
	v_and_b32_e32 v101, 0xffff0000, v192
	v_lshlrev_b32_e32 v102, 16, v193
	v_and_b32_e32 v103, 0xffff0000, v193
	v_pk_add_f32 v[86:87], v[86:87], v[102:103]
	v_pk_add_f32 v[84:85], v[84:85], v[100:101]
	s_nop 0
	v_cvt_pk_bf16_f32 v100, v84, v85
	v_cvt_pk_bf16_f32 v101, v86, v87
	v_mul_f32_e32 v85, v85, v85
	v_mul_f32_e32 v87, v87, v87
	v_fmac_f32_e32 v85, v84, v84
	v_fmac_f32_e32 v87, v86, v86
	v_add_f32_e32 v84, v85, v87
	v_add_f32_e32 v88, v88, v84
	v_mov_b32_e32 v244, v100
	v_mov_b32_e32 v245, v101
	s_waitcnt vmcnt(15)
	v_lshlrev_b32_e32 v84, 16, v194
	v_and_b32_e32 v85, 0xffff0000, v194
	v_lshlrev_b32_e32 v86, 16, v195
	v_and_b32_e32 v87, 0xffff0000, v195
	v_pk_add_f32 v[82:83], v[82:83], v[86:87]
	v_pk_add_f32 v[80:81], v[80:81], v[84:85]
	v_mul_f32_e32 v85, v83, v83
	v_mul_f32_e32 v84, v81, v81
	v_fmac_f32_e32 v84, v80, v80
	v_fmac_f32_e32 v85, v82, v82
	v_add_f32_e32 v84, v84, v85
	v_add_f32_e32 v84, v88, v84
	ds_swizzle_b32 v85, v84 offset:swizzle(SWAP,16)
	v_cvt_pk_bf16_f32 v80, v80, v81
	v_cvt_pk_bf16_f32 v81, v82, v83
	v_mov_b32_e32 v246, v80
	v_mov_b32_e32 v247, v81
	v_lshl_add_u64 v[250:251], v[98:99], 0, v[248:249]
	s_nop 0
	v_permlane16_swap_b32_e32 v244, v246
	v_permlane16_swap_b32_e32 v245, v247
	global_store_dwordx4 v[250:251], v[244:247], off offset:256
	s_waitcnt lgkmcnt(0)
	v_add_f32_e32 v80, v84, v85
	v_mov_b32_e32 v81, v80
	s_nop 1
	v_permlane32_swap_b32_e32 v80, v81
	s_and_saveexec_b64 s[28:29], s[4:5]
	s_cbranch_execz .LBB0_787
	v_add_f32_e32 v82, v80, v81
	v_lshlrev_b64 v[80:81], 6, v[96:97]
	v_lshl_add_u64 v[80:81], s[2:3], 0, v[80:81]
	v_lshl_add_u64 v[80:81], s[26:27], 2, v[80:81]
	s_lshl_b32 s10, s48, 2
	v_lshl_add_u64 v[80:81], v[80:81], 0, s[10:11]
	global_store_dword v[80:81], v82, off
.LBB0_787:
	s_or_b64 exec, exec, s[28:29]
	v_or_b32_e32 v80, 48, v142
	v_ashrrev_i32_e32 v81, 31, v80
	v_lshlrev_b64 v[82:83], 11, v[80:81]
	v_lshl_add_u64 v[82:83], s[8:9], 0, v[82:83]
	v_lshl_add_u64 v[82:83], v[140:141], 1, v[82:83]
	s_waitcnt vmcnt(15)
	v_permlane16_swap_b32_e32 v196, v198
	v_permlane16_swap_b32_e32 v197, v199
	v_lshlrev_b32_e32 v86, 16, v196
	v_and_b32_e32 v87, 0xffff0000, v196
	v_lshlrev_b32_e32 v84, 16, v197
	v_and_b32_e32 v85, 0xffff0000, v197
	v_pk_add_f32 v[78:79], v[78:79], v[84:85]
	v_pk_add_f32 v[76:77], v[76:77], v[86:87]
	s_nop 0
	v_cvt_pk_bf16_f32 v84, v76, v77
	v_cvt_pk_bf16_f32 v85, v78, v79
	v_mul_f32_e32 v77, v77, v77
	v_mov_b32_e32 v240, v84
	v_mov_b32_e32 v241, v85
	v_mul_f32_e32 v79, v79, v79
	v_fmac_f32_e32 v77, v76, v76
	v_fmac_f32_e32 v79, v78, v78
	v_add_f32_e32 v76, v77, v79
	s_waitcnt vmcnt(15)
	v_lshlrev_b32_e32 v84, 16, v198
	v_and_b32_e32 v85, 0xffff0000, v198
	v_lshlrev_b32_e32 v86, 16, v199
	v_and_b32_e32 v87, 0xffff0000, v199
	v_pk_add_f32 v[74:75], v[74:75], v[86:87]
	v_pk_add_f32 v[72:73], v[72:73], v[84:85]
	s_nop 0
	v_cvt_pk_bf16_f32 v84, v72, v73
	v_cvt_pk_bf16_f32 v85, v74, v75
	v_mul_f32_e32 v73, v73, v73
	v_mov_b32_e32 v242, v84
	v_mov_b32_e32 v243, v85
	v_lshl_add_u64 v[250:251], v[82:83], 0, v[248:249]
	s_nop 0
	v_permlane16_swap_b32_e32 v240, v242
	v_permlane16_swap_b32_e32 v241, v243
	global_store_dwordx4 v[250:251], v[240:243], off
	v_mul_f32_e32 v75, v75, v75
	v_fmac_f32_e32 v73, v72, v72
	v_fmac_f32_e32 v75, v74, v74
	v_add_f32_e32 v72, v73, v75
	v_add_f32_e32 v72, v76, v72
	s_waitcnt vmcnt(15)
	v_permlane16_swap_b32_e32 v200, v202
	v_permlane16_swap_b32_e32 v201, v203
	v_lshlrev_b32_e32 v84, 16, v200
	v_and_b32_e32 v85, 0xffff0000, v200
	v_lshlrev_b32_e32 v86, 16, v201
	v_and_b32_e32 v87, 0xffff0000, v201
	v_pk_add_f32 v[70:71], v[70:71], v[86:87]
	v_pk_add_f32 v[68:69], v[68:69], v[84:85]
	s_nop 0
	v_cvt_pk_bf16_f32 v84, v68, v69
	v_cvt_pk_bf16_f32 v85, v70, v71
	v_mul_f32_e32 v69, v69, v69
	v_mul_f32_e32 v71, v71, v71
	v_fmac_f32_e32 v69, v68, v68
	v_fmac_f32_e32 v71, v70, v70
	v_add_f32_e32 v68, v69, v71
	v_add_f32_e32 v72, v72, v68
	v_mov_b32_e32 v244, v84
	v_mov_b32_e32 v245, v85
	s_waitcnt vmcnt(15)
	v_lshlrev_b32_e32 v68, 16, v202
	v_and_b32_e32 v69, 0xffff0000, v202
	v_lshlrev_b32_e32 v70, 16, v203
	v_and_b32_e32 v71, 0xffff0000, v203
	v_pk_add_f32 v[66:67], v[66:67], v[70:71]
	v_pk_add_f32 v[64:65], v[64:65], v[68:69]
	v_mul_f32_e32 v69, v67, v67
	v_mul_f32_e32 v68, v65, v65
	v_fmac_f32_e32 v68, v64, v64
	v_fmac_f32_e32 v69, v66, v66
	v_add_f32_e32 v68, v68, v69
	v_add_f32_e32 v68, v72, v68
	ds_swizzle_b32 v69, v68 offset:swizzle(SWAP,16)
	v_cvt_pk_bf16_f32 v64, v64, v65
	v_cvt_pk_bf16_f32 v65, v66, v67
	v_mov_b32_e32 v246, v64
	v_mov_b32_e32 v247, v65
	v_lshl_add_u64 v[250:251], v[82:83], 0, v[248:249]
	s_nop 0
	v_permlane16_swap_b32_e32 v244, v246
	v_permlane16_swap_b32_e32 v245, v247
	global_store_dwordx4 v[250:251], v[244:247], off offset:256
	s_waitcnt lgkmcnt(0)
	v_add_f32_e32 v64, v68, v69
	v_mov_b32_e32 v65, v64
	s_nop 1
	v_permlane32_swap_b32_e32 v64, v65
	s_and_saveexec_b64 s[28:29], s[4:5]
	s_cbranch_execz .LBB0_789
	v_add_f32_e32 v66, v64, v65
	v_lshlrev_b64 v[64:65], 6, v[80:81]
	v_lshl_add_u64 v[64:65], s[2:3], 0, v[64:65]
	v_lshl_add_u64 v[64:65], s[26:27], 2, v[64:65]
	s_lshl_b32 s10, s48, 2
	v_lshl_add_u64 v[64:65], v[64:65], 0, s[10:11]
	global_store_dword v[64:65], v66, off
.LBB0_789:
	s_or_b64 exec, exec, s[28:29]
	v_add_u32_e32 v64, 0x80, v142
	v_ashrrev_i32_e32 v65, 31, v64
	v_lshlrev_b64 v[66:67], 11, v[64:65]
	v_lshl_add_u64 v[66:67], s[8:9], 0, v[66:67]
	v_lshl_add_u64 v[66:67], v[140:141], 1, v[66:67]
	s_waitcnt vmcnt(15)
	v_permlane16_swap_b32_e32 v208, v210
	v_permlane16_swap_b32_e32 v209, v211
	v_lshlrev_b32_e32 v70, 16, v208
	v_and_b32_e32 v71, 0xffff0000, v208
	v_lshlrev_b32_e32 v68, 16, v209
	v_and_b32_e32 v69, 0xffff0000, v209
	v_pk_add_f32 v[62:63], v[62:63], v[68:69]
	v_pk_add_f32 v[60:61], v[60:61], v[70:71]
	s_nop 0
	v_cvt_pk_bf16_f32 v68, v60, v61
	v_cvt_pk_bf16_f32 v69, v62, v63
	v_mul_f32_e32 v61, v61, v61
	v_mov_b32_e32 v240, v68
	v_mov_b32_e32 v241, v69
	v_mul_f32_e32 v63, v63, v63
	v_fmac_f32_e32 v61, v60, v60
	v_fmac_f32_e32 v63, v62, v62
	v_add_f32_e32 v60, v61, v63
	s_waitcnt vmcnt(15)
	v_lshlrev_b32_e32 v68, 16, v210
	v_and_b32_e32 v69, 0xffff0000, v210
	v_lshlrev_b32_e32 v70, 16, v211
	v_and_b32_e32 v71, 0xffff0000, v211
	v_pk_add_f32 v[58:59], v[58:59], v[70:71]
	v_pk_add_f32 v[56:57], v[56:57], v[68:69]
	s_nop 0
	v_cvt_pk_bf16_f32 v68, v56, v57
	v_cvt_pk_bf16_f32 v69, v58, v59
	v_mul_f32_e32 v57, v57, v57
	v_mov_b32_e32 v242, v68
	v_mov_b32_e32 v243, v69
	v_lshl_add_u64 v[250:251], v[66:67], 0, v[248:249]
	s_nop 0
	v_permlane16_swap_b32_e32 v240, v242
	v_permlane16_swap_b32_e32 v241, v243
	global_store_dwordx4 v[250:251], v[240:243], off
	v_mul_f32_e32 v59, v59, v59
	v_fmac_f32_e32 v57, v56, v56
	v_fmac_f32_e32 v59, v58, v58
	v_add_f32_e32 v56, v57, v59
	v_add_f32_e32 v56, v60, v56
	s_waitcnt vmcnt(15)
	v_permlane16_swap_b32_e32 v212, v214
	v_permlane16_swap_b32_e32 v213, v215
	v_lshlrev_b32_e32 v68, 16, v212
	v_and_b32_e32 v69, 0xffff0000, v212
	v_lshlrev_b32_e32 v70, 16, v213
	v_and_b32_e32 v71, 0xffff0000, v213
	v_pk_add_f32 v[54:55], v[54:55], v[70:71]
	v_pk_add_f32 v[52:53], v[52:53], v[68:69]
	s_nop 0
	v_cvt_pk_bf16_f32 v68, v52, v53
	v_cvt_pk_bf16_f32 v69, v54, v55
	v_mul_f32_e32 v53, v53, v53
	v_mul_f32_e32 v55, v55, v55
	v_fmac_f32_e32 v53, v52, v52
	v_fmac_f32_e32 v55, v54, v54
	v_add_f32_e32 v52, v53, v55
	v_add_f32_e32 v56, v56, v52
	v_mov_b32_e32 v244, v68
	v_mov_b32_e32 v245, v69
	s_waitcnt vmcnt(15)
	v_lshlrev_b32_e32 v52, 16, v214
	v_and_b32_e32 v53, 0xffff0000, v214
	v_lshlrev_b32_e32 v54, 16, v215
	v_and_b32_e32 v55, 0xffff0000, v215
	v_pk_add_f32 v[50:51], v[50:51], v[54:55]
	v_pk_add_f32 v[48:49], v[48:49], v[52:53]
	v_mul_f32_e32 v53, v51, v51
	v_mul_f32_e32 v52, v49, v49
	v_fmac_f32_e32 v52, v48, v48
	v_fmac_f32_e32 v53, v50, v50
	v_add_f32_e32 v52, v52, v53
	v_add_f32_e32 v52, v56, v52
	ds_swizzle_b32 v53, v52 offset:swizzle(SWAP,16)
	v_cvt_pk_bf16_f32 v48, v48, v49
	v_cvt_pk_bf16_f32 v49, v50, v51
	v_mov_b32_e32 v246, v48
	v_mov_b32_e32 v247, v49
	v_lshl_add_u64 v[250:251], v[66:67], 0, v[248:249]
	s_nop 0
	v_permlane16_swap_b32_e32 v244, v246
	v_permlane16_swap_b32_e32 v245, v247
	global_store_dwordx4 v[250:251], v[244:247], off offset:256
	s_waitcnt lgkmcnt(0)
	v_add_f32_e32 v48, v52, v53
	v_mov_b32_e32 v49, v48
	s_nop 1
	v_permlane32_swap_b32_e32 v48, v49
	s_and_saveexec_b64 s[28:29], s[4:5]
	s_cbranch_execz .LBB0_791
	v_add_f32_e32 v50, v48, v49
	v_lshlrev_b64 v[48:49], 6, v[64:65]
	v_lshl_add_u64 v[48:49], s[2:3], 0, v[48:49]
	v_lshl_add_u64 v[48:49], s[26:27], 2, v[48:49]
	s_lshl_b32 s10, s48, 2
	v_lshl_add_u64 v[48:49], v[48:49], 0, s[10:11]
	global_store_dword v[48:49], v50, off
.LBB0_791:
	s_or_b64 exec, exec, s[28:29]
	v_add_u32_e32 v48, 0x90, v142
	v_ashrrev_i32_e32 v49, 31, v48
	v_lshlrev_b64 v[50:51], 11, v[48:49]
	v_lshl_add_u64 v[50:51], s[8:9], 0, v[50:51]
	v_lshl_add_u64 v[50:51], v[140:141], 1, v[50:51]
	s_waitcnt vmcnt(15)
	v_permlane16_swap_b32_e32 v216, v218
	v_permlane16_swap_b32_e32 v217, v219
	v_lshlrev_b32_e32 v54, 16, v216
	v_and_b32_e32 v55, 0xffff0000, v216
	v_lshlrev_b32_e32 v52, 16, v217
	v_and_b32_e32 v53, 0xffff0000, v217
	v_pk_add_f32 v[46:47], v[46:47], v[52:53]
	v_pk_add_f32 v[44:45], v[44:45], v[54:55]
	s_nop 0
	v_cvt_pk_bf16_f32 v52, v44, v45
	v_cvt_pk_bf16_f32 v53, v46, v47
	v_mul_f32_e32 v45, v45, v45
	v_mov_b32_e32 v240, v52
	v_mov_b32_e32 v241, v53
	v_mul_f32_e32 v47, v47, v47
	v_fmac_f32_e32 v45, v44, v44
	v_fmac_f32_e32 v47, v46, v46
	v_add_f32_e32 v44, v45, v47
	s_waitcnt vmcnt(15)
	v_lshlrev_b32_e32 v52, 16, v218
	v_and_b32_e32 v53, 0xffff0000, v218
	v_lshlrev_b32_e32 v54, 16, v219
	v_and_b32_e32 v55, 0xffff0000, v219
	v_pk_add_f32 v[42:43], v[42:43], v[54:55]
	v_pk_add_f32 v[40:41], v[40:41], v[52:53]
	s_nop 0
	v_cvt_pk_bf16_f32 v52, v40, v41
	v_cvt_pk_bf16_f32 v53, v42, v43
	v_mul_f32_e32 v41, v41, v41
	v_mov_b32_e32 v242, v52
	v_mov_b32_e32 v243, v53
	v_lshl_add_u64 v[250:251], v[50:51], 0, v[248:249]
	s_nop 0
	v_permlane16_swap_b32_e32 v240, v242
	v_permlane16_swap_b32_e32 v241, v243
	global_store_dwordx4 v[250:251], v[240:243], off
	v_mul_f32_e32 v43, v43, v43
	v_fmac_f32_e32 v41, v40, v40
	v_fmac_f32_e32 v43, v42, v42
	v_add_f32_e32 v40, v41, v43
	v_add_f32_e32 v40, v44, v40
	s_waitcnt vmcnt(15)
	v_permlane16_swap_b32_e32 v220, v222
	v_permlane16_swap_b32_e32 v221, v223
	v_lshlrev_b32_e32 v52, 16, v220
	v_and_b32_e32 v53, 0xffff0000, v220
	v_lshlrev_b32_e32 v54, 16, v221
	v_and_b32_e32 v55, 0xffff0000, v221
	v_pk_add_f32 v[38:39], v[38:39], v[54:55]
	v_pk_add_f32 v[36:37], v[36:37], v[52:53]
	s_nop 0
	v_cvt_pk_bf16_f32 v52, v36, v37
	v_cvt_pk_bf16_f32 v53, v38, v39
	v_mul_f32_e32 v37, v37, v37
	v_mul_f32_e32 v39, v39, v39
	v_fmac_f32_e32 v37, v36, v36
	v_fmac_f32_e32 v39, v38, v38
	v_add_f32_e32 v36, v37, v39
	v_add_f32_e32 v40, v40, v36
	v_mov_b32_e32 v244, v52
	v_mov_b32_e32 v245, v53
	s_waitcnt vmcnt(15)
	v_lshlrev_b32_e32 v36, 16, v222
	v_and_b32_e32 v37, 0xffff0000, v222
	v_lshlrev_b32_e32 v38, 16, v223
	v_and_b32_e32 v39, 0xffff0000, v223
	v_pk_add_f32 v[34:35], v[34:35], v[38:39]
	v_pk_add_f32 v[32:33], v[32:33], v[36:37]
	v_mul_f32_e32 v37, v35, v35
	v_mul_f32_e32 v36, v33, v33
	v_fmac_f32_e32 v36, v32, v32
	v_fmac_f32_e32 v37, v34, v34
	v_add_f32_e32 v36, v36, v37
	v_add_f32_e32 v36, v40, v36
	ds_swizzle_b32 v37, v36 offset:swizzle(SWAP,16)
	v_cvt_pk_bf16_f32 v32, v32, v33
	v_cvt_pk_bf16_f32 v33, v34, v35
	v_mov_b32_e32 v246, v32
	v_mov_b32_e32 v247, v33
	v_lshl_add_u64 v[250:251], v[50:51], 0, v[248:249]
	s_nop 0
	v_permlane16_swap_b32_e32 v244, v246
	v_permlane16_swap_b32_e32 v245, v247
	global_store_dwordx4 v[250:251], v[244:247], off offset:256
	s_waitcnt lgkmcnt(0)
	v_add_f32_e32 v32, v36, v37
	v_mov_b32_e32 v33, v32
	s_nop 1
	v_permlane32_swap_b32_e32 v32, v33
	s_and_saveexec_b64 s[28:29], s[4:5]
	s_cbranch_execz .LBB0_793
	v_add_f32_e32 v34, v32, v33
	v_lshlrev_b64 v[32:33], 6, v[48:49]
	v_lshl_add_u64 v[32:33], s[2:3], 0, v[32:33]
	v_lshl_add_u64 v[32:33], s[26:27], 2, v[32:33]
	s_lshl_b32 s10, s48, 2
	v_lshl_add_u64 v[32:33], v[32:33], 0, s[10:11]
	global_store_dword v[32:33], v34, off
.LBB0_793:
	s_or_b64 exec, exec, s[28:29]
	v_add_u32_e32 v32, 0xa0, v142
	v_ashrrev_i32_e32 v33, 31, v32
	v_lshlrev_b64 v[34:35], 11, v[32:33]
	v_lshl_add_u64 v[34:35], s[8:9], 0, v[34:35]
	v_lshl_add_u64 v[34:35], v[140:141], 1, v[34:35]
	s_waitcnt vmcnt(15)
	v_permlane16_swap_b32_e32 v224, v226
	v_permlane16_swap_b32_e32 v225, v227
	v_lshlrev_b32_e32 v38, 16, v224
	v_and_b32_e32 v39, 0xffff0000, v224
	v_lshlrev_b32_e32 v36, 16, v225
	v_and_b32_e32 v37, 0xffff0000, v225
	v_pk_add_f32 v[30:31], v[30:31], v[36:37]
	v_pk_add_f32 v[28:29], v[28:29], v[38:39]
	s_nop 0
	v_cvt_pk_bf16_f32 v36, v28, v29
	v_cvt_pk_bf16_f32 v37, v30, v31
	v_mul_f32_e32 v29, v29, v29
	v_mov_b32_e32 v240, v36
	v_mov_b32_e32 v241, v37
	v_mul_f32_e32 v31, v31, v31
	v_fmac_f32_e32 v29, v28, v28
	v_fmac_f32_e32 v31, v30, v30
	v_add_f32_e32 v28, v29, v31
	s_waitcnt vmcnt(15)
	v_lshlrev_b32_e32 v36, 16, v226
	v_and_b32_e32 v37, 0xffff0000, v226
	v_lshlrev_b32_e32 v38, 16, v227
	v_and_b32_e32 v39, 0xffff0000, v227
	v_pk_add_f32 v[26:27], v[26:27], v[38:39]
	v_pk_add_f32 v[24:25], v[24:25], v[36:37]
	s_nop 0
	v_cvt_pk_bf16_f32 v36, v24, v25
	v_cvt_pk_bf16_f32 v37, v26, v27
	v_mul_f32_e32 v25, v25, v25
	v_mov_b32_e32 v242, v36
	v_mov_b32_e32 v243, v37
	v_lshl_add_u64 v[250:251], v[34:35], 0, v[248:249]
	s_nop 0
	v_permlane16_swap_b32_e32 v240, v242
	v_permlane16_swap_b32_e32 v241, v243
	global_store_dwordx4 v[250:251], v[240:243], off
	v_mul_f32_e32 v27, v27, v27
	v_fmac_f32_e32 v25, v24, v24
	v_fmac_f32_e32 v27, v26, v26
	v_add_f32_e32 v24, v25, v27
	v_add_f32_e32 v24, v28, v24
	s_waitcnt vmcnt(15)
	v_permlane16_swap_b32_e32 v228, v230
	v_permlane16_swap_b32_e32 v229, v231
	v_lshlrev_b32_e32 v36, 16, v228
	v_and_b32_e32 v37, 0xffff0000, v228
	v_lshlrev_b32_e32 v38, 16, v229
	v_and_b32_e32 v39, 0xffff0000, v229
	v_pk_add_f32 v[22:23], v[22:23], v[38:39]
	v_pk_add_f32 v[20:21], v[20:21], v[36:37]
	s_nop 0
	v_cvt_pk_bf16_f32 v36, v20, v21
	v_cvt_pk_bf16_f32 v37, v22, v23
	v_mul_f32_e32 v21, v21, v21
	v_mul_f32_e32 v23, v23, v23
	v_fmac_f32_e32 v21, v20, v20
	v_fmac_f32_e32 v23, v22, v22
	v_add_f32_e32 v20, v21, v23
	v_add_f32_e32 v24, v24, v20
	v_mov_b32_e32 v244, v36
	v_mov_b32_e32 v245, v37
	s_waitcnt vmcnt(15)
	v_lshlrev_b32_e32 v20, 16, v230
	v_and_b32_e32 v21, 0xffff0000, v230
	v_lshlrev_b32_e32 v22, 16, v231
	v_and_b32_e32 v23, 0xffff0000, v231
	v_pk_add_f32 v[18:19], v[18:19], v[22:23]
	v_pk_add_f32 v[16:17], v[16:17], v[20:21]
	v_mul_f32_e32 v21, v19, v19
	v_mul_f32_e32 v20, v17, v17
	v_fmac_f32_e32 v20, v16, v16
	v_fmac_f32_e32 v21, v18, v18
	v_add_f32_e32 v20, v20, v21
	v_add_f32_e32 v20, v24, v20
	ds_swizzle_b32 v21, v20 offset:swizzle(SWAP,16)
	v_cvt_pk_bf16_f32 v16, v16, v17
	v_cvt_pk_bf16_f32 v17, v18, v19
	v_mov_b32_e32 v246, v16
	v_mov_b32_e32 v247, v17
	v_lshl_add_u64 v[250:251], v[34:35], 0, v[248:249]
	s_nop 0
	v_permlane16_swap_b32_e32 v244, v246
	v_permlane16_swap_b32_e32 v245, v247
	global_store_dwordx4 v[250:251], v[244:247], off offset:256
	s_waitcnt lgkmcnt(0)
	v_add_f32_e32 v16, v20, v21
	v_mov_b32_e32 v17, v16
	s_nop 1
	v_permlane32_swap_b32_e32 v16, v17
	s_and_saveexec_b64 s[28:29], s[4:5]
	s_cbranch_execz .LBB0_795
	v_add_f32_e32 v18, v16, v17
	v_lshlrev_b64 v[16:17], 6, v[32:33]
	v_lshl_add_u64 v[16:17], s[2:3], 0, v[16:17]
	v_lshl_add_u64 v[16:17], s[26:27], 2, v[16:17]
	s_lshl_b32 s10, s48, 2
	v_lshl_add_u64 v[16:17], v[16:17], 0, s[10:11]
	global_store_dword v[16:17], v18, off
.LBB0_795:
	s_or_b64 exec, exec, s[28:29]
	v_add_u32_e32 v16, 0xb0, v142
	v_ashrrev_i32_e32 v17, 31, v16
	v_lshlrev_b64 v[18:19], 11, v[16:17]
	v_lshl_add_u64 v[18:19], s[8:9], 0, v[18:19]
	v_lshl_add_u64 v[18:19], v[140:141], 1, v[18:19]
	s_waitcnt vmcnt(15)
	v_permlane16_swap_b32_e32 v232, v234
	v_permlane16_swap_b32_e32 v233, v235
	v_lshlrev_b32_e32 v22, 16, v232
	v_and_b32_e32 v23, 0xffff0000, v232
	v_lshlrev_b32_e32 v20, 16, v233
	v_and_b32_e32 v21, 0xffff0000, v233
	v_pk_add_f32 v[14:15], v[14:15], v[20:21]
	v_pk_add_f32 v[12:13], v[12:13], v[22:23]
	s_nop 0
	v_cvt_pk_bf16_f32 v20, v12, v13
	v_cvt_pk_bf16_f32 v21, v14, v15
	v_mul_f32_e32 v13, v13, v13
	v_mov_b32_e32 v240, v20
	v_mov_b32_e32 v241, v21
	v_mul_f32_e32 v15, v15, v15
	v_fmac_f32_e32 v13, v12, v12
	v_fmac_f32_e32 v15, v14, v14
	v_add_f32_e32 v12, v13, v15
	s_waitcnt vmcnt(15)
	v_lshlrev_b32_e32 v20, 16, v234
	v_and_b32_e32 v21, 0xffff0000, v234
	v_lshlrev_b32_e32 v22, 16, v235
	v_and_b32_e32 v23, 0xffff0000, v235
	v_pk_add_f32 v[10:11], v[10:11], v[22:23]
	v_pk_add_f32 v[8:9], v[8:9], v[20:21]
	s_nop 0
	v_cvt_pk_bf16_f32 v20, v8, v9
	v_cvt_pk_bf16_f32 v21, v10, v11
	v_mul_f32_e32 v9, v9, v9
	v_mov_b32_e32 v242, v20
	v_mov_b32_e32 v243, v21
	v_lshl_add_u64 v[250:251], v[18:19], 0, v[248:249]
	s_nop 0
	v_permlane16_swap_b32_e32 v240, v242
	v_permlane16_swap_b32_e32 v241, v243
	global_store_dwordx4 v[250:251], v[240:243], off
	v_mul_f32_e32 v11, v11, v11
	v_fmac_f32_e32 v9, v8, v8
	v_fmac_f32_e32 v11, v10, v10
	v_add_f32_e32 v8, v9, v11
	v_add_f32_e32 v8, v12, v8
	s_waitcnt vmcnt(15)
	v_permlane16_swap_b32_e32 v236, v238
	v_permlane16_swap_b32_e32 v237, v239
	v_lshlrev_b32_e32 v20, 16, v236
	v_and_b32_e32 v21, 0xffff0000, v236
	v_lshlrev_b32_e32 v22, 16, v237
	v_and_b32_e32 v23, 0xffff0000, v237
	v_pk_add_f32 v[6:7], v[6:7], v[22:23]
	v_pk_add_f32 v[4:5], v[4:5], v[20:21]
	s_nop 0
	v_cvt_pk_bf16_f32 v20, v4, v5
	v_cvt_pk_bf16_f32 v21, v6, v7
	v_mul_f32_e32 v5, v5, v5
	v_mul_f32_e32 v7, v7, v7
	v_fmac_f32_e32 v5, v4, v4
	v_fmac_f32_e32 v7, v6, v6
	v_add_f32_e32 v4, v5, v7
	v_add_f32_e32 v8, v8, v4
	v_mov_b32_e32 v244, v20
	v_mov_b32_e32 v245, v21
	s_waitcnt vmcnt(15)
	v_lshlrev_b32_e32 v4, 16, v238
	v_and_b32_e32 v5, 0xffff0000, v238
	v_lshlrev_b32_e32 v6, 16, v239
	v_and_b32_e32 v7, 0xffff0000, v239
	v_pk_add_f32 v[2:3], v[2:3], v[6:7]
	v_pk_add_f32 v[0:1], v[0:1], v[4:5]
	v_mul_f32_e32 v5, v3, v3
	v_mul_f32_e32 v4, v1, v1
	v_fmac_f32_e32 v4, v0, v0
	v_fmac_f32_e32 v5, v2, v2
	v_add_f32_e32 v4, v4, v5
	v_add_f32_e32 v4, v8, v4
	ds_swizzle_b32 v5, v4 offset:swizzle(SWAP,16)
	v_cvt_pk_bf16_f32 v0, v0, v1
	v_cvt_pk_bf16_f32 v1, v2, v3
	v_mov_b32_e32 v246, v0
	v_mov_b32_e32 v247, v1
	v_lshl_add_u64 v[250:251], v[18:19], 0, v[248:249]
	s_nop 0
	v_permlane16_swap_b32_e32 v244, v246
	v_permlane16_swap_b32_e32 v245, v247
	global_store_dwordx4 v[250:251], v[244:247], off offset:256
	s_waitcnt lgkmcnt(0)
	v_add_f32_e32 v0, v4, v5
	v_mov_b32_e32 v1, v0
	s_nop 1
	v_permlane32_swap_b32_e32 v0, v1
	s_and_saveexec_b64 s[28:29], s[4:5]
	s_cbranch_execz .LBB0_797
	v_add_f32_e32 v2, v0, v1
	v_lshlrev_b64 v[0:1], 6, v[16:17]
	v_lshl_add_u64 v[0:1], s[2:3], 0, v[0:1]
	v_lshl_add_u64 v[0:1], s[26:27], 2, v[0:1]
	s_lshl_b32 s10, s48, 2
	v_lshl_add_u64 v[0:1], v[0:1], 0, s[10:11]
	global_store_dword v[0:1], v2, off

.LBB0_1275:
	v_lshl_add_u32 v142, s26, 8, v144
	v_ashrrev_i32_e32 v143, 31, v142
	v_lshl_or_b32 v140, s2, 8, v146
	v_lshlrev_b64 v[150:151], 11, v[142:143]
	v_ashrrev_i32_e32 v141, 31, v140
	v_lshl_add_u64 v[150:151], s[8:9], 0, v[150:151]
	v_lshl_add_u64 v[150:151], v[140:141], 1, v[150:151]
	s_mov_b64 s[98:99], 0x8000
	s_mov_b64 s[100:101], 0x28000
	v_bfe_u32 v248, v206, 4, 1
	v_mul_u32_u24_e32 v248, 24, v248
	v_mov_b32_e32 v249, 0
	v_lshl_add_u64 v[250:251], v[150:151], 0, v[248:249]
	global_load_dwordx4 v[156:159], v[250:251], off
	global_load_dwordx4 v[160:163], v[250:251], off offset:256
	v_lshl_add_u64 v[250:251], v[250:251], 0, s[98:99]
	global_load_dwordx4 v[164:167], v[250:251], off
	global_load_dwordx4 v[184:187], v[250:251], off offset:256
	v_lshl_add_u64 v[250:251], v[250:251], 0, s[98:99]
	global_load_dwordx4 v[188:191], v[250:251], off
	global_load_dwordx4 v[192:195], v[250:251], off offset:256
	v_lshl_add_u64 v[250:251], v[250:251], 0, s[98:99]
	global_load_dwordx4 v[196:199], v[250:251], off
	global_load_dwordx4 v[200:203], v[250:251], off offset:256
	v_lshl_add_u64 v[250:251], v[250:251], 0, s[100:101]
	global_load_dwordx4 v[208:211], v[250:251], off
	global_load_dwordx4 v[212:215], v[250:251], off offset:256
	v_lshl_add_u64 v[250:251], v[250:251], 0, s[98:99]
	global_load_dwordx4 v[216:219], v[250:251], off
	global_load_dwordx4 v[220:223], v[250:251], off offset:256
	v_lshl_add_u64 v[250:251], v[250:251], 0, s[98:99]
	global_load_dwordx4 v[224:227], v[250:251], off
	global_load_dwordx4 v[228:231], v[250:251], off offset:256
	v_lshl_add_u64 v[250:251], v[250:251], 0, s[98:99]
	global_load_dwordx4 v[232:235], v[250:251], off
	global_load_dwordx4 v[236:239], v[250:251], off offset:256
	s_lshl_b32 s26, s2, 2
	s_ashr_i32 s27, s26, 31
	s_waitcnt vmcnt(15)
	v_permlane16_swap_b32_e32 v156, v158
	v_permlane16_swap_b32_e32 v157, v159
	v_lshlrev_b32_e32 v154, 16, v156
	v_and_b32_e32 v155, 0xffff0000, v156
	v_lshlrev_b32_e32 v152, 16, v157
	v_and_b32_e32 v153, 0xffff0000, v157
	v_pk_add_f32 v[126:127], v[126:127], v[152:153]
	v_pk_add_f32 v[124:125], v[124:125], v[154:155]
	s_nop 0
	v_cvt_pk_bf16_f32 v152, v124, v125
	v_cvt_pk_bf16_f32 v153, v126, v127
	v_mul_f32_e32 v125, v125, v125
	v_mov_b32_e32 v240, v152
	v_mov_b32_e32 v241, v153
	v_mul_f32_e32 v127, v127, v127
	v_fmac_f32_e32 v125, v124, v124
	v_fmac_f32_e32 v127, v126, v126
	v_add_f32_e32 v124, v125, v127
	s_waitcnt vmcnt(15)
	v_lshlrev_b32_e32 v152, 16, v158
	v_and_b32_e32 v153, 0xffff0000, v158
	v_lshlrev_b32_e32 v154, 16, v159
	v_and_b32_e32 v155, 0xffff0000, v159
	v_pk_add_f32 v[122:123], v[122:123], v[154:155]
	v_pk_add_f32 v[120:121], v[120:121], v[152:153]
	s_nop 0
	v_cvt_pk_bf16_f32 v152, v120, v121
	v_cvt_pk_bf16_f32 v153, v122, v123
	v_mul_f32_e32 v121, v121, v121
	v_mov_b32_e32 v242, v152
	v_mov_b32_e32 v243, v153
	v_lshl_add_u64 v[250:251], v[150:151], 0, v[248:249]
	s_nop 0
	v_permlane16_swap_b32_e32 v240, v242
	v_permlane16_swap_b32_e32 v241, v243
	global_store_dwordx4 v[250:251], v[240:243], off
	v_mul_f32_e32 v123, v123, v123
	v_fmac_f32_e32 v121, v120, v120
	v_fmac_f32_e32 v123, v122, v122
	v_add_f32_e32 v120, v121, v123
	v_add_f32_e32 v120, v124, v120
	s_waitcnt vmcnt(15)
	v_permlane16_swap_b32_e32 v160, v162
	v_permlane16_swap_b32_e32 v161, v163
	v_lshlrev_b32_e32 v152, 16, v160
	v_and_b32_e32 v153, 0xffff0000, v160
	v_lshlrev_b32_e32 v154, 16, v161
	v_and_b32_e32 v155, 0xffff0000, v161
	v_pk_add_f32 v[118:119], v[118:119], v[154:155]
	v_pk_add_f32 v[116:117], v[116:117], v[152:153]
	s_nop 0
	v_cvt_pk_bf16_f32 v152, v116, v117
	v_cvt_pk_bf16_f32 v153, v118, v119
	v_mul_f32_e32 v117, v117, v117
	v_mul_f32_e32 v119, v119, v119
	v_fmac_f32_e32 v117, v116, v116
	v_fmac_f32_e32 v119, v118, v118
	v_add_f32_e32 v116, v117, v119
	v_add_f32_e32 v120, v120, v116
	v_mov_b32_e32 v244, v152
	v_mov_b32_e32 v245, v153
	s_waitcnt vmcnt(15)
	v_lshlrev_b32_e32 v116, 16, v162
	v_and_b32_e32 v117, 0xffff0000, v162
	v_lshlrev_b32_e32 v118, 16, v163
	v_and_b32_e32 v119, 0xffff0000, v163
	v_pk_add_f32 v[114:115], v[114:115], v[118:119]
	v_pk_add_f32 v[112:113], v[112:113], v[116:117]
	v_mul_f32_e32 v117, v115, v115
	v_mul_f32_e32 v116, v113, v113
	v_fmac_f32_e32 v116, v112, v112
	v_fmac_f32_e32 v117, v114, v114
	v_add_f32_e32 v116, v116, v117
	v_add_f32_e32 v116, v120, v116
	ds_swizzle_b32 v117, v116 offset:swizzle(SWAP,16)
	v_cvt_pk_bf16_f32 v112, v112, v113
	v_cvt_pk_bf16_f32 v113, v114, v115
	v_mov_b32_e32 v246, v112
	v_mov_b32_e32 v247, v113
	v_lshl_add_u64 v[250:251], v[150:151], 0, v[248:249]
	s_nop 0
	v_permlane16_swap_b32_e32 v244, v246
	v_permlane16_swap_b32_e32 v245, v247
	global_store_dwordx4 v[250:251], v[244:247], off offset:256
	s_waitcnt lgkmcnt(0)
	v_add_f32_e32 v112, v116, v117
	v_mov_b32_e32 v113, v112
	s_nop 1
	v_permlane32_swap_b32_e32 v112, v113
	s_and_saveexec_b64 s[28:29], s[4:5]
	s_cbranch_execz .LBB0_1277
	v_add_f32_e32 v114, v112, v113
	v_lshlrev_b64 v[112:113], 6, v[142:143]
	v_lshl_add_u64 v[112:113], s[10:11], 0, v[112:113]
	v_lshl_add_u64 v[112:113], s[26:27], 2, v[112:113]
	s_lshl_b32 s2, s48, 2
	v_lshl_add_u64 v[112:113], v[112:113], 0, s[2:3]
	global_store_dword v[112:113], v114, off
.LBB0_1277:
	s_or_b64 exec, exec, s[28:29]
	v_or_b32_e32 v112, 16, v142
	v_ashrrev_i32_e32 v113, 31, v112
	v_lshlrev_b64 v[114:115], 11, v[112:113]
	v_lshl_add_u64 v[114:115], s[8:9], 0, v[114:115]
	v_lshl_add_u64 v[114:115], v[140:141], 1, v[114:115]
	s_waitcnt vmcnt(15)
	v_permlane16_swap_b32_e32 v164, v166
	v_permlane16_swap_b32_e32 v165, v167
	v_lshlrev_b32_e32 v118, 16, v164
	v_and_b32_e32 v119, 0xffff0000, v164
	v_lshlrev_b32_e32 v116, 16, v165
	v_and_b32_e32 v117, 0xffff0000, v165
	v_pk_add_f32 v[110:111], v[110:111], v[116:117]
	v_pk_add_f32 v[108:109], v[108:109], v[118:119]
	s_nop 0
	v_cvt_pk_bf16_f32 v116, v108, v109
	v_cvt_pk_bf16_f32 v117, v110, v111
	v_mul_f32_e32 v109, v109, v109
	v_mov_b32_e32 v240, v116
	v_mov_b32_e32 v241, v117
	v_mul_f32_e32 v111, v111, v111
	v_fmac_f32_e32 v109, v108, v108
	v_fmac_f32_e32 v111, v110, v110
	v_add_f32_e32 v108, v109, v111
	s_waitcnt vmcnt(15)
	v_lshlrev_b32_e32 v116, 16, v166
	v_and_b32_e32 v117, 0xffff0000, v166
	v_lshlrev_b32_e32 v118, 16, v167
	v_and_b32_e32 v119, 0xffff0000, v167
	v_pk_add_f32 v[106:107], v[106:107], v[118:119]
	v_pk_add_f32 v[104:105], v[104:105], v[116:117]
	s_nop 0
	v_cvt_pk_bf16_f32 v116, v104, v105
	v_cvt_pk_bf16_f32 v117, v106, v107
	v_mul_f32_e32 v105, v105, v105
	v_mov_b32_e32 v242, v116
	v_mov_b32_e32 v243, v117
	v_lshl_add_u64 v[250:251], v[114:115], 0, v[248:249]
	s_nop 0
	v_permlane16_swap_b32_e32 v240, v242
	v_permlane16_swap_b32_e32 v241, v243
	global_store_dwordx4 v[250:251], v[240:243], off
	v_mul_f32_e32 v107, v107, v107
	v_fmac_f32_e32 v105, v104, v104
	v_fmac_f32_e32 v107, v106, v106
	v_add_f32_e32 v104, v105, v107
	v_add_f32_e32 v104, v108, v104
	s_waitcnt vmcnt(15)
	v_permlane16_swap_b32_e32 v184, v186
	v_permlane16_swap_b32_e32 v185, v187
	v_lshlrev_b32_e32 v116, 16, v184
	v_and_b32_e32 v117, 0xffff0000, v184
	v_lshlrev_b32_e32 v118, 16, v185
	v_and_b32_e32 v119, 0xffff0000, v185
	v_pk_add_f32 v[102:103], v[102:103], v[118:119]
	v_pk_add_f32 v[100:101], v[100:101], v[116:117]
	s_nop 0
	v_cvt_pk_bf16_f32 v116, v100, v101
	v_cvt_pk_bf16_f32 v117, v102, v103
	v_mul_f32_e32 v101, v101, v101
	v_mul_f32_e32 v103, v103, v103
	v_fmac_f32_e32 v101, v100, v100
	v_fmac_f32_e32 v103, v102, v102
	v_add_f32_e32 v100, v101, v103
	v_add_f32_e32 v104, v104, v100
	v_mov_b32_e32 v244, v116
	v_mov_b32_e32 v245, v117
	s_waitcnt vmcnt(15)
	v_lshlrev_b32_e32 v100, 16, v186
	v_and_b32_e32 v101, 0xffff0000, v186
	v_lshlrev_b32_e32 v102, 16, v187
	v_and_b32_e32 v103, 0xffff0000, v187
	v_pk_add_f32 v[98:99], v[98:99], v[102:103]
	v_pk_add_f32 v[96:97], v[96:97], v[100:101]
	v_mul_f32_e32 v101, v99, v99
	v_mul_f32_e32 v100, v97, v97
	v_fmac_f32_e32 v100, v96, v96
	v_fmac_f32_e32 v101, v98, v98
	v_add_f32_e32 v100, v100, v101
	v_add_f32_e32 v100, v104, v100
	ds_swizzle_b32 v101, v100 offset:swizzle(SWAP,16)
	v_cvt_pk_bf16_f32 v96, v96, v97
	v_cvt_pk_bf16_f32 v97, v98, v99
	v_mov_b32_e32 v246, v96
	v_mov_b32_e32 v247, v97
	v_lshl_add_u64 v[250:251], v[114:115], 0, v[248:249]
	s_nop 0
	v_permlane16_swap_b32_e32 v244, v246
	v_permlane16_swap_b32_e32 v245, v247
	global_store_dwordx4 v[250:251], v[244:247], off offset:256
	s_waitcnt lgkmcnt(0)
	v_add_f32_e32 v96, v100, v101
	v_mov_b32_e32 v97, v96
	s_nop 1
	v_permlane32_swap_b32_e32 v96, v97
	s_and_saveexec_b64 s[28:29], s[4:5]
	s_cbranch_execz .LBB0_1279
	v_add_f32_e32 v98, v96, v97
	v_lshlrev_b64 v[96:97], 6, v[112:113]
	v_lshl_add_u64 v[96:97], s[10:11], 0, v[96:97]
	v_lshl_add_u64 v[96:97], s[26:27], 2, v[96:97]
	s_lshl_b32 s2, s48, 2
	v_lshl_add_u64 v[96:97], v[96:97], 0, s[2:3]
	global_store_dword v[96:97], v98, off
.LBB0_1279:
	s_or_b64 exec, exec, s[28:29]
	v_or_b32_e32 v96, 32, v142
	v_ashrrev_i32_e32 v97, 31, v96
	v_lshlrev_b64 v[98:99], 11, v[96:97]
	v_lshl_add_u64 v[98:99], s[8:9], 0, v[98:99]
	v_lshl_add_u64 v[98:99], v[140:141], 1, v[98:99]
	s_waitcnt vmcnt(15)
	v_permlane16_swap_b32_e32 v188, v190
	v_permlane16_swap_b32_e32 v189, v191
	v_lshlrev_b32_e32 v102, 16, v188
	v_and_b32_e32 v103, 0xffff0000, v188
	v_lshlrev_b32_e32 v100, 16, v189
	v_and_b32_e32 v101, 0xffff0000, v189
	v_pk_add_f32 v[94:95], v[94:95], v[100:101]
	v_pk_add_f32 v[92:93], v[92:93], v[102:103]
	s_nop 0
	v_cvt_pk_bf16_f32 v100, v92, v93
	v_cvt_pk_bf16_f32 v101, v94, v95
	v_mul_f32_e32 v93, v93, v93
	v_mov_b32_e32 v240, v100
	v_mov_b32_e32 v241, v101
	v_mul_f32_e32 v95, v95, v95
	v_fmac_f32_e32 v93, v92, v92
	v_fmac_f32_e32 v95, v94, v94
	v_add_f32_e32 v92, v93, v95
	s_waitcnt vmcnt(15)
	v_lshlrev_b32_e32 v100, 16, v190
	v_and_b32_e32 v101, 0xffff0000, v190
	v_lshlrev_b32_e32 v102, 16, v191
	v_and_b32_e32 v103, 0xffff0000, v191
	v_pk_add_f32 v[90:91], v[90:91], v[102:103]
	v_pk_add_f32 v[88:89], v[88:89], v[100:101]
	s_nop 0
	v_cvt_pk_bf16_f32 v100, v88, v89
	v_cvt_pk_bf16_f32 v101, v90, v91
	v_mul_f32_e32 v89, v89, v89
	v_mov_b32_e32 v242, v100
	v_mov_b32_e32 v243, v101
	v_lshl_add_u64 v[250:251], v[98:99], 0, v[248:249]
	s_nop 0
	v_permlane16_swap_b32_e32 v240, v242
	v_permlane16_swap_b32_e32 v241, v243
	global_store_dwordx4 v[250:251], v[240:243], off
	v_mul_f32_e32 v91, v91, v91
	v_fmac_f32_e32 v89, v88, v88
	v_fmac_f32_e32 v91, v90, v90
	v_add_f32_e32 v88, v89, v91
	v_add_f32_e32 v88, v92, v88
	s_waitcnt vmcnt(15)
	v_permlane16_swap_b32_e32 v192, v194
	v_permlane16_swap_b32_e32 v193, v195
	v_lshlrev_b32_e32 v100, 16, v192
	v_and_b32_e32 v101, 0xffff0000, v192
	v_lshlrev_b32_e32 v102, 16, v193
	v_and_b32_e32 v103, 0xffff0000, v193
	v_pk_add_f32 v[86:87], v[86:87], v[102:103]
	v_pk_add_f32 v[84:85], v[84:85], v[100:101]
	s_nop 0
	v_cvt_pk_bf16_f32 v100, v84, v85
	v_cvt_pk_bf16_f32 v101, v86, v87
	v_mul_f32_e32 v85, v85, v85
	v_mul_f32_e32 v87, v87, v87
	v_fmac_f32_e32 v85, v84, v84
	v_fmac_f32_e32 v87, v86, v86
	v_add_f32_e32 v84, v85, v87
	v_add_f32_e32 v88, v88, v84
	v_mov_b32_e32 v244, v100
	v_mov_b32_e32 v245, v101
	s_waitcnt vmcnt(15)
	v_lshlrev_b32_e32 v84, 16, v194
	v_and_b32_e32 v85, 0xffff0000, v194
	v_lshlrev_b32_e32 v86, 16, v195
	v_and_b32_e32 v87, 0xffff0000, v195
	v_pk_add_f32 v[82:83], v[82:83], v[86:87]
	v_pk_add_f32 v[80:81], v[80:81], v[84:85]
	v_mul_f32_e32 v85, v83, v83
	v_mul_f32_e32 v84, v81, v81
	v_fmac_f32_e32 v84, v80, v80
	v_fmac_f32_e32 v85, v82, v82
	v_add_f32_e32 v84, v84, v85
	v_add_f32_e32 v84, v88, v84
	ds_swizzle_b32 v85, v84 offset:swizzle(SWAP,16)
	v_cvt_pk_bf16_f32 v80, v80, v81
	v_cvt_pk_bf16_f32 v81, v82, v83
	v_mov_b32_e32 v246, v80
	v_mov_b32_e32 v247, v81
	v_lshl_add_u64 v[250:251], v[98:99], 0, v[248:249]
	s_nop 0
	v_permlane16_swap_b32_e32 v244, v246
	v_permlane16_swap_b32_e32 v245, v247
	global_store_dwordx4 v[250:251], v[244:247], off offset:256
	s_waitcnt lgkmcnt(0)
	v_add_f32_e32 v80, v84, v85
	v_mov_b32_e32 v81, v80
	s_nop 1
	v_permlane32_swap_b32_e32 v80, v81
	s_and_saveexec_b64 s[28:29], s[4:5]
	s_cbranch_execz .LBB0_1281
	v_add_f32_e32 v82, v80, v81
	v_lshlrev_b64 v[80:81], 6, v[96:97]
	v_lshl_add_u64 v[80:81], s[10:11], 0, v[80:81]
	v_lshl_add_u64 v[80:81], s[26:27], 2, v[80:81]
	s_lshl_b32 s2, s48, 2
	v_lshl_add_u64 v[80:81], v[80:81], 0, s[2:3]
	global_store_dword v[80:81], v82, off
.LBB0_1281:
	s_or_b64 exec, exec, s[28:29]
	v_or_b32_e32 v80, 48, v142
	v_ashrrev_i32_e32 v81, 31, v80
	v_lshlrev_b64 v[82:83], 11, v[80:81]
	v_lshl_add_u64 v[82:83], s[8:9], 0, v[82:83]
	v_lshl_add_u64 v[82:83], v[140:141], 1, v[82:83]
	s_waitcnt vmcnt(15)
	v_permlane16_swap_b32_e32 v196, v198
	v_permlane16_swap_b32_e32 v197, v199
	v_lshlrev_b32_e32 v86, 16, v196
	v_and_b32_e32 v87, 0xffff0000, v196
	v_lshlrev_b32_e32 v84, 16, v197
	v_and_b32_e32 v85, 0xffff0000, v197
	v_pk_add_f32 v[78:79], v[78:79], v[84:85]
	v_pk_add_f32 v[76:77], v[76:77], v[86:87]
	s_nop 0
	v_cvt_pk_bf16_f32 v84, v76, v77
	v_cvt_pk_bf16_f32 v85, v78, v79
	v_mul_f32_e32 v77, v77, v77
	v_mov_b32_e32 v240, v84
	v_mov_b32_e32 v241, v85
	v_mul_f32_e32 v79, v79, v79
	v_fmac_f32_e32 v77, v76, v76
	v_fmac_f32_e32 v79, v78, v78
	v_add_f32_e32 v76, v77, v79
	s_waitcnt vmcnt(15)
	v_lshlrev_b32_e32 v84, 16, v198
	v_and_b32_e32 v85, 0xffff0000, v198
	v_lshlrev_b32_e32 v86, 16, v199
	v_and_b32_e32 v87, 0xffff0000, v199
	v_pk_add_f32 v[74:75], v[74:75], v[86:87]
	v_pk_add_f32 v[72:73], v[72:73], v[84:85]
	s_nop 0
	v_cvt_pk_bf16_f32 v84, v72, v73
	v_cvt_pk_bf16_f32 v85, v74, v75
	v_mul_f32_e32 v73, v73, v73
	v_mov_b32_e32 v242, v84
	v_mov_b32_e32 v243, v85
	v_lshl_add_u64 v[250:251], v[82:83], 0, v[248:249]
	s_nop 0
	v_permlane16_swap_b32_e32 v240, v242
	v_permlane16_swap_b32_e32 v241, v243
	global_store_dwordx4 v[250:251], v[240:243], off
	v_mul_f32_e32 v75, v75, v75
	v_fmac_f32_e32 v73, v72, v72
	v_fmac_f32_e32 v75, v74, v74
	v_add_f32_e32 v72, v73, v75
	v_add_f32_e32 v72, v76, v72
	s_waitcnt vmcnt(15)
	v_permlane16_swap_b32_e32 v200, v202
	v_permlane16_swap_b32_e32 v201, v203
	v_lshlrev_b32_e32 v84, 16, v200
	v_and_b32_e32 v85, 0xffff0000, v200
	v_lshlrev_b32_e32 v86, 16, v201
	v_and_b32_e32 v87, 0xffff0000, v201
	v_pk_add_f32 v[70:71], v[70:71], v[86:87]
	v_pk_add_f32 v[68:69], v[68:69], v[84:85]
	s_nop 0
	v_cvt_pk_bf16_f32 v84, v68, v69
	v_cvt_pk_bf16_f32 v85, v70, v71
	v_mul_f32_e32 v69, v69, v69
	v_mul_f32_e32 v71, v71, v71
	v_fmac_f32_e32 v69, v68, v68
	v_fmac_f32_e32 v71, v70, v70
	v_add_f32_e32 v68, v69, v71
	v_add_f32_e32 v72, v72, v68
	v_mov_b32_e32 v244, v84
	v_mov_b32_e32 v245, v85
	s_waitcnt vmcnt(15)
	v_lshlrev_b32_e32 v68, 16, v202
	v_and_b32_e32 v69, 0xffff0000, v202
	v_lshlrev_b32_e32 v70, 16, v203
	v_and_b32_e32 v71, 0xffff0000, v203
	v_pk_add_f32 v[66:67], v[66:67], v[70:71]
	v_pk_add_f32 v[64:65], v[64:65], v[68:69]
	v_mul_f32_e32 v69, v67, v67
	v_mul_f32_e32 v68, v65, v65
	v_fmac_f32_e32 v68, v64, v64
	v_fmac_f32_e32 v69, v66, v66
	v_add_f32_e32 v68, v68, v69
	v_add_f32_e32 v68, v72, v68
	ds_swizzle_b32 v69, v68 offset:swizzle(SWAP,16)
	v_cvt_pk_bf16_f32 v64, v64, v65
	v_cvt_pk_bf16_f32 v65, v66, v67
	v_mov_b32_e32 v246, v64
	v_mov_b32_e32 v247, v65
	v_lshl_add_u64 v[250:251], v[82:83], 0, v[248:249]
	s_nop 0
	v_permlane16_swap_b32_e32 v244, v246
	v_permlane16_swap_b32_e32 v245, v247
	global_store_dwordx4 v[250:251], v[244:247], off offset:256
	s_waitcnt lgkmcnt(0)
	v_add_f32_e32 v64, v68, v69
	v_mov_b32_e32 v65, v64
	s_nop 1
	v_permlane32_swap_b32_e32 v64, v65
	s_and_saveexec_b64 s[28:29], s[4:5]
	s_cbranch_execz .LBB0_1283
	v_add_f32_e32 v66, v64, v65
	v_lshlrev_b64 v[64:65], 6, v[80:81]
	v_lshl_add_u64 v[64:65], s[10:11], 0, v[64:65]
	v_lshl_add_u64 v[64:65], s[26:27], 2, v[64:65]
	s_lshl_b32 s2, s48, 2
	v_lshl_add_u64 v[64:65], v[64:65], 0, s[2:3]
	global_store_dword v[64:65], v66, off
.LBB0_1283:
	s_or_b64 exec, exec, s[28:29]
	v_add_u32_e32 v64, 0x80, v142
	v_ashrrev_i32_e32 v65, 31, v64
	v_lshlrev_b64 v[66:67], 11, v[64:65]
	v_lshl_add_u64 v[66:67], s[8:9], 0, v[66:67]
	v_lshl_add_u64 v[66:67], v[140:141], 1, v[66:67]
	s_waitcnt vmcnt(15)
	v_permlane16_swap_b32_e32 v208, v210
	v_permlane16_swap_b32_e32 v209, v211
	v_lshlrev_b32_e32 v70, 16, v208
	v_and_b32_e32 v71, 0xffff0000, v208
	v_lshlrev_b32_e32 v68, 16, v209
	v_and_b32_e32 v69, 0xffff0000, v209
	v_pk_add_f32 v[62:63], v[62:63], v[68:69]
	v_pk_add_f32 v[60:61], v[60:61], v[70:71]
	s_nop 0
	v_cvt_pk_bf16_f32 v68, v60, v61
	v_cvt_pk_bf16_f32 v69, v62, v63
	v_mul_f32_e32 v61, v61, v61
	v_mov_b32_e32 v240, v68
	v_mov_b32_e32 v241, v69
	v_mul_f32_e32 v63, v63, v63
	v_fmac_f32_e32 v61, v60, v60
	v_fmac_f32_e32 v63, v62, v62
	v_add_f32_e32 v60, v61, v63
	s_waitcnt vmcnt(15)
	v_lshlrev_b32_e32 v68, 16, v210
	v_and_b32_e32 v69, 0xffff0000, v210
	v_lshlrev_b32_e32 v70, 16, v211
	v_and_b32_e32 v71, 0xffff0000, v211
	v_pk_add_f32 v[58:59], v[58:59], v[70:71]
	v_pk_add_f32 v[56:57], v[56:57], v[68:69]
	s_nop 0
	v_cvt_pk_bf16_f32 v68, v56, v57
	v_cvt_pk_bf16_f32 v69, v58, v59
	v_mul_f32_e32 v57, v57, v57
	v_mov_b32_e32 v242, v68
	v_mov_b32_e32 v243, v69
	v_lshl_add_u64 v[250:251], v[66:67], 0, v[248:249]
	s_nop 0
	v_permlane16_swap_b32_e32 v240, v242
	v_permlane16_swap_b32_e32 v241, v243
	global_store_dwordx4 v[250:251], v[240:243], off
	v_mul_f32_e32 v59, v59, v59
	v_fmac_f32_e32 v57, v56, v56
	v_fmac_f32_e32 v59, v58, v58
	v_add_f32_e32 v56, v57, v59
	v_add_f32_e32 v56, v60, v56
	s_waitcnt vmcnt(15)
	v_permlane16_swap_b32_e32 v212, v214
	v_permlane16_swap_b32_e32 v213, v215
	v_lshlrev_b32_e32 v68, 16, v212
	v_and_b32_e32 v69, 0xffff0000, v212
	v_lshlrev_b32_e32 v70, 16, v213
	v_and_b32_e32 v71, 0xffff0000, v213
	v_pk_add_f32 v[54:55], v[54:55], v[70:71]
	v_pk_add_f32 v[52:53], v[52:53], v[68:69]
	s_nop 0
	v_cvt_pk_bf16_f32 v68, v52, v53
	v_cvt_pk_bf16_f32 v69, v54, v55
	v_mul_f32_e32 v53, v53, v53
	v_mul_f32_e32 v55, v55, v55
	v_fmac_f32_e32 v53, v52, v52
	v_fmac_f32_e32 v55, v54, v54
	v_add_f32_e32 v52, v53, v55
	v_add_f32_e32 v56, v56, v52
	v_mov_b32_e32 v244, v68
	v_mov_b32_e32 v245, v69
	s_waitcnt vmcnt(15)
	v_lshlrev_b32_e32 v52, 16, v214
	v_and_b32_e32 v53, 0xffff0000, v214
	v_lshlrev_b32_e32 v54, 16, v215
	v_and_b32_e32 v55, 0xffff0000, v215
	v_pk_add_f32 v[50:51], v[50:51], v[54:55]
	v_pk_add_f32 v[48:49], v[48:49], v[52:53]
	v_mul_f32_e32 v53, v51, v51
	v_mul_f32_e32 v52, v49, v49
	v_fmac_f32_e32 v52, v48, v48
	v_fmac_f32_e32 v53, v50, v50
	v_add_f32_e32 v52, v52, v53
	v_add_f32_e32 v52, v56, v52
	ds_swizzle_b32 v53, v52 offset:swizzle(SWAP,16)
	v_cvt_pk_bf16_f32 v48, v48, v49
	v_cvt_pk_bf16_f32 v49, v50, v51
	v_mov_b32_e32 v246, v48
	v_mov_b32_e32 v247, v49
	v_lshl_add_u64 v[250:251], v[66:67], 0, v[248:249]
	s_nop 0
	v_permlane16_swap_b32_e32 v244, v246
	v_permlane16_swap_b32_e32 v245, v247
	global_store_dwordx4 v[250:251], v[244:247], off offset:256
	s_waitcnt lgkmcnt(0)
	v_add_f32_e32 v48, v52, v53
	v_mov_b32_e32 v49, v48
	s_nop 1
	v_permlane32_swap_b32_e32 v48, v49
	s_and_saveexec_b64 s[28:29], s[4:5]
	s_cbranch_execz .LBB0_1285
	v_add_f32_e32 v50, v48, v49
	v_lshlrev_b64 v[48:49], 6, v[64:65]
	v_lshl_add_u64 v[48:49], s[10:11], 0, v[48:49]
	v_lshl_add_u64 v[48:49], s[26:27], 2, v[48:49]
	s_lshl_b32 s2, s48, 2
	v_lshl_add_u64 v[48:49], v[48:49], 0, s[2:3]
	global_store_dword v[48:49], v50, off
.LBB0_1285:
	s_or_b64 exec, exec, s[28:29]
	v_add_u32_e32 v48, 0x90, v142
	v_ashrrev_i32_e32 v49, 31, v48
	v_lshlrev_b64 v[50:51], 11, v[48:49]
	v_lshl_add_u64 v[50:51], s[8:9], 0, v[50:51]
	v_lshl_add_u64 v[50:51], v[140:141], 1, v[50:51]
	s_waitcnt vmcnt(15)
	v_permlane16_swap_b32_e32 v216, v218
	v_permlane16_swap_b32_e32 v217, v219
	v_lshlrev_b32_e32 v54, 16, v216
	v_and_b32_e32 v55, 0xffff0000, v216
	v_lshlrev_b32_e32 v52, 16, v217
	v_and_b32_e32 v53, 0xffff0000, v217
	v_pk_add_f32 v[46:47], v[46:47], v[52:53]
	v_pk_add_f32 v[44:45], v[44:45], v[54:55]
	s_nop 0
	v_cvt_pk_bf16_f32 v52, v44, v45
	v_cvt_pk_bf16_f32 v53, v46, v47
	v_mul_f32_e32 v45, v45, v45
	v_mov_b32_e32 v240, v52
	v_mov_b32_e32 v241, v53
	v_mul_f32_e32 v47, v47, v47
	v_fmac_f32_e32 v45, v44, v44
	v_fmac_f32_e32 v47, v46, v46
	v_add_f32_e32 v44, v45, v47
	s_waitcnt vmcnt(15)
	v_lshlrev_b32_e32 v52, 16, v218
	v_and_b32_e32 v53, 0xffff0000, v218
	v_lshlrev_b32_e32 v54, 16, v219
	v_and_b32_e32 v55, 0xffff0000, v219
	v_pk_add_f32 v[42:43], v[42:43], v[54:55]
	v_pk_add_f32 v[40:41], v[40:41], v[52:53]
	s_nop 0
	v_cvt_pk_bf16_f32 v52, v40, v41
	v_cvt_pk_bf16_f32 v53, v42, v43
	v_mul_f32_e32 v41, v41, v41
	v_mov_b32_e32 v242, v52
	v_mov_b32_e32 v243, v53
	v_lshl_add_u64 v[250:251], v[50:51], 0, v[248:249]
	s_nop 0
	v_permlane16_swap_b32_e32 v240, v242
	v_permlane16_swap_b32_e32 v241, v243
	global_store_dwordx4 v[250:251], v[240:243], off
	v_mul_f32_e32 v43, v43, v43
	v_fmac_f32_e32 v41, v40, v40
	v_fmac_f32_e32 v43, v42, v42
	v_add_f32_e32 v40, v41, v43
	v_add_f32_e32 v40, v44, v40
	s_waitcnt vmcnt(15)
	v_permlane16_swap_b32_e32 v220, v222
	v_permlane16_swap_b32_e32 v221, v223
	v_lshlrev_b32_e32 v52, 16, v220
	v_and_b32_e32 v53, 0xffff0000, v220
	v_lshlrev_b32_e32 v54, 16, v221
	v_and_b32_e32 v55, 0xffff0000, v221
	v_pk_add_f32 v[38:39], v[38:39], v[54:55]
	v_pk_add_f32 v[36:37], v[36:37], v[52:53]
	s_nop 0
	v_cvt_pk_bf16_f32 v52, v36, v37
	v_cvt_pk_bf16_f32 v53, v38, v39
	v_mul_f32_e32 v37, v37, v37
	v_mul_f32_e32 v39, v39, v39
	v_fmac_f32_e32 v37, v36, v36
	v_fmac_f32_e32 v39, v38, v38
	v_add_f32_e32 v36, v37, v39
	v_add_f32_e32 v40, v40, v36
	v_mov_b32_e32 v244, v52
	v_mov_b32_e32 v245, v53
	s_waitcnt vmcnt(15)
	v_lshlrev_b32_e32 v36, 16, v222
	v_and_b32_e32 v37, 0xffff0000, v222
	v_lshlrev_b32_e32 v38, 16, v223
	v_and_b32_e32 v39, 0xffff0000, v223
	v_pk_add_f32 v[34:35], v[34:35], v[38:39]
	v_pk_add_f32 v[32:33], v[32:33], v[36:37]
	v_mul_f32_e32 v37, v35, v35
	v_mul_f32_e32 v36, v33, v33
	v_fmac_f32_e32 v36, v32, v32
	v_fmac_f32_e32 v37, v34, v34
	v_add_f32_e32 v36, v36, v37
	v_add_f32_e32 v36, v40, v36
	ds_swizzle_b32 v37, v36 offset:swizzle(SWAP,16)
	v_cvt_pk_bf16_f32 v32, v32, v33
	v_cvt_pk_bf16_f32 v33, v34, v35
	v_mov_b32_e32 v246, v32
	v_mov_b32_e32 v247, v33
	v_lshl_add_u64 v[250:251], v[50:51], 0, v[248:249]
	s_nop 0
	v_permlane16_swap_b32_e32 v244, v246
	v_permlane16_swap_b32_e32 v245, v247
	global_store_dwordx4 v[250:251], v[244:247], off offset:256
	s_waitcnt lgkmcnt(0)
	v_add_f32_e32 v32, v36, v37
	v_mov_b32_e32 v33, v32
	s_nop 1
	v_permlane32_swap_b32_e32 v32, v33
	s_and_saveexec_b64 s[28:29], s[4:5]
	s_cbranch_execz .LBB0_1287
	v_add_f32_e32 v34, v32, v33
	v_lshlrev_b64 v[32:33], 6, v[48:49]
	v_lshl_add_u64 v[32:33], s[10:11], 0, v[32:33]
	v_lshl_add_u64 v[32:33], s[26:27], 2, v[32:33]
	s_lshl_b32 s2, s48, 2
	v_lshl_add_u64 v[32:33], v[32:33], 0, s[2:3]
	global_store_dword v[32:33], v34, off
.LBB0_1287:
	s_or_b64 exec, exec, s[28:29]
	v_add_u32_e32 v32, 0xa0, v142
	v_ashrrev_i32_e32 v33, 31, v32
	v_lshlrev_b64 v[34:35], 11, v[32:33]
	v_lshl_add_u64 v[34:35], s[8:9], 0, v[34:35]
	v_lshl_add_u64 v[34:35], v[140:141], 1, v[34:35]
	s_waitcnt vmcnt(15)
	v_permlane16_swap_b32_e32 v224, v226
	v_permlane16_swap_b32_e32 v225, v227
	v_lshlrev_b32_e32 v38, 16, v224
	v_and_b32_e32 v39, 0xffff0000, v224
	v_lshlrev_b32_e32 v36, 16, v225
	v_and_b32_e32 v37, 0xffff0000, v225
	v_pk_add_f32 v[30:31], v[30:31], v[36:37]
	v_pk_add_f32 v[28:29], v[28:29], v[38:39]
	s_nop 0
	v_cvt_pk_bf16_f32 v36, v28, v29
	v_cvt_pk_bf16_f32 v37, v30, v31
	v_mul_f32_e32 v29, v29, v29
	v_mov_b32_e32 v240, v36
	v_mov_b32_e32 v241, v37
	v_mul_f32_e32 v31, v31, v31
	v_fmac_f32_e32 v29, v28, v28
	v_fmac_f32_e32 v31, v30, v30
	v_add_f32_e32 v28, v29, v31
	s_waitcnt vmcnt(15)
	v_lshlrev_b32_e32 v36, 16, v226
	v_and_b32_e32 v37, 0xffff0000, v226
	v_lshlrev_b32_e32 v38, 16, v227
	v_and_b32_e32 v39, 0xffff0000, v227
	v_pk_add_f32 v[26:27], v[26:27], v[38:39]
	v_pk_add_f32 v[24:25], v[24:25], v[36:37]
	s_nop 0
	v_cvt_pk_bf16_f32 v36, v24, v25
	v_cvt_pk_bf16_f32 v37, v26, v27
	v_mul_f32_e32 v25, v25, v25
	v_mov_b32_e32 v242, v36
	v_mov_b32_e32 v243, v37
	v_lshl_add_u64 v[250:251], v[34:35], 0, v[248:249]
	s_nop 0
	v_permlane16_swap_b32_e32 v240, v242
	v_permlane16_swap_b32_e32 v241, v243
	global_store_dwordx4 v[250:251], v[240:243], off
	v_mul_f32_e32 v27, v27, v27
	v_fmac_f32_e32 v25, v24, v24
	v_fmac_f32_e32 v27, v26, v26
	v_add_f32_e32 v24, v25, v27
	v_add_f32_e32 v24, v28, v24
	s_waitcnt vmcnt(15)
	v_permlane16_swap_b32_e32 v228, v230
	v_permlane16_swap_b32_e32 v229, v231
	v_lshlrev_b32_e32 v36, 16, v228
	v_and_b32_e32 v37, 0xffff0000, v228
	v_lshlrev_b32_e32 v38, 16, v229
	v_and_b32_e32 v39, 0xffff0000, v229
	v_pk_add_f32 v[22:23], v[22:23], v[38:39]
	v_pk_add_f32 v[20:21], v[20:21], v[36:37]
	s_nop 0
	v_cvt_pk_bf16_f32 v36, v20, v21
	v_cvt_pk_bf16_f32 v37, v22, v23
	v_mul_f32_e32 v21, v21, v21
	v_mul_f32_e32 v23, v23, v23
	v_fmac_f32_e32 v21, v20, v20
	v_fmac_f32_e32 v23, v22, v22
	v_add_f32_e32 v20, v21, v23
	v_add_f32_e32 v24, v24, v20
	v_mov_b32_e32 v244, v36
	v_mov_b32_e32 v245, v37
	s_waitcnt vmcnt(15)
	v_lshlrev_b32_e32 v20, 16, v230
	v_and_b32_e32 v21, 0xffff0000, v230
	v_lshlrev_b32_e32 v22, 16, v231
	v_and_b32_e32 v23, 0xffff0000, v231
	v_pk_add_f32 v[18:19], v[18:19], v[22:23]
	v_pk_add_f32 v[16:17], v[16:17], v[20:21]
	v_mul_f32_e32 v21, v19, v19
	v_mul_f32_e32 v20, v17, v17
	v_fmac_f32_e32 v20, v16, v16
	v_fmac_f32_e32 v21, v18, v18
	v_add_f32_e32 v20, v20, v21
	v_add_f32_e32 v20, v24, v20
	ds_swizzle_b32 v21, v20 offset:swizzle(SWAP,16)
	v_cvt_pk_bf16_f32 v16, v16, v17
	v_cvt_pk_bf16_f32 v17, v18, v19
	v_mov_b32_e32 v246, v16
	v_mov_b32_e32 v247, v17
	v_lshl_add_u64 v[250:251], v[34:35], 0, v[248:249]
	s_nop 0
	v_permlane16_swap_b32_e32 v244, v246
	v_permlane16_swap_b32_e32 v245, v247
	global_store_dwordx4 v[250:251], v[244:247], off offset:256
	s_waitcnt lgkmcnt(0)
	v_add_f32_e32 v16, v20, v21
	v_mov_b32_e32 v17, v16
	s_nop 1
	v_permlane32_swap_b32_e32 v16, v17
	s_and_saveexec_b64 s[28:29], s[4:5]
	s_cbranch_execz .LBB0_1289
	v_add_f32_e32 v18, v16, v17
	v_lshlrev_b64 v[16:17], 6, v[32:33]
	v_lshl_add_u64 v[16:17], s[10:11], 0, v[16:17]
	v_lshl_add_u64 v[16:17], s[26:27], 2, v[16:17]
	s_lshl_b32 s2, s48, 2
	v_lshl_add_u64 v[16:17], v[16:17], 0, s[2:3]
	global_store_dword v[16:17], v18, off
.LBB0_1289:
	s_or_b64 exec, exec, s[28:29]
	v_add_u32_e32 v16, 0xb0, v142
	v_ashrrev_i32_e32 v17, 31, v16
	v_lshlrev_b64 v[18:19], 11, v[16:17]
	v_lshl_add_u64 v[18:19], s[8:9], 0, v[18:19]
	v_lshl_add_u64 v[18:19], v[140:141], 1, v[18:19]
	s_waitcnt vmcnt(15)
	v_permlane16_swap_b32_e32 v232, v234
	v_permlane16_swap_b32_e32 v233, v235
	v_lshlrev_b32_e32 v22, 16, v232
	v_and_b32_e32 v23, 0xffff0000, v232
	v_lshlrev_b32_e32 v20, 16, v233
	v_and_b32_e32 v21, 0xffff0000, v233
	v_pk_add_f32 v[14:15], v[14:15], v[20:21]
	v_pk_add_f32 v[12:13], v[12:13], v[22:23]
	s_nop 0
	v_cvt_pk_bf16_f32 v20, v12, v13
	v_cvt_pk_bf16_f32 v21, v14, v15
	v_mul_f32_e32 v13, v13, v13
	v_mov_b32_e32 v240, v20
	v_mov_b32_e32 v241, v21
	v_mul_f32_e32 v15, v15, v15
	v_fmac_f32_e32 v13, v12, v12
	v_fmac_f32_e32 v15, v14, v14
	v_add_f32_e32 v12, v13, v15
	s_waitcnt vmcnt(15)
	v_lshlrev_b32_e32 v20, 16, v234
	v_and_b32_e32 v21, 0xffff0000, v234
	v_lshlrev_b32_e32 v22, 16, v235
	v_and_b32_e32 v23, 0xffff0000, v235
	v_pk_add_f32 v[10:11], v[10:11], v[22:23]
	v_pk_add_f32 v[8:9], v[8:9], v[20:21]
	s_nop 0
	v_cvt_pk_bf16_f32 v20, v8, v9
	v_cvt_pk_bf16_f32 v21, v10, v11
	v_mul_f32_e32 v9, v9, v9
	v_mov_b32_e32 v242, v20
	v_mov_b32_e32 v243, v21
	v_lshl_add_u64 v[250:251], v[18:19], 0, v[248:249]
	s_nop 0
	v_permlane16_swap_b32_e32 v240, v242
	v_permlane16_swap_b32_e32 v241, v243
	global_store_dwordx4 v[250:251], v[240:243], off
	v_mul_f32_e32 v11, v11, v11
	v_fmac_f32_e32 v9, v8, v8
	v_fmac_f32_e32 v11, v10, v10
	v_add_f32_e32 v8, v9, v11
	v_add_f32_e32 v8, v12, v8
	s_waitcnt vmcnt(15)
	v_permlane16_swap_b32_e32 v236, v238
	v_permlane16_swap_b32_e32 v237, v239
	v_lshlrev_b32_e32 v20, 16, v236
	v_and_b32_e32 v21, 0xffff0000, v236
	v_lshlrev_b32_e32 v22, 16, v237
	v_and_b32_e32 v23, 0xffff0000, v237
	v_pk_add_f32 v[6:7], v[6:7], v[22:23]
	v_pk_add_f32 v[4:5], v[4:5], v[20:21]
	s_nop 0
	v_cvt_pk_bf16_f32 v20, v4, v5
	v_cvt_pk_bf16_f32 v21, v6, v7
	v_mul_f32_e32 v5, v5, v5
	v_mul_f32_e32 v7, v7, v7
	v_fmac_f32_e32 v5, v4, v4
	v_fmac_f32_e32 v7, v6, v6
	v_add_f32_e32 v4, v5, v7
	v_add_f32_e32 v8, v8, v4
	v_mov_b32_e32 v244, v20
	v_mov_b32_e32 v245, v21
	s_waitcnt vmcnt(15)
	v_lshlrev_b32_e32 v4, 16, v238
	v_and_b32_e32 v5, 0xffff0000, v238
	v_lshlrev_b32_e32 v6, 16, v239
	v_and_b32_e32 v7, 0xffff0000, v239
	v_pk_add_f32 v[2:3], v[2:3], v[6:7]
	v_pk_add_f32 v[0:1], v[0:1], v[4:5]
	v_mul_f32_e32 v5, v3, v3
	v_mul_f32_e32 v4, v1, v1
	v_fmac_f32_e32 v4, v0, v0
	v_fmac_f32_e32 v5, v2, v2
	v_add_f32_e32 v4, v4, v5
	v_add_f32_e32 v4, v8, v4
	ds_swizzle_b32 v5, v4 offset:swizzle(SWAP,16)
	v_cvt_pk_bf16_f32 v0, v0, v1
	v_cvt_pk_bf16_f32 v1, v2, v3
	v_mov_b32_e32 v246, v0
	v_mov_b32_e32 v247, v1
	v_lshl_add_u64 v[250:251], v[18:19], 0, v[248:249]
	s_nop 0
	v_permlane16_swap_b32_e32 v244, v246
	v_permlane16_swap_b32_e32 v245, v247
	global_store_dwordx4 v[250:251], v[244:247], off offset:256
	s_waitcnt lgkmcnt(0)
	v_add_f32_e32 v0, v4, v5
	v_mov_b32_e32 v1, v0
	s_nop 1
	v_permlane32_swap_b32_e32 v0, v1
	s_and_saveexec_b64 s[28:29], s[4:5]
	s_cbranch_execz .LBB0_1291
	v_add_f32_e32 v2, v0, v1
	v_lshlrev_b64 v[0:1], 6, v[16:17]
	v_lshl_add_u64 v[0:1], s[10:11], 0, v[0:1]
	v_lshl_add_u64 v[0:1], s[26:27], 2, v[0:1]
	s_lshl_b32 s2, s48, 2
	v_lshl_add_u64 v[0:1], v[0:1], 0, s[2:3]
	global_store_dword v[0:1], v2, off

.LBB0_1447:
	v_lshl_add_u32 v142, s26, 8, v144
	v_ashrrev_i32_e32 v143, 31, v142
	v_lshl_or_b32 v140, s2, 8, v146
	v_lshlrev_b64 v[150:151], 11, v[142:143]
	v_ashrrev_i32_e32 v141, 31, v140
	v_lshl_add_u64 v[150:151], s[10:11], 0, v[150:151]
	v_lshl_add_u64 v[150:151], v[140:141], 1, v[150:151]
	s_mov_b64 s[98:99], 0x8000
	s_mov_b64 s[100:101], 0x28000
	v_bfe_u32 v248, v206, 4, 1
	v_mul_u32_u24_e32 v248, 24, v248
	v_mov_b32_e32 v249, 0
	v_lshl_add_u64 v[250:251], v[150:151], 0, v[248:249]
	global_load_dwordx4 v[156:159], v[250:251], off
	global_load_dwordx4 v[160:163], v[250:251], off offset:256
	v_lshl_add_u64 v[250:251], v[250:251], 0, s[98:99]
	global_load_dwordx4 v[164:167], v[250:251], off
	global_load_dwordx4 v[184:187], v[250:251], off offset:256
	v_lshl_add_u64 v[250:251], v[250:251], 0, s[98:99]
	global_load_dwordx4 v[188:191], v[250:251], off
	global_load_dwordx4 v[192:195], v[250:251], off offset:256
	v_lshl_add_u64 v[250:251], v[250:251], 0, s[98:99]
	global_load_dwordx4 v[196:199], v[250:251], off
	global_load_dwordx4 v[200:203], v[250:251], off offset:256
	v_lshl_add_u64 v[250:251], v[250:251], 0, s[100:101]
	global_load_dwordx4 v[208:211], v[250:251], off
	global_load_dwordx4 v[212:215], v[250:251], off offset:256
	v_lshl_add_u64 v[250:251], v[250:251], 0, s[98:99]
	global_load_dwordx4 v[216:219], v[250:251], off
	global_load_dwordx4 v[220:223], v[250:251], off offset:256
	v_lshl_add_u64 v[250:251], v[250:251], 0, s[98:99]
	global_load_dwordx4 v[224:227], v[250:251], off
	global_load_dwordx4 v[228:231], v[250:251], off offset:256
	v_lshl_add_u64 v[250:251], v[250:251], 0, s[98:99]
	global_load_dwordx4 v[232:235], v[250:251], off
	global_load_dwordx4 v[236:239], v[250:251], off offset:256
	s_lshl_b32 s26, s2, 2
	s_ashr_i32 s27, s26, 31
	s_waitcnt vmcnt(15)
	v_permlane16_swap_b32_e32 v156, v158
	v_permlane16_swap_b32_e32 v157, v159
	v_lshlrev_b32_e32 v154, 16, v156
	v_and_b32_e32 v155, 0xffff0000, v156
	v_lshlrev_b32_e32 v152, 16, v157
	v_and_b32_e32 v153, 0xffff0000, v157
	v_pk_add_f32 v[126:127], v[126:127], v[152:153]
	v_pk_add_f32 v[124:125], v[124:125], v[154:155]
	s_nop 0
	v_cvt_pk_bf16_f32 v152, v124, v125
	v_cvt_pk_bf16_f32 v153, v126, v127
	v_mul_f32_e32 v125, v125, v125
	v_mov_b32_e32 v240, v152
	v_mov_b32_e32 v241, v153
	v_mul_f32_e32 v127, v127, v127
	v_fmac_f32_e32 v125, v124, v124
	v_fmac_f32_e32 v127, v126, v126
	v_add_f32_e32 v124, v125, v127
	s_waitcnt vmcnt(15)
	v_lshlrev_b32_e32 v152, 16, v158
	v_and_b32_e32 v153, 0xffff0000, v158
	v_lshlrev_b32_e32 v154, 16, v159
	v_and_b32_e32 v155, 0xffff0000, v159
	v_pk_add_f32 v[122:123], v[122:123], v[154:155]
	v_pk_add_f32 v[120:121], v[120:121], v[152:153]
	s_nop 0
	v_cvt_pk_bf16_f32 v152, v120, v121
	v_cvt_pk_bf16_f32 v153, v122, v123
	v_mul_f32_e32 v121, v121, v121
	v_mov_b32_e32 v242, v152
	v_mov_b32_e32 v243, v153
	v_lshl_add_u64 v[250:251], v[150:151], 0, v[248:249]
	s_nop 0
	v_permlane16_swap_b32_e32 v240, v242
	v_permlane16_swap_b32_e32 v241, v243
	global_store_dwordx4 v[250:251], v[240:243], off
	v_mul_f32_e32 v123, v123, v123
	v_fmac_f32_e32 v121, v120, v120
	v_fmac_f32_e32 v123, v122, v122
	v_add_f32_e32 v120, v121, v123
	v_add_f32_e32 v120, v124, v120
	s_waitcnt vmcnt(15)
	v_permlane16_swap_b32_e32 v160, v162
	v_permlane16_swap_b32_e32 v161, v163
	v_lshlrev_b32_e32 v152, 16, v160
	v_and_b32_e32 v153, 0xffff0000, v160
	v_lshlrev_b32_e32 v154, 16, v161
	v_and_b32_e32 v155, 0xffff0000, v161
	v_pk_add_f32 v[118:119], v[118:119], v[154:155]
	v_pk_add_f32 v[116:117], v[116:117], v[152:153]
	s_nop 0
	v_cvt_pk_bf16_f32 v152, v116, v117
	v_cvt_pk_bf16_f32 v153, v118, v119
	v_mul_f32_e32 v117, v117, v117
	v_mul_f32_e32 v119, v119, v119
	v_fmac_f32_e32 v117, v116, v116
	v_fmac_f32_e32 v119, v118, v118
	v_add_f32_e32 v116, v117, v119
	v_add_f32_e32 v120, v120, v116
	v_mov_b32_e32 v244, v152
	v_mov_b32_e32 v245, v153
	s_waitcnt vmcnt(15)
	v_lshlrev_b32_e32 v116, 16, v162
	v_and_b32_e32 v117, 0xffff0000, v162
	v_lshlrev_b32_e32 v118, 16, v163
	v_and_b32_e32 v119, 0xffff0000, v163
	v_pk_add_f32 v[114:115], v[114:115], v[118:119]
	v_pk_add_f32 v[112:113], v[112:113], v[116:117]
	v_mul_f32_e32 v117, v115, v115
	v_mul_f32_e32 v116, v113, v113
	v_fmac_f32_e32 v116, v112, v112
	v_fmac_f32_e32 v117, v114, v114
	v_add_f32_e32 v116, v116, v117
	v_add_f32_e32 v116, v120, v116
	ds_swizzle_b32 v117, v116 offset:swizzle(SWAP,16)
	v_cvt_pk_bf16_f32 v112, v112, v113
	v_cvt_pk_bf16_f32 v113, v114, v115
	v_mov_b32_e32 v246, v112
	v_mov_b32_e32 v247, v113
	v_lshl_add_u64 v[250:251], v[150:151], 0, v[248:249]
	s_nop 0
	v_permlane16_swap_b32_e32 v244, v246
	v_permlane16_swap_b32_e32 v245, v247
	global_store_dwordx4 v[250:251], v[244:247], off offset:256
	s_waitcnt lgkmcnt(0)
	v_add_f32_e32 v112, v116, v117
	v_mov_b32_e32 v113, v112
	s_nop 1
	v_permlane32_swap_b32_e32 v112, v113
	s_and_saveexec_b64 s[28:29], s[4:5]
	s_cbranch_execz .LBB0_1449
	v_add_f32_e32 v114, v112, v113
	v_lshlrev_b64 v[112:113], 6, v[142:143]
	v_lshl_add_u64 v[112:113], s[12:13], 0, v[112:113]
	v_lshl_add_u64 v[112:113], s[26:27], 2, v[112:113]
	s_lshl_b32 s2, s48, 2
	v_lshl_add_u64 v[112:113], v[112:113], 0, s[2:3]
	global_store_dword v[112:113], v114, off
.LBB0_1449:
	s_or_b64 exec, exec, s[28:29]
	v_or_b32_e32 v112, 16, v142
	v_ashrrev_i32_e32 v113, 31, v112
	v_lshlrev_b64 v[114:115], 11, v[112:113]
	v_lshl_add_u64 v[114:115], s[10:11], 0, v[114:115]
	v_lshl_add_u64 v[114:115], v[140:141], 1, v[114:115]
	s_waitcnt vmcnt(15)
	v_permlane16_swap_b32_e32 v164, v166
	v_permlane16_swap_b32_e32 v165, v167
	v_lshlrev_b32_e32 v118, 16, v164
	v_and_b32_e32 v119, 0xffff0000, v164
	v_lshlrev_b32_e32 v116, 16, v165
	v_and_b32_e32 v117, 0xffff0000, v165
	v_pk_add_f32 v[110:111], v[110:111], v[116:117]
	v_pk_add_f32 v[108:109], v[108:109], v[118:119]
	s_nop 0
	v_cvt_pk_bf16_f32 v116, v108, v109
	v_cvt_pk_bf16_f32 v117, v110, v111
	v_mul_f32_e32 v109, v109, v109
	v_mov_b32_e32 v240, v116
	v_mov_b32_e32 v241, v117
	v_mul_f32_e32 v111, v111, v111
	v_fmac_f32_e32 v109, v108, v108
	v_fmac_f32_e32 v111, v110, v110
	v_add_f32_e32 v108, v109, v111
	s_waitcnt vmcnt(15)
	v_lshlrev_b32_e32 v116, 16, v166
	v_and_b32_e32 v117, 0xffff0000, v166
	v_lshlrev_b32_e32 v118, 16, v167
	v_and_b32_e32 v119, 0xffff0000, v167
	v_pk_add_f32 v[106:107], v[106:107], v[118:119]
	v_pk_add_f32 v[104:105], v[104:105], v[116:117]
	s_nop 0
	v_cvt_pk_bf16_f32 v116, v104, v105
	v_cvt_pk_bf16_f32 v117, v106, v107
	v_mul_f32_e32 v105, v105, v105
	v_mov_b32_e32 v242, v116
	v_mov_b32_e32 v243, v117
	v_lshl_add_u64 v[250:251], v[114:115], 0, v[248:249]
	s_nop 0
	v_permlane16_swap_b32_e32 v240, v242
	v_permlane16_swap_b32_e32 v241, v243
	global_store_dwordx4 v[250:251], v[240:243], off
	v_mul_f32_e32 v107, v107, v107
	v_fmac_f32_e32 v105, v104, v104
	v_fmac_f32_e32 v107, v106, v106
	v_add_f32_e32 v104, v105, v107
	v_add_f32_e32 v104, v108, v104
	s_waitcnt vmcnt(15)
	v_permlane16_swap_b32_e32 v184, v186
	v_permlane16_swap_b32_e32 v185, v187
	v_lshlrev_b32_e32 v116, 16, v184
	v_and_b32_e32 v117, 0xffff0000, v184
	v_lshlrev_b32_e32 v118, 16, v185
	v_and_b32_e32 v119, 0xffff0000, v185
	v_pk_add_f32 v[102:103], v[102:103], v[118:119]
	v_pk_add_f32 v[100:101], v[100:101], v[116:117]
	s_nop 0
	v_cvt_pk_bf16_f32 v116, v100, v101
	v_cvt_pk_bf16_f32 v117, v102, v103
	v_mul_f32_e32 v101, v101, v101
	v_mul_f32_e32 v103, v103, v103
	v_fmac_f32_e32 v101, v100, v100
	v_fmac_f32_e32 v103, v102, v102
	v_add_f32_e32 v100, v101, v103
	v_add_f32_e32 v104, v104, v100
	v_mov_b32_e32 v244, v116
	v_mov_b32_e32 v245, v117
	s_waitcnt vmcnt(15)
	v_lshlrev_b32_e32 v100, 16, v186
	v_and_b32_e32 v101, 0xffff0000, v186
	v_lshlrev_b32_e32 v102, 16, v187
	v_and_b32_e32 v103, 0xffff0000, v187
	v_pk_add_f32 v[98:99], v[98:99], v[102:103]
	v_pk_add_f32 v[96:97], v[96:97], v[100:101]
	v_mul_f32_e32 v101, v99, v99
	v_mul_f32_e32 v100, v97, v97
	v_fmac_f32_e32 v100, v96, v96
	v_fmac_f32_e32 v101, v98, v98
	v_add_f32_e32 v100, v100, v101
	v_add_f32_e32 v100, v104, v100
	ds_swizzle_b32 v101, v100 offset:swizzle(SWAP,16)
	v_cvt_pk_bf16_f32 v96, v96, v97
	v_cvt_pk_bf16_f32 v97, v98, v99
	v_mov_b32_e32 v246, v96
	v_mov_b32_e32 v247, v97
	v_lshl_add_u64 v[250:251], v[114:115], 0, v[248:249]
	s_nop 0
	v_permlane16_swap_b32_e32 v244, v246
	v_permlane16_swap_b32_e32 v245, v247
	global_store_dwordx4 v[250:251], v[244:247], off offset:256
	s_waitcnt lgkmcnt(0)
	v_add_f32_e32 v96, v100, v101
	v_mov_b32_e32 v97, v96
	s_nop 1
	v_permlane32_swap_b32_e32 v96, v97
	s_and_saveexec_b64 s[28:29], s[4:5]
	s_cbranch_execz .LBB0_1451
	v_add_f32_e32 v98, v96, v97
	v_lshlrev_b64 v[96:97], 6, v[112:113]
	v_lshl_add_u64 v[96:97], s[12:13], 0, v[96:97]
	v_lshl_add_u64 v[96:97], s[26:27], 2, v[96:97]
	s_lshl_b32 s2, s48, 2
	v_lshl_add_u64 v[96:97], v[96:97], 0, s[2:3]
	global_store_dword v[96:97], v98, off
.LBB0_1451:
	s_or_b64 exec, exec, s[28:29]
	v_or_b32_e32 v96, 32, v142
	v_ashrrev_i32_e32 v97, 31, v96
	v_lshlrev_b64 v[98:99], 11, v[96:97]
	v_lshl_add_u64 v[98:99], s[10:11], 0, v[98:99]
	v_lshl_add_u64 v[98:99], v[140:141], 1, v[98:99]
	s_waitcnt vmcnt(15)
	v_permlane16_swap_b32_e32 v188, v190
	v_permlane16_swap_b32_e32 v189, v191
	v_lshlrev_b32_e32 v102, 16, v188
	v_and_b32_e32 v103, 0xffff0000, v188
	v_lshlrev_b32_e32 v100, 16, v189
	v_and_b32_e32 v101, 0xffff0000, v189
	v_pk_add_f32 v[94:95], v[94:95], v[100:101]
	v_pk_add_f32 v[92:93], v[92:93], v[102:103]
	s_nop 0
	v_cvt_pk_bf16_f32 v100, v92, v93
	v_cvt_pk_bf16_f32 v101, v94, v95
	v_mul_f32_e32 v93, v93, v93
	v_mov_b32_e32 v240, v100
	v_mov_b32_e32 v241, v101
	v_mul_f32_e32 v95, v95, v95
	v_fmac_f32_e32 v93, v92, v92
	v_fmac_f32_e32 v95, v94, v94
	v_add_f32_e32 v92, v93, v95
	s_waitcnt vmcnt(15)
	v_lshlrev_b32_e32 v100, 16, v190
	v_and_b32_e32 v101, 0xffff0000, v190
	v_lshlrev_b32_e32 v102, 16, v191
	v_and_b32_e32 v103, 0xffff0000, v191
	v_pk_add_f32 v[90:91], v[90:91], v[102:103]
	v_pk_add_f32 v[88:89], v[88:89], v[100:101]
	s_nop 0
	v_cvt_pk_bf16_f32 v100, v88, v89
	v_cvt_pk_bf16_f32 v101, v90, v91
	v_mul_f32_e32 v89, v89, v89
	v_mov_b32_e32 v242, v100
	v_mov_b32_e32 v243, v101
	v_lshl_add_u64 v[250:251], v[98:99], 0, v[248:249]
	s_nop 0
	v_permlane16_swap_b32_e32 v240, v242
	v_permlane16_swap_b32_e32 v241, v243
	global_store_dwordx4 v[250:251], v[240:243], off
	v_mul_f32_e32 v91, v91, v91
	v_fmac_f32_e32 v89, v88, v88
	v_fmac_f32_e32 v91, v90, v90
	v_add_f32_e32 v88, v89, v91
	v_add_f32_e32 v88, v92, v88
	s_waitcnt vmcnt(15)
	v_permlane16_swap_b32_e32 v192, v194
	v_permlane16_swap_b32_e32 v193, v195
	v_lshlrev_b32_e32 v100, 16, v192
	v_and_b32_e32 v101, 0xffff0000, v192
	v_lshlrev_b32_e32 v102, 16, v193
	v_and_b32_e32 v103, 0xffff0000, v193
	v_pk_add_f32 v[86:87], v[86:87], v[102:103]
	v_pk_add_f32 v[84:85], v[84:85], v[100:101]
	s_nop 0
	v_cvt_pk_bf16_f32 v100, v84, v85
	v_cvt_pk_bf16_f32 v101, v86, v87
	v_mul_f32_e32 v85, v85, v85
	v_mul_f32_e32 v87, v87, v87
	v_fmac_f32_e32 v85, v84, v84
	v_fmac_f32_e32 v87, v86, v86
	v_add_f32_e32 v84, v85, v87
	v_add_f32_e32 v88, v88, v84
	v_mov_b32_e32 v244, v100
	v_mov_b32_e32 v245, v101
	s_waitcnt vmcnt(15)
	v_lshlrev_b32_e32 v84, 16, v194
	v_and_b32_e32 v85, 0xffff0000, v194
	v_lshlrev_b32_e32 v86, 16, v195
	v_and_b32_e32 v87, 0xffff0000, v195
	v_pk_add_f32 v[82:83], v[82:83], v[86:87]
	v_pk_add_f32 v[80:81], v[80:81], v[84:85]
	v_mul_f32_e32 v85, v83, v83
	v_mul_f32_e32 v84, v81, v81
	v_fmac_f32_e32 v84, v80, v80
	v_fmac_f32_e32 v85, v82, v82
	v_add_f32_e32 v84, v84, v85
	v_add_f32_e32 v84, v88, v84
	ds_swizzle_b32 v85, v84 offset:swizzle(SWAP,16)
	v_cvt_pk_bf16_f32 v80, v80, v81
	v_cvt_pk_bf16_f32 v81, v82, v83
	v_mov_b32_e32 v246, v80
	v_mov_b32_e32 v247, v81
	v_lshl_add_u64 v[250:251], v[98:99], 0, v[248:249]
	s_nop 0
	v_permlane16_swap_b32_e32 v244, v246
	v_permlane16_swap_b32_e32 v245, v247
	global_store_dwordx4 v[250:251], v[244:247], off offset:256
	s_waitcnt lgkmcnt(0)
	v_add_f32_e32 v80, v84, v85
	v_mov_b32_e32 v81, v80
	s_nop 1
	v_permlane32_swap_b32_e32 v80, v81
	s_and_saveexec_b64 s[28:29], s[4:5]
	s_cbranch_execz .LBB0_1453
	v_add_f32_e32 v82, v80, v81
	v_lshlrev_b64 v[80:81], 6, v[96:97]
	v_lshl_add_u64 v[80:81], s[12:13], 0, v[80:81]
	v_lshl_add_u64 v[80:81], s[26:27], 2, v[80:81]
	s_lshl_b32 s2, s48, 2
	v_lshl_add_u64 v[80:81], v[80:81], 0, s[2:3]
	global_store_dword v[80:81], v82, off
.LBB0_1453:
	s_or_b64 exec, exec, s[28:29]
	v_or_b32_e32 v80, 48, v142
	v_ashrrev_i32_e32 v81, 31, v80
	v_lshlrev_b64 v[82:83], 11, v[80:81]
	v_lshl_add_u64 v[82:83], s[10:11], 0, v[82:83]
	v_lshl_add_u64 v[82:83], v[140:141], 1, v[82:83]
	s_waitcnt vmcnt(15)
	v_permlane16_swap_b32_e32 v196, v198
	v_permlane16_swap_b32_e32 v197, v199
	v_lshlrev_b32_e32 v86, 16, v196
	v_and_b32_e32 v87, 0xffff0000, v196
	v_lshlrev_b32_e32 v84, 16, v197
	v_and_b32_e32 v85, 0xffff0000, v197
	v_pk_add_f32 v[78:79], v[78:79], v[84:85]
	v_pk_add_f32 v[76:77], v[76:77], v[86:87]
	s_nop 0
	v_cvt_pk_bf16_f32 v84, v76, v77
	v_cvt_pk_bf16_f32 v85, v78, v79
	v_mul_f32_e32 v77, v77, v77
	v_mov_b32_e32 v240, v84
	v_mov_b32_e32 v241, v85
	v_mul_f32_e32 v79, v79, v79
	v_fmac_f32_e32 v77, v76, v76
	v_fmac_f32_e32 v79, v78, v78
	v_add_f32_e32 v76, v77, v79
	s_waitcnt vmcnt(15)
	v_lshlrev_b32_e32 v84, 16, v198
	v_and_b32_e32 v85, 0xffff0000, v198
	v_lshlrev_b32_e32 v86, 16, v199
	v_and_b32_e32 v87, 0xffff0000, v199
	v_pk_add_f32 v[74:75], v[74:75], v[86:87]
	v_pk_add_f32 v[72:73], v[72:73], v[84:85]
	s_nop 0
	v_cvt_pk_bf16_f32 v84, v72, v73
	v_cvt_pk_bf16_f32 v85, v74, v75
	v_mul_f32_e32 v73, v73, v73
	v_mov_b32_e32 v242, v84
	v_mov_b32_e32 v243, v85
	v_lshl_add_u64 v[250:251], v[82:83], 0, v[248:249]
	s_nop 0
	v_permlane16_swap_b32_e32 v240, v242
	v_permlane16_swap_b32_e32 v241, v243
	global_store_dwordx4 v[250:251], v[240:243], off
	v_mul_f32_e32 v75, v75, v75
	v_fmac_f32_e32 v73, v72, v72
	v_fmac_f32_e32 v75, v74, v74
	v_add_f32_e32 v72, v73, v75
	v_add_f32_e32 v72, v76, v72
	s_waitcnt vmcnt(15)
	v_permlane16_swap_b32_e32 v200, v202
	v_permlane16_swap_b32_e32 v201, v203
	v_lshlrev_b32_e32 v84, 16, v200
	v_and_b32_e32 v85, 0xffff0000, v200
	v_lshlrev_b32_e32 v86, 16, v201
	v_and_b32_e32 v87, 0xffff0000, v201
	v_pk_add_f32 v[70:71], v[70:71], v[86:87]
	v_pk_add_f32 v[68:69], v[68:69], v[84:85]
	s_nop 0
	v_cvt_pk_bf16_f32 v84, v68, v69
	v_cvt_pk_bf16_f32 v85, v70, v71
	v_mul_f32_e32 v69, v69, v69
	v_mul_f32_e32 v71, v71, v71
	v_fmac_f32_e32 v69, v68, v68
	v_fmac_f32_e32 v71, v70, v70
	v_add_f32_e32 v68, v69, v71
	v_add_f32_e32 v72, v72, v68
	v_mov_b32_e32 v244, v84
	v_mov_b32_e32 v245, v85
	s_waitcnt vmcnt(15)
	v_lshlrev_b32_e32 v68, 16, v202
	v_and_b32_e32 v69, 0xffff0000, v202
	v_lshlrev_b32_e32 v70, 16, v203
	v_and_b32_e32 v71, 0xffff0000, v203
	v_pk_add_f32 v[66:67], v[66:67], v[70:71]
	v_pk_add_f32 v[64:65], v[64:65], v[68:69]
	v_mul_f32_e32 v69, v67, v67
	v_mul_f32_e32 v68, v65, v65
	v_fmac_f32_e32 v68, v64, v64
	v_fmac_f32_e32 v69, v66, v66
	v_add_f32_e32 v68, v68, v69
	v_add_f32_e32 v68, v72, v68
	ds_swizzle_b32 v69, v68 offset:swizzle(SWAP,16)
	v_cvt_pk_bf16_f32 v64, v64, v65
	v_cvt_pk_bf16_f32 v65, v66, v67
	v_mov_b32_e32 v246, v64
	v_mov_b32_e32 v247, v65
	v_lshl_add_u64 v[250:251], v[82:83], 0, v[248:249]
	s_nop 0
	v_permlane16_swap_b32_e32 v244, v246
	v_permlane16_swap_b32_e32 v245, v247
	global_store_dwordx4 v[250:251], v[244:247], off offset:256
	s_waitcnt lgkmcnt(0)
	v_add_f32_e32 v64, v68, v69
	v_mov_b32_e32 v65, v64
	s_nop 1
	v_permlane32_swap_b32_e32 v64, v65
	s_and_saveexec_b64 s[28:29], s[4:5]
	s_cbranch_execz .LBB0_1455
	v_add_f32_e32 v66, v64, v65
	v_lshlrev_b64 v[64:65], 6, v[80:81]
	v_lshl_add_u64 v[64:65], s[12:13], 0, v[64:65]
	v_lshl_add_u64 v[64:65], s[26:27], 2, v[64:65]
	s_lshl_b32 s2, s48, 2
	v_lshl_add_u64 v[64:65], v[64:65], 0, s[2:3]
	global_store_dword v[64:65], v66, off
.LBB0_1455:
	s_or_b64 exec, exec, s[28:29]
	v_add_u32_e32 v64, 0x80, v142
	v_ashrrev_i32_e32 v65, 31, v64
	v_lshlrev_b64 v[66:67], 11, v[64:65]
	v_lshl_add_u64 v[66:67], s[10:11], 0, v[66:67]
	v_lshl_add_u64 v[66:67], v[140:141], 1, v[66:67]
	s_waitcnt vmcnt(15)
	v_permlane16_swap_b32_e32 v208, v210
	v_permlane16_swap_b32_e32 v209, v211
	v_lshlrev_b32_e32 v70, 16, v208
	v_and_b32_e32 v71, 0xffff0000, v208
	v_lshlrev_b32_e32 v68, 16, v209
	v_and_b32_e32 v69, 0xffff0000, v209
	v_pk_add_f32 v[62:63], v[62:63], v[68:69]
	v_pk_add_f32 v[60:61], v[60:61], v[70:71]
	s_nop 0
	v_cvt_pk_bf16_f32 v68, v60, v61
	v_cvt_pk_bf16_f32 v69, v62, v63
	v_mul_f32_e32 v61, v61, v61
	v_mov_b32_e32 v240, v68
	v_mov_b32_e32 v241, v69
	v_mul_f32_e32 v63, v63, v63
	v_fmac_f32_e32 v61, v60, v60
	v_fmac_f32_e32 v63, v62, v62
	v_add_f32_e32 v60, v61, v63
	s_waitcnt vmcnt(15)
	v_lshlrev_b32_e32 v68, 16, v210
	v_and_b32_e32 v69, 0xffff0000, v210
	v_lshlrev_b32_e32 v70, 16, v211
	v_and_b32_e32 v71, 0xffff0000, v211
	v_pk_add_f32 v[58:59], v[58:59], v[70:71]
	v_pk_add_f32 v[56:57], v[56:57], v[68:69]
	s_nop 0
	v_cvt_pk_bf16_f32 v68, v56, v57
	v_cvt_pk_bf16_f32 v69, v58, v59
	v_mul_f32_e32 v57, v57, v57
	v_mov_b32_e32 v242, v68
	v_mov_b32_e32 v243, v69
	v_lshl_add_u64 v[250:251], v[66:67], 0, v[248:249]
	s_nop 0
	v_permlane16_swap_b32_e32 v240, v242
	v_permlane16_swap_b32_e32 v241, v243
	global_store_dwordx4 v[250:251], v[240:243], off
	v_mul_f32_e32 v59, v59, v59
	v_fmac_f32_e32 v57, v56, v56
	v_fmac_f32_e32 v59, v58, v58
	v_add_f32_e32 v56, v57, v59
	v_add_f32_e32 v56, v60, v56
	s_waitcnt vmcnt(15)
	v_permlane16_swap_b32_e32 v212, v214
	v_permlane16_swap_b32_e32 v213, v215
	v_lshlrev_b32_e32 v68, 16, v212
	v_and_b32_e32 v69, 0xffff0000, v212
	v_lshlrev_b32_e32 v70, 16, v213
	v_and_b32_e32 v71, 0xffff0000, v213
	v_pk_add_f32 v[54:55], v[54:55], v[70:71]
	v_pk_add_f32 v[52:53], v[52:53], v[68:69]
	s_nop 0
	v_cvt_pk_bf16_f32 v68, v52, v53
	v_cvt_pk_bf16_f32 v69, v54, v55
	v_mul_f32_e32 v53, v53, v53
	v_mul_f32_e32 v55, v55, v55
	v_fmac_f32_e32 v53, v52, v52
	v_fmac_f32_e32 v55, v54, v54
	v_add_f32_e32 v52, v53, v55
	v_add_f32_e32 v56, v56, v52
	v_mov_b32_e32 v244, v68
	v_mov_b32_e32 v245, v69
	s_waitcnt vmcnt(15)
	v_lshlrev_b32_e32 v52, 16, v214
	v_and_b32_e32 v53, 0xffff0000, v214
	v_lshlrev_b32_e32 v54, 16, v215
	v_and_b32_e32 v55, 0xffff0000, v215
	v_pk_add_f32 v[50:51], v[50:51], v[54:55]
	v_pk_add_f32 v[48:49], v[48:49], v[52:53]
	v_mul_f32_e32 v53, v51, v51
	v_mul_f32_e32 v52, v49, v49
	v_fmac_f32_e32 v52, v48, v48
	v_fmac_f32_e32 v53, v50, v50
	v_add_f32_e32 v52, v52, v53
	v_add_f32_e32 v52, v56, v52
	ds_swizzle_b32 v53, v52 offset:swizzle(SWAP,16)
	v_cvt_pk_bf16_f32 v48, v48, v49
	v_cvt_pk_bf16_f32 v49, v50, v51
	v_mov_b32_e32 v246, v48
	v_mov_b32_e32 v247, v49
	v_lshl_add_u64 v[250:251], v[66:67], 0, v[248:249]
	s_nop 0
	v_permlane16_swap_b32_e32 v244, v246
	v_permlane16_swap_b32_e32 v245, v247
	global_store_dwordx4 v[250:251], v[244:247], off offset:256
	s_waitcnt lgkmcnt(0)
	v_add_f32_e32 v48, v52, v53
	v_mov_b32_e32 v49, v48
	s_nop 1
	v_permlane32_swap_b32_e32 v48, v49
	s_and_saveexec_b64 s[28:29], s[4:5]
	s_cbranch_execz .LBB0_1457
	v_add_f32_e32 v50, v48, v49
	v_lshlrev_b64 v[48:49], 6, v[64:65]
	v_lshl_add_u64 v[48:49], s[12:13], 0, v[48:49]
	v_lshl_add_u64 v[48:49], s[26:27], 2, v[48:49]
	s_lshl_b32 s2, s48, 2
	v_lshl_add_u64 v[48:49], v[48:49], 0, s[2:3]
	global_store_dword v[48:49], v50, off
.LBB0_1457:
	s_or_b64 exec, exec, s[28:29]
	v_add_u32_e32 v48, 0x90, v142
	v_ashrrev_i32_e32 v49, 31, v48
	v_lshlrev_b64 v[50:51], 11, v[48:49]
	v_lshl_add_u64 v[50:51], s[10:11], 0, v[50:51]
	v_lshl_add_u64 v[50:51], v[140:141], 1, v[50:51]
	s_waitcnt vmcnt(15)
	v_permlane16_swap_b32_e32 v216, v218
	v_permlane16_swap_b32_e32 v217, v219
	v_lshlrev_b32_e32 v54, 16, v216
	v_and_b32_e32 v55, 0xffff0000, v216
	v_lshlrev_b32_e32 v52, 16, v217
	v_and_b32_e32 v53, 0xffff0000, v217
	v_pk_add_f32 v[46:47], v[46:47], v[52:53]
	v_pk_add_f32 v[44:45], v[44:45], v[54:55]
	s_nop 0
	v_cvt_pk_bf16_f32 v52, v44, v45
	v_cvt_pk_bf16_f32 v53, v46, v47
	v_mul_f32_e32 v45, v45, v45
	v_mov_b32_e32 v240, v52
	v_mov_b32_e32 v241, v53
	v_mul_f32_e32 v47, v47, v47
	v_fmac_f32_e32 v45, v44, v44
	v_fmac_f32_e32 v47, v46, v46
	v_add_f32_e32 v44, v45, v47
	s_waitcnt vmcnt(15)
	v_lshlrev_b32_e32 v52, 16, v218
	v_and_b32_e32 v53, 0xffff0000, v218
	v_lshlrev_b32_e32 v54, 16, v219
	v_and_b32_e32 v55, 0xffff0000, v219
	v_pk_add_f32 v[42:43], v[42:43], v[54:55]
	v_pk_add_f32 v[40:41], v[40:41], v[52:53]
	s_nop 0
	v_cvt_pk_bf16_f32 v52, v40, v41
	v_cvt_pk_bf16_f32 v53, v42, v43
	v_mul_f32_e32 v41, v41, v41
	v_mov_b32_e32 v242, v52
	v_mov_b32_e32 v243, v53
	v_lshl_add_u64 v[250:251], v[50:51], 0, v[248:249]
	s_nop 0
	v_permlane16_swap_b32_e32 v240, v242
	v_permlane16_swap_b32_e32 v241, v243
	global_store_dwordx4 v[250:251], v[240:243], off
	v_mul_f32_e32 v43, v43, v43
	v_fmac_f32_e32 v41, v40, v40
	v_fmac_f32_e32 v43, v42, v42
	v_add_f32_e32 v40, v41, v43
	v_add_f32_e32 v40, v44, v40
	s_waitcnt vmcnt(15)
	v_permlane16_swap_b32_e32 v220, v222
	v_permlane16_swap_b32_e32 v221, v223
	v_lshlrev_b32_e32 v52, 16, v220
	v_and_b32_e32 v53, 0xffff0000, v220
	v_lshlrev_b32_e32 v54, 16, v221
	v_and_b32_e32 v55, 0xffff0000, v221
	v_pk_add_f32 v[38:39], v[38:39], v[54:55]
	v_pk_add_f32 v[36:37], v[36:37], v[52:53]
	s_nop 0
	v_cvt_pk_bf16_f32 v52, v36, v37
	v_cvt_pk_bf16_f32 v53, v38, v39
	v_mul_f32_e32 v37, v37, v37
	v_mul_f32_e32 v39, v39, v39
	v_fmac_f32_e32 v37, v36, v36
	v_fmac_f32_e32 v39, v38, v38
	v_add_f32_e32 v36, v37, v39
	v_add_f32_e32 v40, v40, v36
	v_mov_b32_e32 v244, v52
	v_mov_b32_e32 v245, v53
	s_waitcnt vmcnt(15)
	v_lshlrev_b32_e32 v36, 16, v222
	v_and_b32_e32 v37, 0xffff0000, v222
	v_lshlrev_b32_e32 v38, 16, v223
	v_and_b32_e32 v39, 0xffff0000, v223
	v_pk_add_f32 v[34:35], v[34:35], v[38:39]
	v_pk_add_f32 v[32:33], v[32:33], v[36:37]
	v_mul_f32_e32 v37, v35, v35
	v_mul_f32_e32 v36, v33, v33
	v_fmac_f32_e32 v36, v32, v32
	v_fmac_f32_e32 v37, v34, v34
	v_add_f32_e32 v36, v36, v37
	v_add_f32_e32 v36, v40, v36
	ds_swizzle_b32 v37, v36 offset:swizzle(SWAP,16)
	v_cvt_pk_bf16_f32 v32, v32, v33
	v_cvt_pk_bf16_f32 v33, v34, v35
	v_mov_b32_e32 v246, v32
	v_mov_b32_e32 v247, v33
	v_lshl_add_u64 v[250:251], v[50:51], 0, v[248:249]
	s_nop 0
	v_permlane16_swap_b32_e32 v244, v246
	v_permlane16_swap_b32_e32 v245, v247
	global_store_dwordx4 v[250:251], v[244:247], off offset:256
	s_waitcnt lgkmcnt(0)
	v_add_f32_e32 v32, v36, v37
	v_mov_b32_e32 v33, v32
	s_nop 1
	v_permlane32_swap_b32_e32 v32, v33
	s_and_saveexec_b64 s[28:29], s[4:5]
	s_cbranch_execz .LBB0_1459
	v_add_f32_e32 v34, v32, v33
	v_lshlrev_b64 v[32:33], 6, v[48:49]
	v_lshl_add_u64 v[32:33], s[12:13], 0, v[32:33]
	v_lshl_add_u64 v[32:33], s[26:27], 2, v[32:33]
	s_lshl_b32 s2, s48, 2
	v_lshl_add_u64 v[32:33], v[32:33], 0, s[2:3]
	global_store_dword v[32:33], v34, off
.LBB0_1459:
	s_or_b64 exec, exec, s[28:29]
	v_add_u32_e32 v32, 0xa0, v142
	v_ashrrev_i32_e32 v33, 31, v32
	v_lshlrev_b64 v[34:35], 11, v[32:33]
	v_lshl_add_u64 v[34:35], s[10:11], 0, v[34:35]
	v_lshl_add_u64 v[34:35], v[140:141], 1, v[34:35]
	s_waitcnt vmcnt(15)
	v_permlane16_swap_b32_e32 v224, v226
	v_permlane16_swap_b32_e32 v225, v227
	v_lshlrev_b32_e32 v38, 16, v224
	v_and_b32_e32 v39, 0xffff0000, v224
	v_lshlrev_b32_e32 v36, 16, v225
	v_and_b32_e32 v37, 0xffff0000, v225
	v_pk_add_f32 v[30:31], v[30:31], v[36:37]
	v_pk_add_f32 v[28:29], v[28:29], v[38:39]
	s_nop 0
	v_cvt_pk_bf16_f32 v36, v28, v29
	v_cvt_pk_bf16_f32 v37, v30, v31
	v_mul_f32_e32 v29, v29, v29
	v_mov_b32_e32 v240, v36
	v_mov_b32_e32 v241, v37
	v_mul_f32_e32 v31, v31, v31
	v_fmac_f32_e32 v29, v28, v28
	v_fmac_f32_e32 v31, v30, v30
	v_add_f32_e32 v28, v29, v31
	s_waitcnt vmcnt(15)
	v_lshlrev_b32_e32 v36, 16, v226
	v_and_b32_e32 v37, 0xffff0000, v226
	v_lshlrev_b32_e32 v38, 16, v227
	v_and_b32_e32 v39, 0xffff0000, v227
	v_pk_add_f32 v[26:27], v[26:27], v[38:39]
	v_pk_add_f32 v[24:25], v[24:25], v[36:37]
	s_nop 0
	v_cvt_pk_bf16_f32 v36, v24, v25
	v_cvt_pk_bf16_f32 v37, v26, v27
	v_mul_f32_e32 v25, v25, v25
	v_mov_b32_e32 v242, v36
	v_mov_b32_e32 v243, v37
	v_lshl_add_u64 v[250:251], v[34:35], 0, v[248:249]
	s_nop 0
	v_permlane16_swap_b32_e32 v240, v242
	v_permlane16_swap_b32_e32 v241, v243
	global_store_dwordx4 v[250:251], v[240:243], off
	v_mul_f32_e32 v27, v27, v27
	v_fmac_f32_e32 v25, v24, v24
	v_fmac_f32_e32 v27, v26, v26
	v_add_f32_e32 v24, v25, v27
	v_add_f32_e32 v24, v28, v24
	s_waitcnt vmcnt(15)
	v_permlane16_swap_b32_e32 v228, v230
	v_permlane16_swap_b32_e32 v229, v231
	v_lshlrev_b32_e32 v36, 16, v228
	v_and_b32_e32 v37, 0xffff0000, v228
	v_lshlrev_b32_e32 v38, 16, v229
	v_and_b32_e32 v39, 0xffff0000, v229
	v_pk_add_f32 v[22:23], v[22:23], v[38:39]
	v_pk_add_f32 v[20:21], v[20:21], v[36:37]
	s_nop 0
	v_cvt_pk_bf16_f32 v36, v20, v21
	v_cvt_pk_bf16_f32 v37, v22, v23
	v_mul_f32_e32 v21, v21, v21
	v_mul_f32_e32 v23, v23, v23
	v_fmac_f32_e32 v21, v20, v20
	v_fmac_f32_e32 v23, v22, v22
	v_add_f32_e32 v20, v21, v23
	v_add_f32_e32 v24, v24, v20
	v_mov_b32_e32 v244, v36
	v_mov_b32_e32 v245, v37
	s_waitcnt vmcnt(15)
	v_lshlrev_b32_e32 v20, 16, v230
	v_and_b32_e32 v21, 0xffff0000, v230
	v_lshlrev_b32_e32 v22, 16, v231
	v_and_b32_e32 v23, 0xffff0000, v231
	v_pk_add_f32 v[18:19], v[18:19], v[22:23]
	v_pk_add_f32 v[16:17], v[16:17], v[20:21]
	v_mul_f32_e32 v21, v19, v19
	v_mul_f32_e32 v20, v17, v17
	v_fmac_f32_e32 v20, v16, v16
	v_fmac_f32_e32 v21, v18, v18
	v_add_f32_e32 v20, v20, v21
	v_add_f32_e32 v20, v24, v20
	ds_swizzle_b32 v21, v20 offset:swizzle(SWAP,16)
	v_cvt_pk_bf16_f32 v16, v16, v17
	v_cvt_pk_bf16_f32 v17, v18, v19
	v_mov_b32_e32 v246, v16
	v_mov_b32_e32 v247, v17
	v_lshl_add_u64 v[250:251], v[34:35], 0, v[248:249]
	s_nop 0
	v_permlane16_swap_b32_e32 v244, v246
	v_permlane16_swap_b32_e32 v245, v247
	global_store_dwordx4 v[250:251], v[244:247], off offset:256
	s_waitcnt lgkmcnt(0)
	v_add_f32_e32 v16, v20, v21
	v_mov_b32_e32 v17, v16
	s_nop 1
	v_permlane32_swap_b32_e32 v16, v17
	s_and_saveexec_b64 s[28:29], s[4:5]
	s_cbranch_execz .LBB0_1461
	v_add_f32_e32 v18, v16, v17
	v_lshlrev_b64 v[16:17], 6, v[32:33]
	v_lshl_add_u64 v[16:17], s[12:13], 0, v[16:17]
	v_lshl_add_u64 v[16:17], s[26:27], 2, v[16:17]
	s_lshl_b32 s2, s48, 2
	v_lshl_add_u64 v[16:17], v[16:17], 0, s[2:3]
	global_store_dword v[16:17], v18, off
.LBB0_1461:
	s_or_b64 exec, exec, s[28:29]
	v_add_u32_e32 v16, 0xb0, v142
	v_ashrrev_i32_e32 v17, 31, v16
	v_lshlrev_b64 v[18:19], 11, v[16:17]
	v_lshl_add_u64 v[18:19], s[10:11], 0, v[18:19]
	v_lshl_add_u64 v[18:19], v[140:141], 1, v[18:19]
	s_waitcnt vmcnt(15)
	v_permlane16_swap_b32_e32 v232, v234
	v_permlane16_swap_b32_e32 v233, v235
	v_lshlrev_b32_e32 v22, 16, v232
	v_and_b32_e32 v23, 0xffff0000, v232
	v_lshlrev_b32_e32 v20, 16, v233
	v_and_b32_e32 v21, 0xffff0000, v233
	v_pk_add_f32 v[14:15], v[14:15], v[20:21]
	v_pk_add_f32 v[12:13], v[12:13], v[22:23]
	s_nop 0
	v_cvt_pk_bf16_f32 v20, v12, v13
	v_cvt_pk_bf16_f32 v21, v14, v15
	v_mul_f32_e32 v13, v13, v13
	v_mov_b32_e32 v240, v20
	v_mov_b32_e32 v241, v21
	v_mul_f32_e32 v15, v15, v15
	v_fmac_f32_e32 v13, v12, v12
	v_fmac_f32_e32 v15, v14, v14
	v_add_f32_e32 v12, v13, v15
	s_waitcnt vmcnt(15)
	v_lshlrev_b32_e32 v20, 16, v234
	v_and_b32_e32 v21, 0xffff0000, v234
	v_lshlrev_b32_e32 v22, 16, v235
	v_and_b32_e32 v23, 0xffff0000, v235
	v_pk_add_f32 v[10:11], v[10:11], v[22:23]
	v_pk_add_f32 v[8:9], v[8:9], v[20:21]
	s_nop 0
	v_cvt_pk_bf16_f32 v20, v8, v9
	v_cvt_pk_bf16_f32 v21, v10, v11
	v_mul_f32_e32 v9, v9, v9
	v_mov_b32_e32 v242, v20
	v_mov_b32_e32 v243, v21
	v_lshl_add_u64 v[250:251], v[18:19], 0, v[248:249]
	s_nop 0
	v_permlane16_swap_b32_e32 v240, v242
	v_permlane16_swap_b32_e32 v241, v243
	global_store_dwordx4 v[250:251], v[240:243], off
	v_mul_f32_e32 v11, v11, v11
	v_fmac_f32_e32 v9, v8, v8
	v_fmac_f32_e32 v11, v10, v10
	v_add_f32_e32 v8, v9, v11
	v_add_f32_e32 v8, v12, v8
	s_waitcnt vmcnt(15)
	v_permlane16_swap_b32_e32 v236, v238
	v_permlane16_swap_b32_e32 v237, v239
	v_lshlrev_b32_e32 v20, 16, v236
	v_and_b32_e32 v21, 0xffff0000, v236
	v_lshlrev_b32_e32 v22, 16, v237
	v_and_b32_e32 v23, 0xffff0000, v237
	v_pk_add_f32 v[6:7], v[6:7], v[22:23]
	v_pk_add_f32 v[4:5], v[4:5], v[20:21]
	s_nop 0
	v_cvt_pk_bf16_f32 v20, v4, v5
	v_cvt_pk_bf16_f32 v21, v6, v7
	v_mul_f32_e32 v5, v5, v5
	v_mul_f32_e32 v7, v7, v7
	v_fmac_f32_e32 v5, v4, v4
	v_fmac_f32_e32 v7, v6, v6
	v_add_f32_e32 v4, v5, v7
	v_add_f32_e32 v8, v8, v4
	v_mov_b32_e32 v244, v20
	v_mov_b32_e32 v245, v21
	s_waitcnt vmcnt(15)
	v_lshlrev_b32_e32 v4, 16, v238
	v_and_b32_e32 v5, 0xffff0000, v238
	v_lshlrev_b32_e32 v6, 16, v239
	v_and_b32_e32 v7, 0xffff0000, v239
	v_pk_add_f32 v[2:3], v[2:3], v[6:7]
	v_pk_add_f32 v[0:1], v[0:1], v[4:5]
	v_mul_f32_e32 v5, v3, v3
	v_mul_f32_e32 v4, v1, v1
	v_fmac_f32_e32 v4, v0, v0
	v_fmac_f32_e32 v5, v2, v2
	v_add_f32_e32 v4, v4, v5
	v_add_f32_e32 v4, v8, v4
	ds_swizzle_b32 v5, v4 offset:swizzle(SWAP,16)
	v_cvt_pk_bf16_f32 v0, v0, v1
	v_cvt_pk_bf16_f32 v1, v2, v3
	v_mov_b32_e32 v246, v0
	v_mov_b32_e32 v247, v1
	v_lshl_add_u64 v[250:251], v[18:19], 0, v[248:249]
	s_nop 0
	v_permlane16_swap_b32_e32 v244, v246
	v_permlane16_swap_b32_e32 v245, v247
	global_store_dwordx4 v[250:251], v[244:247], off offset:256
	s_waitcnt lgkmcnt(0)
	v_add_f32_e32 v0, v4, v5
	v_mov_b32_e32 v1, v0
	s_nop 1
	v_permlane32_swap_b32_e32 v0, v1
	s_and_saveexec_b64 s[28:29], s[4:5]
	s_cbranch_execz .LBB0_1463
	v_add_f32_e32 v2, v0, v1
	v_lshlrev_b64 v[0:1], 6, v[16:17]
	v_lshl_add_u64 v[0:1], s[12:13], 0, v[0:1]
	v_lshl_add_u64 v[0:1], s[26:27], 2, v[0:1]
	s_lshl_b32 s2, s48, 2
	v_lshl_add_u64 v[0:1], v[0:1], 0, s[2:3]
	global_store_dword v[0:1], v2, off

.LBB0_2089:
	v_lshl_add_u32 v142, s26, 8, v144
	v_ashrrev_i32_e32 v143, 31, v142
	v_lshl_or_b32 v140, s8, 8, v146
	v_lshlrev_b64 v[150:151], 11, v[142:143]
	v_ashrrev_i32_e32 v141, 31, v140
	v_lshl_add_u64 v[150:151], s[2:3], 0, v[150:151]
	v_lshl_add_u64 v[150:151], v[140:141], 1, v[150:151]
	s_mov_b64 s[98:99], 0x8000
	s_mov_b64 s[100:101], 0x28000
	v_bfe_u32 v232, v206, 4, 1
	v_mul_u32_u24_e32 v232, 24, v232
	v_mov_b32_e32 v233, 0
	v_lshl_add_u64 v[234:235], v[150:151], 0, v[232:233]
	global_load_dwordx4 v[156:159], v[234:235], off
	global_load_dwordx4 v[160:163], v[234:235], off offset:256
	v_lshl_add_u64 v[234:235], v[234:235], 0, s[98:99]
	global_load_dwordx4 v[164:167], v[234:235], off
	global_load_dwordx4 v[168:171], v[234:235], off offset:256
	v_lshl_add_u64 v[234:235], v[234:235], 0, s[98:99]
	global_load_dwordx4 v[172:175], v[234:235], off
	global_load_dwordx4 v[176:179], v[234:235], off offset:256
	v_lshl_add_u64 v[234:235], v[234:235], 0, s[98:99]
	global_load_dwordx4 v[180:183], v[234:235], off
	global_load_dwordx4 v[184:187], v[234:235], off offset:256
	v_lshl_add_u64 v[234:235], v[234:235], 0, s[100:101]
	global_load_dwordx4 v[188:191], v[234:235], off
	global_load_dwordx4 v[192:195], v[234:235], off offset:256
	v_lshl_add_u64 v[234:235], v[234:235], 0, s[98:99]
	global_load_dwordx4 v[196:199], v[234:235], off
	global_load_dwordx4 v[200:203], v[234:235], off offset:256
	v_lshl_add_u64 v[234:235], v[234:235], 0, s[98:99]
	global_load_dwordx4 v[208:211], v[234:235], off
	global_load_dwordx4 v[212:215], v[234:235], off offset:256
	v_lshl_add_u64 v[234:235], v[234:235], 0, s[98:99]
	global_load_dwordx4 v[216:219], v[234:235], off
	global_load_dwordx4 v[220:223], v[234:235], off offset:256
	s_lshl_b32 s26, s8, 2
	s_ashr_i32 s27, s26, 31
	s_waitcnt vmcnt(15)
	v_permlane16_swap_b32_e32 v156, v158
	v_permlane16_swap_b32_e32 v157, v159
	v_lshlrev_b32_e32 v154, 16, v156
	v_and_b32_e32 v155, 0xffff0000, v156
	v_lshlrev_b32_e32 v152, 16, v157
	v_and_b32_e32 v153, 0xffff0000, v157
	v_pk_add_f32 v[126:127], v[126:127], v[152:153]
	v_pk_add_f32 v[124:125], v[124:125], v[154:155]
	s_nop 0
	v_cvt_pk_bf16_f32 v152, v124, v125
	v_cvt_pk_bf16_f32 v153, v126, v127
	v_mul_f32_e32 v125, v125, v125
	v_mov_b32_e32 v224, v152
	v_mov_b32_e32 v225, v153
	v_mul_f32_e32 v127, v127, v127
	v_fmac_f32_e32 v125, v124, v124
	v_fmac_f32_e32 v127, v126, v126
	v_add_f32_e32 v124, v125, v127
	s_waitcnt vmcnt(15)
	v_lshlrev_b32_e32 v152, 16, v158
	v_and_b32_e32 v153, 0xffff0000, v158
	v_lshlrev_b32_e32 v154, 16, v159
	v_and_b32_e32 v155, 0xffff0000, v159
	v_pk_add_f32 v[122:123], v[122:123], v[154:155]
	v_pk_add_f32 v[120:121], v[120:121], v[152:153]
	s_nop 0
	v_cvt_pk_bf16_f32 v152, v120, v121
	v_cvt_pk_bf16_f32 v153, v122, v123
	v_mul_f32_e32 v121, v121, v121
	v_mov_b32_e32 v226, v152
	v_mov_b32_e32 v227, v153
	v_lshl_add_u64 v[234:235], v[150:151], 0, v[232:233]
	s_nop 0
	v_permlane16_swap_b32_e32 v224, v226
	v_permlane16_swap_b32_e32 v225, v227
	global_store_dwordx4 v[234:235], v[224:227], off
	v_mul_f32_e32 v123, v123, v123
	v_fmac_f32_e32 v121, v120, v120
	v_fmac_f32_e32 v123, v122, v122
	v_add_f32_e32 v120, v121, v123
	v_add_f32_e32 v120, v124, v120
	s_waitcnt vmcnt(15)
	v_permlane16_swap_b32_e32 v160, v162
	v_permlane16_swap_b32_e32 v161, v163
	v_lshlrev_b32_e32 v152, 16, v160
	v_and_b32_e32 v153, 0xffff0000, v160
	v_lshlrev_b32_e32 v154, 16, v161
	v_and_b32_e32 v155, 0xffff0000, v161
	v_pk_add_f32 v[118:119], v[118:119], v[154:155]
	v_pk_add_f32 v[116:117], v[116:117], v[152:153]
	s_nop 0
	v_cvt_pk_bf16_f32 v152, v116, v117
	v_cvt_pk_bf16_f32 v153, v118, v119
	v_mul_f32_e32 v117, v117, v117
	v_mul_f32_e32 v119, v119, v119
	v_fmac_f32_e32 v117, v116, v116
	v_fmac_f32_e32 v119, v118, v118
	v_add_f32_e32 v116, v117, v119
	v_add_f32_e32 v120, v120, v116
	v_mov_b32_e32 v228, v152
	v_mov_b32_e32 v229, v153
	s_waitcnt vmcnt(15)
	v_lshlrev_b32_e32 v116, 16, v162
	v_and_b32_e32 v117, 0xffff0000, v162
	v_lshlrev_b32_e32 v118, 16, v163
	v_and_b32_e32 v119, 0xffff0000, v163
	v_pk_add_f32 v[114:115], v[114:115], v[118:119]
	v_pk_add_f32 v[112:113], v[112:113], v[116:117]
	v_mul_f32_e32 v117, v115, v115
	v_mul_f32_e32 v116, v113, v113
	v_fmac_f32_e32 v116, v112, v112
	v_fmac_f32_e32 v117, v114, v114
	v_add_f32_e32 v116, v116, v117
	v_add_f32_e32 v116, v120, v116
	ds_swizzle_b32 v117, v116 offset:swizzle(SWAP,16)
	v_cvt_pk_bf16_f32 v112, v112, v113
	v_cvt_pk_bf16_f32 v113, v114, v115
	v_mov_b32_e32 v230, v112
	v_mov_b32_e32 v231, v113
	v_lshl_add_u64 v[234:235], v[150:151], 0, v[232:233]
	s_nop 0
	v_permlane16_swap_b32_e32 v228, v230
	v_permlane16_swap_b32_e32 v229, v231
	global_store_dwordx4 v[234:235], v[228:231], off offset:256
	s_waitcnt lgkmcnt(0)
	v_add_f32_e32 v112, v116, v117
	v_mov_b32_e32 v113, v112
	s_nop 1
	v_permlane32_swap_b32_e32 v112, v113
	s_and_saveexec_b64 s[28:29], s[4:5]
	s_cbranch_execz .LBB0_2091
	v_add_f32_e32 v114, v112, v113
	v_lshlrev_b64 v[112:113], 6, v[142:143]
	v_lshl_add_u64 v[112:113], s[12:13], 0, v[112:113]
	v_lshl_add_u64 v[112:113], s[26:27], 2, v[112:113]
	s_lshl_b32 s8, s48, 2
	v_lshl_add_u64 v[112:113], v[112:113], 0, s[8:9]
	global_store_dword v[112:113], v114, off
.LBB0_2091:
	s_or_b64 exec, exec, s[28:29]
	v_or_b32_e32 v112, 16, v142
	v_ashrrev_i32_e32 v113, 31, v112
	v_lshlrev_b64 v[114:115], 11, v[112:113]
	v_lshl_add_u64 v[114:115], s[2:3], 0, v[114:115]
	v_lshl_add_u64 v[114:115], v[140:141], 1, v[114:115]
	s_waitcnt vmcnt(15)
	v_permlane16_swap_b32_e32 v164, v166
	v_permlane16_swap_b32_e32 v165, v167
	v_lshlrev_b32_e32 v118, 16, v164
	v_and_b32_e32 v119, 0xffff0000, v164
	v_lshlrev_b32_e32 v116, 16, v165
	v_and_b32_e32 v117, 0xffff0000, v165
	v_pk_add_f32 v[110:111], v[110:111], v[116:117]
	v_pk_add_f32 v[108:109], v[108:109], v[118:119]
	s_nop 0
	v_cvt_pk_bf16_f32 v116, v108, v109
	v_cvt_pk_bf16_f32 v117, v110, v111
	v_mul_f32_e32 v109, v109, v109
	v_mov_b32_e32 v224, v116
	v_mov_b32_e32 v225, v117
	v_mul_f32_e32 v111, v111, v111
	v_fmac_f32_e32 v109, v108, v108
	v_fmac_f32_e32 v111, v110, v110
	v_add_f32_e32 v108, v109, v111
	s_waitcnt vmcnt(15)
	v_lshlrev_b32_e32 v116, 16, v166
	v_and_b32_e32 v117, 0xffff0000, v166
	v_lshlrev_b32_e32 v118, 16, v167
	v_and_b32_e32 v119, 0xffff0000, v167
	v_pk_add_f32 v[106:107], v[106:107], v[118:119]
	v_pk_add_f32 v[104:105], v[104:105], v[116:117]
	s_nop 0
	v_cvt_pk_bf16_f32 v116, v104, v105
	v_cvt_pk_bf16_f32 v117, v106, v107
	v_mul_f32_e32 v105, v105, v105
	v_mov_b32_e32 v226, v116
	v_mov_b32_e32 v227, v117
	v_lshl_add_u64 v[234:235], v[114:115], 0, v[232:233]
	s_nop 0
	v_permlane16_swap_b32_e32 v224, v226
	v_permlane16_swap_b32_e32 v225, v227
	global_store_dwordx4 v[234:235], v[224:227], off
	v_mul_f32_e32 v107, v107, v107
	v_fmac_f32_e32 v105, v104, v104
	v_fmac_f32_e32 v107, v106, v106
	v_add_f32_e32 v104, v105, v107
	v_add_f32_e32 v104, v108, v104
	s_waitcnt vmcnt(15)
	v_permlane16_swap_b32_e32 v168, v170
	v_permlane16_swap_b32_e32 v169, v171
	v_lshlrev_b32_e32 v116, 16, v168
	v_and_b32_e32 v117, 0xffff0000, v168
	v_lshlrev_b32_e32 v118, 16, v169
	v_and_b32_e32 v119, 0xffff0000, v169
	v_pk_add_f32 v[102:103], v[102:103], v[118:119]
	v_pk_add_f32 v[100:101], v[100:101], v[116:117]
	s_nop 0
	v_cvt_pk_bf16_f32 v116, v100, v101
	v_cvt_pk_bf16_f32 v117, v102, v103
	v_mul_f32_e32 v101, v101, v101
	v_mul_f32_e32 v103, v103, v103
	v_fmac_f32_e32 v101, v100, v100
	v_fmac_f32_e32 v103, v102, v102
	v_add_f32_e32 v100, v101, v103
	v_add_f32_e32 v104, v104, v100
	v_mov_b32_e32 v228, v116
	v_mov_b32_e32 v229, v117
	s_waitcnt vmcnt(15)
	v_lshlrev_b32_e32 v100, 16, v170
	v_and_b32_e32 v101, 0xffff0000, v170
	v_lshlrev_b32_e32 v102, 16, v171
	v_and_b32_e32 v103, 0xffff0000, v171
	v_pk_add_f32 v[98:99], v[98:99], v[102:103]
	v_pk_add_f32 v[96:97], v[96:97], v[100:101]
	v_mul_f32_e32 v101, v99, v99
	v_mul_f32_e32 v100, v97, v97
	v_fmac_f32_e32 v100, v96, v96
	v_fmac_f32_e32 v101, v98, v98
	v_add_f32_e32 v100, v100, v101
	v_add_f32_e32 v100, v104, v100
	ds_swizzle_b32 v101, v100 offset:swizzle(SWAP,16)
	v_cvt_pk_bf16_f32 v96, v96, v97
	v_cvt_pk_bf16_f32 v97, v98, v99
	v_mov_b32_e32 v230, v96
	v_mov_b32_e32 v231, v97
	v_lshl_add_u64 v[234:235], v[114:115], 0, v[232:233]
	s_nop 0
	v_permlane16_swap_b32_e32 v228, v230
	v_permlane16_swap_b32_e32 v229, v231
	global_store_dwordx4 v[234:235], v[228:231], off offset:256
	s_waitcnt lgkmcnt(0)
	v_add_f32_e32 v96, v100, v101
	v_mov_b32_e32 v97, v96
	s_nop 1
	v_permlane32_swap_b32_e32 v96, v97
	s_and_saveexec_b64 s[28:29], s[4:5]
	s_cbranch_execz .LBB0_2093
	v_add_f32_e32 v98, v96, v97
	v_lshlrev_b64 v[96:97], 6, v[112:113]
	v_lshl_add_u64 v[96:97], s[12:13], 0, v[96:97]
	v_lshl_add_u64 v[96:97], s[26:27], 2, v[96:97]
	s_lshl_b32 s8, s48, 2
	v_lshl_add_u64 v[96:97], v[96:97], 0, s[8:9]
	global_store_dword v[96:97], v98, off
.LBB0_2093:
	s_or_b64 exec, exec, s[28:29]
	v_or_b32_e32 v96, 32, v142
	v_ashrrev_i32_e32 v97, 31, v96
	v_lshlrev_b64 v[98:99], 11, v[96:97]
	v_lshl_add_u64 v[98:99], s[2:3], 0, v[98:99]
	v_lshl_add_u64 v[98:99], v[140:141], 1, v[98:99]
	s_waitcnt vmcnt(15)
	v_permlane16_swap_b32_e32 v172, v174
	v_permlane16_swap_b32_e32 v173, v175
	v_lshlrev_b32_e32 v102, 16, v172
	v_and_b32_e32 v103, 0xffff0000, v172
	v_lshlrev_b32_e32 v100, 16, v173
	v_and_b32_e32 v101, 0xffff0000, v173
	v_pk_add_f32 v[94:95], v[94:95], v[100:101]
	v_pk_add_f32 v[92:93], v[92:93], v[102:103]
	s_nop 0
	v_cvt_pk_bf16_f32 v100, v92, v93
	v_cvt_pk_bf16_f32 v101, v94, v95
	v_mul_f32_e32 v93, v93, v93
	v_mov_b32_e32 v224, v100
	v_mov_b32_e32 v225, v101
	v_mul_f32_e32 v95, v95, v95
	v_fmac_f32_e32 v93, v92, v92
	v_fmac_f32_e32 v95, v94, v94
	v_add_f32_e32 v92, v93, v95
	s_waitcnt vmcnt(15)
	v_lshlrev_b32_e32 v100, 16, v174
	v_and_b32_e32 v101, 0xffff0000, v174
	v_lshlrev_b32_e32 v102, 16, v175
	v_and_b32_e32 v103, 0xffff0000, v175
	v_pk_add_f32 v[90:91], v[90:91], v[102:103]
	v_pk_add_f32 v[88:89], v[88:89], v[100:101]
	s_nop 0
	v_cvt_pk_bf16_f32 v100, v88, v89
	v_cvt_pk_bf16_f32 v101, v90, v91
	v_mul_f32_e32 v89, v89, v89
	v_mov_b32_e32 v226, v100
	v_mov_b32_e32 v227, v101
	v_lshl_add_u64 v[234:235], v[98:99], 0, v[232:233]
	s_nop 0
	v_permlane16_swap_b32_e32 v224, v226
	v_permlane16_swap_b32_e32 v225, v227
	global_store_dwordx4 v[234:235], v[224:227], off
	v_mul_f32_e32 v91, v91, v91
	v_fmac_f32_e32 v89, v88, v88
	v_fmac_f32_e32 v91, v90, v90
	v_add_f32_e32 v88, v89, v91
	v_add_f32_e32 v88, v92, v88
	s_waitcnt vmcnt(15)
	v_permlane16_swap_b32_e32 v176, v178
	v_permlane16_swap_b32_e32 v177, v179
	v_lshlrev_b32_e32 v100, 16, v176
	v_and_b32_e32 v101, 0xffff0000, v176
	v_lshlrev_b32_e32 v102, 16, v177
	v_and_b32_e32 v103, 0xffff0000, v177
	v_pk_add_f32 v[86:87], v[86:87], v[102:103]
	v_pk_add_f32 v[84:85], v[84:85], v[100:101]
	s_nop 0
	v_cvt_pk_bf16_f32 v100, v84, v85
	v_cvt_pk_bf16_f32 v101, v86, v87
	v_mul_f32_e32 v85, v85, v85
	v_mul_f32_e32 v87, v87, v87
	v_fmac_f32_e32 v85, v84, v84
	v_fmac_f32_e32 v87, v86, v86
	v_add_f32_e32 v84, v85, v87
	v_add_f32_e32 v88, v88, v84
	v_mov_b32_e32 v228, v100
	v_mov_b32_e32 v229, v101
	s_waitcnt vmcnt(15)
	v_lshlrev_b32_e32 v84, 16, v178
	v_and_b32_e32 v85, 0xffff0000, v178
	v_lshlrev_b32_e32 v86, 16, v179
	v_and_b32_e32 v87, 0xffff0000, v179
	v_pk_add_f32 v[82:83], v[82:83], v[86:87]
	v_pk_add_f32 v[80:81], v[80:81], v[84:85]
	v_mul_f32_e32 v85, v83, v83
	v_mul_f32_e32 v84, v81, v81
	v_fmac_f32_e32 v84, v80, v80
	v_fmac_f32_e32 v85, v82, v82
	v_add_f32_e32 v84, v84, v85
	v_add_f32_e32 v84, v88, v84
	ds_swizzle_b32 v85, v84 offset:swizzle(SWAP,16)
	v_cvt_pk_bf16_f32 v80, v80, v81
	v_cvt_pk_bf16_f32 v81, v82, v83
	v_mov_b32_e32 v230, v80
	v_mov_b32_e32 v231, v81
	v_lshl_add_u64 v[234:235], v[98:99], 0, v[232:233]
	s_nop 0
	v_permlane16_swap_b32_e32 v228, v230
	v_permlane16_swap_b32_e32 v229, v231
	global_store_dwordx4 v[234:235], v[228:231], off offset:256
	s_waitcnt lgkmcnt(0)
	v_add_f32_e32 v80, v84, v85
	v_mov_b32_e32 v81, v80
	s_nop 1
	v_permlane32_swap_b32_e32 v80, v81
	s_and_saveexec_b64 s[28:29], s[4:5]
	s_cbranch_execz .LBB0_2095
	v_add_f32_e32 v82, v80, v81
	v_lshlrev_b64 v[80:81], 6, v[96:97]
	v_lshl_add_u64 v[80:81], s[12:13], 0, v[80:81]
	v_lshl_add_u64 v[80:81], s[26:27], 2, v[80:81]
	s_lshl_b32 s8, s48, 2
	v_lshl_add_u64 v[80:81], v[80:81], 0, s[8:9]
	global_store_dword v[80:81], v82, off
.LBB0_2095:
	s_or_b64 exec, exec, s[28:29]
	v_or_b32_e32 v80, 48, v142
	v_ashrrev_i32_e32 v81, 31, v80
	v_lshlrev_b64 v[82:83], 11, v[80:81]
	v_lshl_add_u64 v[82:83], s[2:3], 0, v[82:83]
	v_lshl_add_u64 v[82:83], v[140:141], 1, v[82:83]
	s_waitcnt vmcnt(15)
	v_permlane16_swap_b32_e32 v180, v182
	v_permlane16_swap_b32_e32 v181, v183
	v_lshlrev_b32_e32 v86, 16, v180
	v_and_b32_e32 v87, 0xffff0000, v180
	v_lshlrev_b32_e32 v84, 16, v181
	v_and_b32_e32 v85, 0xffff0000, v181
	v_pk_add_f32 v[78:79], v[78:79], v[84:85]
	v_pk_add_f32 v[76:77], v[76:77], v[86:87]
	s_nop 0
	v_cvt_pk_bf16_f32 v84, v76, v77
	v_cvt_pk_bf16_f32 v85, v78, v79
	v_mul_f32_e32 v77, v77, v77
	v_mov_b32_e32 v224, v84
	v_mov_b32_e32 v225, v85
	v_mul_f32_e32 v79, v79, v79
	v_fmac_f32_e32 v77, v76, v76
	v_fmac_f32_e32 v79, v78, v78
	v_add_f32_e32 v76, v77, v79
	s_waitcnt vmcnt(15)
	v_lshlrev_b32_e32 v84, 16, v182
	v_and_b32_e32 v85, 0xffff0000, v182
	v_lshlrev_b32_e32 v86, 16, v183
	v_and_b32_e32 v87, 0xffff0000, v183
	v_pk_add_f32 v[74:75], v[74:75], v[86:87]
	v_pk_add_f32 v[72:73], v[72:73], v[84:85]
	s_nop 0
	v_cvt_pk_bf16_f32 v84, v72, v73
	v_cvt_pk_bf16_f32 v85, v74, v75
	v_mul_f32_e32 v73, v73, v73
	v_mov_b32_e32 v226, v84
	v_mov_b32_e32 v227, v85
	v_lshl_add_u64 v[234:235], v[82:83], 0, v[232:233]
	s_nop 0
	v_permlane16_swap_b32_e32 v224, v226
	v_permlane16_swap_b32_e32 v225, v227
	global_store_dwordx4 v[234:235], v[224:227], off
	v_mul_f32_e32 v75, v75, v75
	v_fmac_f32_e32 v73, v72, v72
	v_fmac_f32_e32 v75, v74, v74
	v_add_f32_e32 v72, v73, v75
	v_add_f32_e32 v72, v76, v72
	s_waitcnt vmcnt(15)
	v_permlane16_swap_b32_e32 v184, v186
	v_permlane16_swap_b32_e32 v185, v187
	v_lshlrev_b32_e32 v84, 16, v184
	v_and_b32_e32 v85, 0xffff0000, v184
	v_lshlrev_b32_e32 v86, 16, v185
	v_and_b32_e32 v87, 0xffff0000, v185
	v_pk_add_f32 v[70:71], v[70:71], v[86:87]
	v_pk_add_f32 v[68:69], v[68:69], v[84:85]
	s_nop 0
	v_cvt_pk_bf16_f32 v84, v68, v69
	v_cvt_pk_bf16_f32 v85, v70, v71
	v_mul_f32_e32 v69, v69, v69
	v_mul_f32_e32 v71, v71, v71
	v_fmac_f32_e32 v69, v68, v68
	v_fmac_f32_e32 v71, v70, v70
	v_add_f32_e32 v68, v69, v71
	v_add_f32_e32 v72, v72, v68
	v_mov_b32_e32 v228, v84
	v_mov_b32_e32 v229, v85
	s_waitcnt vmcnt(15)
	v_lshlrev_b32_e32 v68, 16, v186
	v_and_b32_e32 v69, 0xffff0000, v186
	v_lshlrev_b32_e32 v70, 16, v187
	v_and_b32_e32 v71, 0xffff0000, v187
	v_pk_add_f32 v[66:67], v[66:67], v[70:71]
	v_pk_add_f32 v[64:65], v[64:65], v[68:69]
	v_mul_f32_e32 v69, v67, v67
	v_mul_f32_e32 v68, v65, v65
	v_fmac_f32_e32 v68, v64, v64
	v_fmac_f32_e32 v69, v66, v66
	v_add_f32_e32 v68, v68, v69
	v_add_f32_e32 v68, v72, v68
	ds_swizzle_b32 v69, v68 offset:swizzle(SWAP,16)
	v_cvt_pk_bf16_f32 v64, v64, v65
	v_cvt_pk_bf16_f32 v65, v66, v67
	v_mov_b32_e32 v230, v64
	v_mov_b32_e32 v231, v65
	v_lshl_add_u64 v[234:235], v[82:83], 0, v[232:233]
	s_nop 0
	v_permlane16_swap_b32_e32 v228, v230
	v_permlane16_swap_b32_e32 v229, v231
	global_store_dwordx4 v[234:235], v[228:231], off offset:256
	s_waitcnt lgkmcnt(0)
	v_add_f32_e32 v64, v68, v69
	v_mov_b32_e32 v65, v64
	s_nop 1
	v_permlane32_swap_b32_e32 v64, v65
	s_and_saveexec_b64 s[28:29], s[4:5]
	s_cbranch_execz .LBB0_2097
	v_add_f32_e32 v66, v64, v65
	v_lshlrev_b64 v[64:65], 6, v[80:81]
	v_lshl_add_u64 v[64:65], s[12:13], 0, v[64:65]
	v_lshl_add_u64 v[64:65], s[26:27], 2, v[64:65]
	s_lshl_b32 s8, s48, 2
	v_lshl_add_u64 v[64:65], v[64:65], 0, s[8:9]
	global_store_dword v[64:65], v66, off
.LBB0_2097:
	s_or_b64 exec, exec, s[28:29]
	v_add_u32_e32 v64, 0x80, v142
	v_ashrrev_i32_e32 v65, 31, v64
	v_lshlrev_b64 v[66:67], 11, v[64:65]
	v_lshl_add_u64 v[66:67], s[2:3], 0, v[66:67]
	v_lshl_add_u64 v[66:67], v[140:141], 1, v[66:67]
	s_waitcnt vmcnt(15)
	v_permlane16_swap_b32_e32 v188, v190
	v_permlane16_swap_b32_e32 v189, v191
	v_lshlrev_b32_e32 v70, 16, v188
	v_and_b32_e32 v71, 0xffff0000, v188
	v_lshlrev_b32_e32 v68, 16, v189
	v_and_b32_e32 v69, 0xffff0000, v189
	v_pk_add_f32 v[62:63], v[62:63], v[68:69]
	v_pk_add_f32 v[60:61], v[60:61], v[70:71]
	s_nop 0
	v_cvt_pk_bf16_f32 v68, v60, v61
	v_cvt_pk_bf16_f32 v69, v62, v63
	v_mul_f32_e32 v61, v61, v61
	v_mov_b32_e32 v224, v68
	v_mov_b32_e32 v225, v69
	v_mul_f32_e32 v63, v63, v63
	v_fmac_f32_e32 v61, v60, v60
	v_fmac_f32_e32 v63, v62, v62
	v_add_f32_e32 v60, v61, v63
	s_waitcnt vmcnt(15)
	v_lshlrev_b32_e32 v68, 16, v190
	v_and_b32_e32 v69, 0xffff0000, v190
	v_lshlrev_b32_e32 v70, 16, v191
	v_and_b32_e32 v71, 0xffff0000, v191
	v_pk_add_f32 v[58:59], v[58:59], v[70:71]
	v_pk_add_f32 v[56:57], v[56:57], v[68:69]
	s_nop 0
	v_cvt_pk_bf16_f32 v68, v56, v57
	v_cvt_pk_bf16_f32 v69, v58, v59
	v_mul_f32_e32 v57, v57, v57
	v_mov_b32_e32 v226, v68
	v_mov_b32_e32 v227, v69
	v_lshl_add_u64 v[234:235], v[66:67], 0, v[232:233]
	s_nop 0
	v_permlane16_swap_b32_e32 v224, v226
	v_permlane16_swap_b32_e32 v225, v227
	global_store_dwordx4 v[234:235], v[224:227], off
	v_mul_f32_e32 v59, v59, v59
	v_fmac_f32_e32 v57, v56, v56
	v_fmac_f32_e32 v59, v58, v58
	v_add_f32_e32 v56, v57, v59
	v_add_f32_e32 v56, v60, v56
	s_waitcnt vmcnt(15)
	v_permlane16_swap_b32_e32 v192, v194
	v_permlane16_swap_b32_e32 v193, v195
	v_lshlrev_b32_e32 v68, 16, v192
	v_and_b32_e32 v69, 0xffff0000, v192
	v_lshlrev_b32_e32 v70, 16, v193
	v_and_b32_e32 v71, 0xffff0000, v193
	v_pk_add_f32 v[54:55], v[54:55], v[70:71]
	v_pk_add_f32 v[52:53], v[52:53], v[68:69]
	s_nop 0
	v_cvt_pk_bf16_f32 v68, v52, v53
	v_cvt_pk_bf16_f32 v69, v54, v55
	v_mul_f32_e32 v53, v53, v53
	v_mul_f32_e32 v55, v55, v55
	v_fmac_f32_e32 v53, v52, v52
	v_fmac_f32_e32 v55, v54, v54
	v_add_f32_e32 v52, v53, v55
	v_add_f32_e32 v56, v56, v52
	v_mov_b32_e32 v228, v68
	v_mov_b32_e32 v229, v69
	s_waitcnt vmcnt(15)
	v_lshlrev_b32_e32 v52, 16, v194
	v_and_b32_e32 v53, 0xffff0000, v194
	v_lshlrev_b32_e32 v54, 16, v195
	v_and_b32_e32 v55, 0xffff0000, v195
	v_pk_add_f32 v[50:51], v[50:51], v[54:55]
	v_pk_add_f32 v[48:49], v[48:49], v[52:53]
	v_mul_f32_e32 v53, v51, v51
	v_mul_f32_e32 v52, v49, v49
	v_fmac_f32_e32 v52, v48, v48
	v_fmac_f32_e32 v53, v50, v50
	v_add_f32_e32 v52, v52, v53
	v_add_f32_e32 v52, v56, v52
	ds_swizzle_b32 v53, v52 offset:swizzle(SWAP,16)
	v_cvt_pk_bf16_f32 v48, v48, v49
	v_cvt_pk_bf16_f32 v49, v50, v51
	v_mov_b32_e32 v230, v48
	v_mov_b32_e32 v231, v49
	v_lshl_add_u64 v[234:235], v[66:67], 0, v[232:233]
	s_nop 0
	v_permlane16_swap_b32_e32 v228, v230
	v_permlane16_swap_b32_e32 v229, v231
	global_store_dwordx4 v[234:235], v[228:231], off offset:256
	s_waitcnt lgkmcnt(0)
	v_add_f32_e32 v48, v52, v53
	v_mov_b32_e32 v49, v48
	s_nop 1
	v_permlane32_swap_b32_e32 v48, v49
	s_and_saveexec_b64 s[28:29], s[4:5]
	s_cbranch_execz .LBB0_2099
	v_add_f32_e32 v50, v48, v49
	v_lshlrev_b64 v[48:49], 6, v[64:65]
	v_lshl_add_u64 v[48:49], s[12:13], 0, v[48:49]
	v_lshl_add_u64 v[48:49], s[26:27], 2, v[48:49]
	s_lshl_b32 s8, s48, 2
	v_lshl_add_u64 v[48:49], v[48:49], 0, s[8:9]
	global_store_dword v[48:49], v50, off
.LBB0_2099:
	s_or_b64 exec, exec, s[28:29]
	v_add_u32_e32 v48, 0x90, v142
	v_ashrrev_i32_e32 v49, 31, v48
	v_lshlrev_b64 v[50:51], 11, v[48:49]
	v_lshl_add_u64 v[50:51], s[2:3], 0, v[50:51]
	v_lshl_add_u64 v[50:51], v[140:141], 1, v[50:51]
	s_waitcnt vmcnt(15)
	v_permlane16_swap_b32_e32 v196, v198
	v_permlane16_swap_b32_e32 v197, v199
	v_lshlrev_b32_e32 v54, 16, v196
	v_and_b32_e32 v55, 0xffff0000, v196
	v_lshlrev_b32_e32 v52, 16, v197
	v_and_b32_e32 v53, 0xffff0000, v197
	v_pk_add_f32 v[46:47], v[46:47], v[52:53]
	v_pk_add_f32 v[44:45], v[44:45], v[54:55]
	s_nop 0
	v_cvt_pk_bf16_f32 v52, v44, v45
	v_cvt_pk_bf16_f32 v53, v46, v47
	v_mul_f32_e32 v45, v45, v45
	v_mov_b32_e32 v224, v52
	v_mov_b32_e32 v225, v53
	v_mul_f32_e32 v47, v47, v47
	v_fmac_f32_e32 v45, v44, v44
	v_fmac_f32_e32 v47, v46, v46
	v_add_f32_e32 v44, v45, v47
	s_waitcnt vmcnt(15)
	v_lshlrev_b32_e32 v52, 16, v198
	v_and_b32_e32 v53, 0xffff0000, v198
	v_lshlrev_b32_e32 v54, 16, v199
	v_and_b32_e32 v55, 0xffff0000, v199
	v_pk_add_f32 v[42:43], v[42:43], v[54:55]
	v_pk_add_f32 v[40:41], v[40:41], v[52:53]
	s_nop 0
	v_cvt_pk_bf16_f32 v52, v40, v41
	v_cvt_pk_bf16_f32 v53, v42, v43
	v_mul_f32_e32 v41, v41, v41
	v_mov_b32_e32 v226, v52
	v_mov_b32_e32 v227, v53
	v_lshl_add_u64 v[234:235], v[50:51], 0, v[232:233]
	s_nop 0
	v_permlane16_swap_b32_e32 v224, v226
	v_permlane16_swap_b32_e32 v225, v227
	global_store_dwordx4 v[234:235], v[224:227], off
	v_mul_f32_e32 v43, v43, v43
	v_fmac_f32_e32 v41, v40, v40
	v_fmac_f32_e32 v43, v42, v42
	v_add_f32_e32 v40, v41, v43
	v_add_f32_e32 v40, v44, v40
	s_waitcnt vmcnt(15)
	v_permlane16_swap_b32_e32 v200, v202
	v_permlane16_swap_b32_e32 v201, v203
	v_lshlrev_b32_e32 v52, 16, v200
	v_and_b32_e32 v53, 0xffff0000, v200
	v_lshlrev_b32_e32 v54, 16, v201
	v_and_b32_e32 v55, 0xffff0000, v201
	v_pk_add_f32 v[38:39], v[38:39], v[54:55]
	v_pk_add_f32 v[36:37], v[36:37], v[52:53]
	s_nop 0
	v_cvt_pk_bf16_f32 v52, v36, v37
	v_cvt_pk_bf16_f32 v53, v38, v39
	v_mul_f32_e32 v37, v37, v37
	v_mul_f32_e32 v39, v39, v39
	v_fmac_f32_e32 v37, v36, v36
	v_fmac_f32_e32 v39, v38, v38
	v_add_f32_e32 v36, v37, v39
	v_add_f32_e32 v40, v40, v36
	v_mov_b32_e32 v228, v52
	v_mov_b32_e32 v229, v53
	s_waitcnt vmcnt(15)
	v_lshlrev_b32_e32 v36, 16, v202
	v_and_b32_e32 v37, 0xffff0000, v202
	v_lshlrev_b32_e32 v38, 16, v203
	v_and_b32_e32 v39, 0xffff0000, v203
	v_pk_add_f32 v[34:35], v[34:35], v[38:39]
	v_pk_add_f32 v[32:33], v[32:33], v[36:37]
	v_mul_f32_e32 v37, v35, v35
	v_mul_f32_e32 v36, v33, v33
	v_fmac_f32_e32 v36, v32, v32
	v_fmac_f32_e32 v37, v34, v34
	v_add_f32_e32 v36, v36, v37
	v_add_f32_e32 v36, v40, v36
	ds_swizzle_b32 v37, v36 offset:swizzle(SWAP,16)
	v_cvt_pk_bf16_f32 v32, v32, v33
	v_cvt_pk_bf16_f32 v33, v34, v35
	v_mov_b32_e32 v230, v32
	v_mov_b32_e32 v231, v33
	v_lshl_add_u64 v[234:235], v[50:51], 0, v[232:233]
	s_nop 0
	v_permlane16_swap_b32_e32 v228, v230
	v_permlane16_swap_b32_e32 v229, v231
	global_store_dwordx4 v[234:235], v[228:231], off offset:256
	s_waitcnt lgkmcnt(0)
	v_add_f32_e32 v32, v36, v37
	v_mov_b32_e32 v33, v32
	s_nop 1
	v_permlane32_swap_b32_e32 v32, v33
	s_and_saveexec_b64 s[28:29], s[4:5]
	s_cbranch_execz .LBB0_2101
	v_add_f32_e32 v34, v32, v33
	v_lshlrev_b64 v[32:33], 6, v[48:49]
	v_lshl_add_u64 v[32:33], s[12:13], 0, v[32:33]
	v_lshl_add_u64 v[32:33], s[26:27], 2, v[32:33]
	s_lshl_b32 s8, s48, 2
	v_lshl_add_u64 v[32:33], v[32:33], 0, s[8:9]
	global_store_dword v[32:33], v34, off
.LBB0_2101:
	s_or_b64 exec, exec, s[28:29]
	v_add_u32_e32 v32, 0xa0, v142
	v_ashrrev_i32_e32 v33, 31, v32
	v_lshlrev_b64 v[34:35], 11, v[32:33]
	v_lshl_add_u64 v[34:35], s[2:3], 0, v[34:35]
	v_lshl_add_u64 v[34:35], v[140:141], 1, v[34:35]
	s_waitcnt vmcnt(15)
	v_permlane16_swap_b32_e32 v208, v210
	v_permlane16_swap_b32_e32 v209, v211
	v_lshlrev_b32_e32 v38, 16, v208
	v_and_b32_e32 v39, 0xffff0000, v208
	v_lshlrev_b32_e32 v36, 16, v209
	v_and_b32_e32 v37, 0xffff0000, v209
	v_pk_add_f32 v[30:31], v[30:31], v[36:37]
	v_pk_add_f32 v[28:29], v[28:29], v[38:39]
	s_nop 0
	v_cvt_pk_bf16_f32 v36, v28, v29
	v_cvt_pk_bf16_f32 v37, v30, v31
	v_mul_f32_e32 v29, v29, v29
	v_mov_b32_e32 v224, v36
	v_mov_b32_e32 v225, v37
	v_mul_f32_e32 v31, v31, v31
	v_fmac_f32_e32 v29, v28, v28
	v_fmac_f32_e32 v31, v30, v30
	v_add_f32_e32 v28, v29, v31
	s_waitcnt vmcnt(15)
	v_lshlrev_b32_e32 v36, 16, v210
	v_and_b32_e32 v37, 0xffff0000, v210
	v_lshlrev_b32_e32 v38, 16, v211
	v_and_b32_e32 v39, 0xffff0000, v211
	v_pk_add_f32 v[26:27], v[26:27], v[38:39]
	v_pk_add_f32 v[24:25], v[24:25], v[36:37]
	s_nop 0
	v_cvt_pk_bf16_f32 v36, v24, v25
	v_cvt_pk_bf16_f32 v37, v26, v27
	v_mul_f32_e32 v25, v25, v25
	v_mov_b32_e32 v226, v36
	v_mov_b32_e32 v227, v37
	v_lshl_add_u64 v[234:235], v[34:35], 0, v[232:233]
	s_nop 0
	v_permlane16_swap_b32_e32 v224, v226
	v_permlane16_swap_b32_e32 v225, v227
	global_store_dwordx4 v[234:235], v[224:227], off
	v_mul_f32_e32 v27, v27, v27
	v_fmac_f32_e32 v25, v24, v24
	v_fmac_f32_e32 v27, v26, v26
	v_add_f32_e32 v24, v25, v27
	v_add_f32_e32 v24, v28, v24
	s_waitcnt vmcnt(15)
	v_permlane16_swap_b32_e32 v212, v214
	v_permlane16_swap_b32_e32 v213, v215
	v_lshlrev_b32_e32 v36, 16, v212
	v_and_b32_e32 v37, 0xffff0000, v212
	v_lshlrev_b32_e32 v38, 16, v213
	v_and_b32_e32 v39, 0xffff0000, v213
	v_pk_add_f32 v[22:23], v[22:23], v[38:39]
	v_pk_add_f32 v[20:21], v[20:21], v[36:37]
	s_nop 0
	v_cvt_pk_bf16_f32 v36, v20, v21
	v_cvt_pk_bf16_f32 v37, v22, v23
	v_mul_f32_e32 v21, v21, v21
	v_mul_f32_e32 v23, v23, v23
	v_fmac_f32_e32 v21, v20, v20
	v_fmac_f32_e32 v23, v22, v22
	v_add_f32_e32 v20, v21, v23
	v_add_f32_e32 v24, v24, v20
	v_mov_b32_e32 v228, v36
	v_mov_b32_e32 v229, v37
	s_waitcnt vmcnt(15)
	v_lshlrev_b32_e32 v20, 16, v214
	v_and_b32_e32 v21, 0xffff0000, v214
	v_lshlrev_b32_e32 v22, 16, v215
	v_and_b32_e32 v23, 0xffff0000, v215
	v_pk_add_f32 v[18:19], v[18:19], v[22:23]
	v_pk_add_f32 v[16:17], v[16:17], v[20:21]
	v_mul_f32_e32 v21, v19, v19
	v_mul_f32_e32 v20, v17, v17
	v_fmac_f32_e32 v20, v16, v16
	v_fmac_f32_e32 v21, v18, v18
	v_add_f32_e32 v20, v20, v21
	v_add_f32_e32 v20, v24, v20
	ds_swizzle_b32 v21, v20 offset:swizzle(SWAP,16)
	v_cvt_pk_bf16_f32 v16, v16, v17
	v_cvt_pk_bf16_f32 v17, v18, v19
	v_mov_b32_e32 v230, v16
	v_mov_b32_e32 v231, v17
	v_lshl_add_u64 v[234:235], v[34:35], 0, v[232:233]
	s_nop 0
	v_permlane16_swap_b32_e32 v228, v230
	v_permlane16_swap_b32_e32 v229, v231
	global_store_dwordx4 v[234:235], v[228:231], off offset:256
	s_waitcnt lgkmcnt(0)
	v_add_f32_e32 v16, v20, v21
	v_mov_b32_e32 v17, v16
	s_nop 1
	v_permlane32_swap_b32_e32 v16, v17
	s_and_saveexec_b64 s[28:29], s[4:5]
	s_cbranch_execz .LBB0_2103
	v_add_f32_e32 v18, v16, v17
	v_lshlrev_b64 v[16:17], 6, v[32:33]
	v_lshl_add_u64 v[16:17], s[12:13], 0, v[16:17]
	v_lshl_add_u64 v[16:17], s[26:27], 2, v[16:17]
	s_lshl_b32 s8, s48, 2
	v_lshl_add_u64 v[16:17], v[16:17], 0, s[8:9]
	global_store_dword v[16:17], v18, off
.LBB0_2103:
	s_or_b64 exec, exec, s[28:29]
	v_add_u32_e32 v16, 0xb0, v142
	v_ashrrev_i32_e32 v17, 31, v16
	v_lshlrev_b64 v[18:19], 11, v[16:17]
	v_lshl_add_u64 v[18:19], s[2:3], 0, v[18:19]
	v_lshl_add_u64 v[18:19], v[140:141], 1, v[18:19]
	s_waitcnt vmcnt(15)
	v_permlane16_swap_b32_e32 v216, v218
	v_permlane16_swap_b32_e32 v217, v219
	v_lshlrev_b32_e32 v22, 16, v216
	v_and_b32_e32 v23, 0xffff0000, v216
	v_lshlrev_b32_e32 v20, 16, v217
	v_and_b32_e32 v21, 0xffff0000, v217
	v_pk_add_f32 v[14:15], v[14:15], v[20:21]
	v_pk_add_f32 v[12:13], v[12:13], v[22:23]
	s_nop 0
	v_cvt_pk_bf16_f32 v20, v12, v13
	v_cvt_pk_bf16_f32 v21, v14, v15
	v_mul_f32_e32 v13, v13, v13
	v_mov_b32_e32 v224, v20
	v_mov_b32_e32 v225, v21
	v_mul_f32_e32 v15, v15, v15
	v_fmac_f32_e32 v13, v12, v12
	v_fmac_f32_e32 v15, v14, v14
	v_add_f32_e32 v12, v13, v15
	s_waitcnt vmcnt(15)
	v_lshlrev_b32_e32 v20, 16, v218
	v_and_b32_e32 v21, 0xffff0000, v218
	v_lshlrev_b32_e32 v22, 16, v219
	v_and_b32_e32 v23, 0xffff0000, v219
	v_pk_add_f32 v[10:11], v[10:11], v[22:23]
	v_pk_add_f32 v[8:9], v[8:9], v[20:21]
	s_nop 0
	v_cvt_pk_bf16_f32 v20, v8, v9
	v_cvt_pk_bf16_f32 v21, v10, v11
	v_mul_f32_e32 v9, v9, v9
	v_mov_b32_e32 v226, v20
	v_mov_b32_e32 v227, v21
	v_lshl_add_u64 v[234:235], v[18:19], 0, v[232:233]
	s_nop 0
	v_permlane16_swap_b32_e32 v224, v226
	v_permlane16_swap_b32_e32 v225, v227
	global_store_dwordx4 v[234:235], v[224:227], off
	v_mul_f32_e32 v11, v11, v11
	v_fmac_f32_e32 v9, v8, v8
	v_fmac_f32_e32 v11, v10, v10
	v_add_f32_e32 v8, v9, v11
	v_add_f32_e32 v8, v12, v8
	s_waitcnt vmcnt(15)
	v_permlane16_swap_b32_e32 v220, v222
	v_permlane16_swap_b32_e32 v221, v223
	v_lshlrev_b32_e32 v20, 16, v220
	v_and_b32_e32 v21, 0xffff0000, v220
	v_lshlrev_b32_e32 v22, 16, v221
	v_and_b32_e32 v23, 0xffff0000, v221
	v_pk_add_f32 v[6:7], v[6:7], v[22:23]
	v_pk_add_f32 v[4:5], v[4:5], v[20:21]
	s_nop 0
	v_cvt_pk_bf16_f32 v20, v4, v5
	v_cvt_pk_bf16_f32 v21, v6, v7
	v_mul_f32_e32 v5, v5, v5
	v_mul_f32_e32 v7, v7, v7
	v_fmac_f32_e32 v5, v4, v4
	v_fmac_f32_e32 v7, v6, v6
	v_add_f32_e32 v4, v5, v7
	v_add_f32_e32 v8, v8, v4
	v_mov_b32_e32 v228, v20
	v_mov_b32_e32 v229, v21
	s_waitcnt vmcnt(15)
	v_lshlrev_b32_e32 v4, 16, v222
	v_and_b32_e32 v5, 0xffff0000, v222
	v_lshlrev_b32_e32 v6, 16, v223
	v_and_b32_e32 v7, 0xffff0000, v223
	v_pk_add_f32 v[2:3], v[2:3], v[6:7]
	v_pk_add_f32 v[0:1], v[0:1], v[4:5]
	v_mul_f32_e32 v5, v3, v3
	v_mul_f32_e32 v4, v1, v1
	v_fmac_f32_e32 v4, v0, v0
	v_fmac_f32_e32 v5, v2, v2
	v_add_f32_e32 v4, v4, v5
	v_add_f32_e32 v4, v8, v4
	ds_swizzle_b32 v5, v4 offset:swizzle(SWAP,16)
	v_cvt_pk_bf16_f32 v0, v0, v1
	v_cvt_pk_bf16_f32 v1, v2, v3
	v_mov_b32_e32 v230, v0
	v_mov_b32_e32 v231, v1
	v_lshl_add_u64 v[234:235], v[18:19], 0, v[232:233]
	s_nop 0
	v_permlane16_swap_b32_e32 v228, v230
	v_permlane16_swap_b32_e32 v229, v231
	global_store_dwordx4 v[234:235], v[228:231], off offset:256
	s_waitcnt lgkmcnt(0)
	v_add_f32_e32 v0, v4, v5
	v_mov_b32_e32 v1, v0
	s_nop 1
	v_permlane32_swap_b32_e32 v0, v1
	s_and_saveexec_b64 s[28:29], s[4:5]
	s_cbranch_execz .LBB0_2105
	v_add_f32_e32 v2, v0, v1
	v_lshlrev_b64 v[0:1], 6, v[16:17]
	v_lshl_add_u64 v[0:1], s[12:13], 0, v[0:1]
	v_lshl_add_u64 v[0:1], s[26:27], 2, v[0:1]
	s_lshl_b32 s8, s48, 2
	v_lshl_add_u64 v[0:1], v[0:1], 0, s[8:9]
	global_store_dword v[0:1], v2, off

.LBB0_2261:
	v_lshl_add_u32 v142, s26, 8, v144
	v_ashrrev_i32_e32 v143, 31, v142
	v_lshl_or_b32 v140, s10, 8, v146
	v_lshlrev_b64 v[150:151], 11, v[142:143]
	v_ashrrev_i32_e32 v141, 31, v140
	v_lshl_add_u64 v[150:151], s[8:9], 0, v[150:151]
	v_lshl_add_u64 v[150:151], v[140:141], 1, v[150:151]
	s_mov_b64 s[98:99], 0x8000
	s_mov_b64 s[100:101], 0x28000
	v_bfe_u32 v232, v206, 4, 1
	v_mul_u32_u24_e32 v232, 24, v232
	v_mov_b32_e32 v233, 0
	v_lshl_add_u64 v[234:235], v[150:151], 0, v[232:233]
	global_load_dwordx4 v[156:159], v[234:235], off
	global_load_dwordx4 v[160:163], v[234:235], off offset:256
	v_lshl_add_u64 v[234:235], v[234:235], 0, s[98:99]
	global_load_dwordx4 v[164:167], v[234:235], off
	global_load_dwordx4 v[168:171], v[234:235], off offset:256
	v_lshl_add_u64 v[234:235], v[234:235], 0, s[98:99]
	global_load_dwordx4 v[172:175], v[234:235], off
	global_load_dwordx4 v[176:179], v[234:235], off offset:256
	v_lshl_add_u64 v[234:235], v[234:235], 0, s[98:99]
	global_load_dwordx4 v[180:183], v[234:235], off
	global_load_dwordx4 v[184:187], v[234:235], off offset:256
	v_lshl_add_u64 v[234:235], v[234:235], 0, s[100:101]
	global_load_dwordx4 v[188:191], v[234:235], off
	global_load_dwordx4 v[192:195], v[234:235], off offset:256
	v_lshl_add_u64 v[234:235], v[234:235], 0, s[98:99]
	global_load_dwordx4 v[196:199], v[234:235], off
	global_load_dwordx4 v[200:203], v[234:235], off offset:256
	v_lshl_add_u64 v[234:235], v[234:235], 0, s[98:99]
	global_load_dwordx4 v[208:211], v[234:235], off
	global_load_dwordx4 v[212:215], v[234:235], off offset:256
	v_lshl_add_u64 v[234:235], v[234:235], 0, s[98:99]
	global_load_dwordx4 v[216:219], v[234:235], off
	global_load_dwordx4 v[220:223], v[234:235], off offset:256
	s_lshl_b32 s26, s10, 2
	s_ashr_i32 s27, s26, 31
	s_waitcnt vmcnt(15)
	v_permlane16_swap_b32_e32 v156, v158
	v_permlane16_swap_b32_e32 v157, v159
	v_lshlrev_b32_e32 v154, 16, v156
	v_and_b32_e32 v155, 0xffff0000, v156
	v_lshlrev_b32_e32 v152, 16, v157
	v_and_b32_e32 v153, 0xffff0000, v157
	v_pk_add_f32 v[126:127], v[126:127], v[152:153]
	v_pk_add_f32 v[124:125], v[124:125], v[154:155]
	s_nop 0
	v_cvt_pk_bf16_f32 v152, v124, v125
	v_cvt_pk_bf16_f32 v153, v126, v127
	v_mul_f32_e32 v125, v125, v125
	v_mov_b32_e32 v224, v152
	v_mov_b32_e32 v225, v153
	v_mul_f32_e32 v127, v127, v127
	v_fmac_f32_e32 v125, v124, v124
	v_fmac_f32_e32 v127, v126, v126
	v_add_f32_e32 v124, v125, v127
	s_waitcnt vmcnt(15)
	v_lshlrev_b32_e32 v152, 16, v158
	v_and_b32_e32 v153, 0xffff0000, v158
	v_lshlrev_b32_e32 v154, 16, v159
	v_and_b32_e32 v155, 0xffff0000, v159
	v_pk_add_f32 v[122:123], v[122:123], v[154:155]
	v_pk_add_f32 v[120:121], v[120:121], v[152:153]
	s_nop 0
	v_cvt_pk_bf16_f32 v152, v120, v121
	v_cvt_pk_bf16_f32 v153, v122, v123
	v_mul_f32_e32 v121, v121, v121
	v_mov_b32_e32 v226, v152
	v_mov_b32_e32 v227, v153
	v_lshl_add_u64 v[234:235], v[150:151], 0, v[232:233]
	s_nop 0
	v_permlane16_swap_b32_e32 v224, v226
	v_permlane16_swap_b32_e32 v225, v227
	global_store_dwordx4 v[234:235], v[224:227], off
	v_mul_f32_e32 v123, v123, v123
	v_fmac_f32_e32 v121, v120, v120
	v_fmac_f32_e32 v123, v122, v122
	v_add_f32_e32 v120, v121, v123
	v_add_f32_e32 v120, v124, v120
	s_waitcnt vmcnt(15)
	v_permlane16_swap_b32_e32 v160, v162
	v_permlane16_swap_b32_e32 v161, v163
	v_lshlrev_b32_e32 v152, 16, v160
	v_and_b32_e32 v153, 0xffff0000, v160
	v_lshlrev_b32_e32 v154, 16, v161
	v_and_b32_e32 v155, 0xffff0000, v161
	v_pk_add_f32 v[118:119], v[118:119], v[154:155]
	v_pk_add_f32 v[116:117], v[116:117], v[152:153]
	s_nop 0
	v_cvt_pk_bf16_f32 v152, v116, v117
	v_cvt_pk_bf16_f32 v153, v118, v119
	v_mul_f32_e32 v117, v117, v117
	v_mul_f32_e32 v119, v119, v119
	v_fmac_f32_e32 v117, v116, v116
	v_fmac_f32_e32 v119, v118, v118
	v_add_f32_e32 v116, v117, v119
	v_add_f32_e32 v120, v120, v116
	v_mov_b32_e32 v228, v152
	v_mov_b32_e32 v229, v153
	s_waitcnt vmcnt(15)
	v_lshlrev_b32_e32 v116, 16, v162
	v_and_b32_e32 v117, 0xffff0000, v162
	v_lshlrev_b32_e32 v118, 16, v163
	v_and_b32_e32 v119, 0xffff0000, v163
	v_pk_add_f32 v[114:115], v[114:115], v[118:119]
	v_pk_add_f32 v[112:113], v[112:113], v[116:117]
	v_mul_f32_e32 v117, v115, v115
	v_mul_f32_e32 v116, v113, v113
	v_fmac_f32_e32 v116, v112, v112
	v_fmac_f32_e32 v117, v114, v114
	v_add_f32_e32 v116, v116, v117
	v_add_f32_e32 v116, v120, v116
	ds_swizzle_b32 v117, v116 offset:swizzle(SWAP,16)
	v_cvt_pk_bf16_f32 v112, v112, v113
	v_cvt_pk_bf16_f32 v113, v114, v115
	v_mov_b32_e32 v230, v112
	v_mov_b32_e32 v231, v113
	v_lshl_add_u64 v[234:235], v[150:151], 0, v[232:233]
	s_nop 0
	v_permlane16_swap_b32_e32 v228, v230
	v_permlane16_swap_b32_e32 v229, v231
	global_store_dwordx4 v[234:235], v[228:231], off offset:256
	s_waitcnt lgkmcnt(0)
	v_add_f32_e32 v112, v116, v117
	v_mov_b32_e32 v113, v112
	s_nop 1
	v_permlane32_swap_b32_e32 v112, v113
	s_and_saveexec_b64 s[28:29], s[4:5]
	s_cbranch_execz .LBB0_2263
	v_add_f32_e32 v114, v112, v113
	v_lshlrev_b64 v[112:113], 6, v[142:143]
	v_lshl_add_u64 v[112:113], s[2:3], 0, v[112:113]
	v_lshl_add_u64 v[112:113], s[26:27], 2, v[112:113]
	s_lshl_b32 s10, s48, 2
	v_lshl_add_u64 v[112:113], v[112:113], 0, s[10:11]
	global_store_dword v[112:113], v114, off
.LBB0_2263:
	s_or_b64 exec, exec, s[28:29]
	v_or_b32_e32 v112, 16, v142
	v_ashrrev_i32_e32 v113, 31, v112
	v_lshlrev_b64 v[114:115], 11, v[112:113]
	v_lshl_add_u64 v[114:115], s[8:9], 0, v[114:115]
	v_lshl_add_u64 v[114:115], v[140:141], 1, v[114:115]
	s_waitcnt vmcnt(15)
	v_permlane16_swap_b32_e32 v164, v166
	v_permlane16_swap_b32_e32 v165, v167
	v_lshlrev_b32_e32 v118, 16, v164
	v_and_b32_e32 v119, 0xffff0000, v164
	v_lshlrev_b32_e32 v116, 16, v165
	v_and_b32_e32 v117, 0xffff0000, v165
	v_pk_add_f32 v[110:111], v[110:111], v[116:117]
	v_pk_add_f32 v[108:109], v[108:109], v[118:119]
	s_nop 0
	v_cvt_pk_bf16_f32 v116, v108, v109
	v_cvt_pk_bf16_f32 v117, v110, v111
	v_mul_f32_e32 v109, v109, v109
	v_mov_b32_e32 v224, v116
	v_mov_b32_e32 v225, v117
	v_mul_f32_e32 v111, v111, v111
	v_fmac_f32_e32 v109, v108, v108
	v_fmac_f32_e32 v111, v110, v110
	v_add_f32_e32 v108, v109, v111
	s_waitcnt vmcnt(15)
	v_lshlrev_b32_e32 v116, 16, v166
	v_and_b32_e32 v117, 0xffff0000, v166
	v_lshlrev_b32_e32 v118, 16, v167
	v_and_b32_e32 v119, 0xffff0000, v167
	v_pk_add_f32 v[106:107], v[106:107], v[118:119]
	v_pk_add_f32 v[104:105], v[104:105], v[116:117]
	s_nop 0
	v_cvt_pk_bf16_f32 v116, v104, v105
	v_cvt_pk_bf16_f32 v117, v106, v107
	v_mul_f32_e32 v105, v105, v105
	v_mov_b32_e32 v226, v116
	v_mov_b32_e32 v227, v117
	v_lshl_add_u64 v[234:235], v[114:115], 0, v[232:233]
	s_nop 0
	v_permlane16_swap_b32_e32 v224, v226
	v_permlane16_swap_b32_e32 v225, v227
	global_store_dwordx4 v[234:235], v[224:227], off
	v_mul_f32_e32 v107, v107, v107
	v_fmac_f32_e32 v105, v104, v104
	v_fmac_f32_e32 v107, v106, v106
	v_add_f32_e32 v104, v105, v107
	v_add_f32_e32 v104, v108, v104
	s_waitcnt vmcnt(15)
	v_permlane16_swap_b32_e32 v168, v170
	v_permlane16_swap_b32_e32 v169, v171
	v_lshlrev_b32_e32 v116, 16, v168
	v_and_b32_e32 v117, 0xffff0000, v168
	v_lshlrev_b32_e32 v118, 16, v169
	v_and_b32_e32 v119, 0xffff0000, v169
	v_pk_add_f32 v[102:103], v[102:103], v[118:119]
	v_pk_add_f32 v[100:101], v[100:101], v[116:117]
	s_nop 0
	v_cvt_pk_bf16_f32 v116, v100, v101
	v_cvt_pk_bf16_f32 v117, v102, v103
	v_mul_f32_e32 v101, v101, v101
	v_mul_f32_e32 v103, v103, v103
	v_fmac_f32_e32 v101, v100, v100
	v_fmac_f32_e32 v103, v102, v102
	v_add_f32_e32 v100, v101, v103
	v_add_f32_e32 v104, v104, v100
	v_mov_b32_e32 v228, v116
	v_mov_b32_e32 v229, v117
	s_waitcnt vmcnt(15)
	v_lshlrev_b32_e32 v100, 16, v170
	v_and_b32_e32 v101, 0xffff0000, v170
	v_lshlrev_b32_e32 v102, 16, v171
	v_and_b32_e32 v103, 0xffff0000, v171
	v_pk_add_f32 v[98:99], v[98:99], v[102:103]
	v_pk_add_f32 v[96:97], v[96:97], v[100:101]
	v_mul_f32_e32 v101, v99, v99
	v_mul_f32_e32 v100, v97, v97
	v_fmac_f32_e32 v100, v96, v96
	v_fmac_f32_e32 v101, v98, v98
	v_add_f32_e32 v100, v100, v101
	v_add_f32_e32 v100, v104, v100
	ds_swizzle_b32 v101, v100 offset:swizzle(SWAP,16)
	v_cvt_pk_bf16_f32 v96, v96, v97
	v_cvt_pk_bf16_f32 v97, v98, v99
	v_mov_b32_e32 v230, v96
	v_mov_b32_e32 v231, v97
	v_lshl_add_u64 v[234:235], v[114:115], 0, v[232:233]
	s_nop 0
	v_permlane16_swap_b32_e32 v228, v230
	v_permlane16_swap_b32_e32 v229, v231
	global_store_dwordx4 v[234:235], v[228:231], off offset:256
	s_waitcnt lgkmcnt(0)
	v_add_f32_e32 v96, v100, v101
	v_mov_b32_e32 v97, v96
	s_nop 1
	v_permlane32_swap_b32_e32 v96, v97
	s_and_saveexec_b64 s[28:29], s[4:5]
	s_cbranch_execz .LBB0_2265
	v_add_f32_e32 v98, v96, v97
	v_lshlrev_b64 v[96:97], 6, v[112:113]
	v_lshl_add_u64 v[96:97], s[2:3], 0, v[96:97]
	v_lshl_add_u64 v[96:97], s[26:27], 2, v[96:97]
	s_lshl_b32 s10, s48, 2
	v_lshl_add_u64 v[96:97], v[96:97], 0, s[10:11]
	global_store_dword v[96:97], v98, off
.LBB0_2265:
	s_or_b64 exec, exec, s[28:29]
	v_or_b32_e32 v96, 32, v142
	v_ashrrev_i32_e32 v97, 31, v96
	v_lshlrev_b64 v[98:99], 11, v[96:97]
	v_lshl_add_u64 v[98:99], s[8:9], 0, v[98:99]
	v_lshl_add_u64 v[98:99], v[140:141], 1, v[98:99]
	s_waitcnt vmcnt(15)
	v_permlane16_swap_b32_e32 v172, v174
	v_permlane16_swap_b32_e32 v173, v175
	v_lshlrev_b32_e32 v102, 16, v172
	v_and_b32_e32 v103, 0xffff0000, v172
	v_lshlrev_b32_e32 v100, 16, v173
	v_and_b32_e32 v101, 0xffff0000, v173
	v_pk_add_f32 v[94:95], v[94:95], v[100:101]
	v_pk_add_f32 v[92:93], v[92:93], v[102:103]
	s_nop 0
	v_cvt_pk_bf16_f32 v100, v92, v93
	v_cvt_pk_bf16_f32 v101, v94, v95
	v_mul_f32_e32 v93, v93, v93
	v_mov_b32_e32 v224, v100
	v_mov_b32_e32 v225, v101
	v_mul_f32_e32 v95, v95, v95
	v_fmac_f32_e32 v93, v92, v92
	v_fmac_f32_e32 v95, v94, v94
	v_add_f32_e32 v92, v93, v95
	s_waitcnt vmcnt(15)
	v_lshlrev_b32_e32 v100, 16, v174
	v_and_b32_e32 v101, 0xffff0000, v174
	v_lshlrev_b32_e32 v102, 16, v175
	v_and_b32_e32 v103, 0xffff0000, v175
	v_pk_add_f32 v[90:91], v[90:91], v[102:103]
	v_pk_add_f32 v[88:89], v[88:89], v[100:101]
	s_nop 0
	v_cvt_pk_bf16_f32 v100, v88, v89
	v_cvt_pk_bf16_f32 v101, v90, v91
	v_mul_f32_e32 v89, v89, v89
	v_mov_b32_e32 v226, v100
	v_mov_b32_e32 v227, v101
	v_lshl_add_u64 v[234:235], v[98:99], 0, v[232:233]
	s_nop 0
	v_permlane16_swap_b32_e32 v224, v226
	v_permlane16_swap_b32_e32 v225, v227
	global_store_dwordx4 v[234:235], v[224:227], off
	v_mul_f32_e32 v91, v91, v91
	v_fmac_f32_e32 v89, v88, v88
	v_fmac_f32_e32 v91, v90, v90
	v_add_f32_e32 v88, v89, v91
	v_add_f32_e32 v88, v92, v88
	s_waitcnt vmcnt(15)
	v_permlane16_swap_b32_e32 v176, v178
	v_permlane16_swap_b32_e32 v177, v179
	v_lshlrev_b32_e32 v100, 16, v176
	v_and_b32_e32 v101, 0xffff0000, v176
	v_lshlrev_b32_e32 v102, 16, v177
	v_and_b32_e32 v103, 0xffff0000, v177
	v_pk_add_f32 v[86:87], v[86:87], v[102:103]
	v_pk_add_f32 v[84:85], v[84:85], v[100:101]
	s_nop 0
	v_cvt_pk_bf16_f32 v100, v84, v85
	v_cvt_pk_bf16_f32 v101, v86, v87
	v_mul_f32_e32 v85, v85, v85
	v_mul_f32_e32 v87, v87, v87
	v_fmac_f32_e32 v85, v84, v84
	v_fmac_f32_e32 v87, v86, v86
	v_add_f32_e32 v84, v85, v87
	v_add_f32_e32 v88, v88, v84
	v_mov_b32_e32 v228, v100
	v_mov_b32_e32 v229, v101
	s_waitcnt vmcnt(15)
	v_lshlrev_b32_e32 v84, 16, v178
	v_and_b32_e32 v85, 0xffff0000, v178
	v_lshlrev_b32_e32 v86, 16, v179
	v_and_b32_e32 v87, 0xffff0000, v179
	v_pk_add_f32 v[82:83], v[82:83], v[86:87]
	v_pk_add_f32 v[80:81], v[80:81], v[84:85]
	v_mul_f32_e32 v85, v83, v83
	v_mul_f32_e32 v84, v81, v81
	v_fmac_f32_e32 v84, v80, v80
	v_fmac_f32_e32 v85, v82, v82
	v_add_f32_e32 v84, v84, v85
	v_add_f32_e32 v84, v88, v84
	ds_swizzle_b32 v85, v84 offset:swizzle(SWAP,16)
	v_cvt_pk_bf16_f32 v80, v80, v81
	v_cvt_pk_bf16_f32 v81, v82, v83
	v_mov_b32_e32 v230, v80
	v_mov_b32_e32 v231, v81
	v_lshl_add_u64 v[234:235], v[98:99], 0, v[232:233]
	s_nop 0
	v_permlane16_swap_b32_e32 v228, v230
	v_permlane16_swap_b32_e32 v229, v231
	global_store_dwordx4 v[234:235], v[228:231], off offset:256
	s_waitcnt lgkmcnt(0)
	v_add_f32_e32 v80, v84, v85
	v_mov_b32_e32 v81, v80
	s_nop 1
	v_permlane32_swap_b32_e32 v80, v81
	s_and_saveexec_b64 s[28:29], s[4:5]
	s_cbranch_execz .LBB0_2267
	v_add_f32_e32 v82, v80, v81
	v_lshlrev_b64 v[80:81], 6, v[96:97]
	v_lshl_add_u64 v[80:81], s[2:3], 0, v[80:81]
	v_lshl_add_u64 v[80:81], s[26:27], 2, v[80:81]
	s_lshl_b32 s10, s48, 2
	v_lshl_add_u64 v[80:81], v[80:81], 0, s[10:11]
	global_store_dword v[80:81], v82, off
.LBB0_2267:
	s_or_b64 exec, exec, s[28:29]
	v_or_b32_e32 v80, 48, v142
	v_ashrrev_i32_e32 v81, 31, v80
	v_lshlrev_b64 v[82:83], 11, v[80:81]
	v_lshl_add_u64 v[82:83], s[8:9], 0, v[82:83]
	v_lshl_add_u64 v[82:83], v[140:141], 1, v[82:83]
	s_waitcnt vmcnt(15)
	v_permlane16_swap_b32_e32 v180, v182
	v_permlane16_swap_b32_e32 v181, v183
	v_lshlrev_b32_e32 v86, 16, v180
	v_and_b32_e32 v87, 0xffff0000, v180
	v_lshlrev_b32_e32 v84, 16, v181
	v_and_b32_e32 v85, 0xffff0000, v181
	v_pk_add_f32 v[78:79], v[78:79], v[84:85]
	v_pk_add_f32 v[76:77], v[76:77], v[86:87]
	s_nop 0
	v_cvt_pk_bf16_f32 v84, v76, v77
	v_cvt_pk_bf16_f32 v85, v78, v79
	v_mul_f32_e32 v77, v77, v77
	v_mov_b32_e32 v224, v84
	v_mov_b32_e32 v225, v85
	v_mul_f32_e32 v79, v79, v79
	v_fmac_f32_e32 v77, v76, v76
	v_fmac_f32_e32 v79, v78, v78
	v_add_f32_e32 v76, v77, v79
	s_waitcnt vmcnt(15)
	v_lshlrev_b32_e32 v84, 16, v182
	v_and_b32_e32 v85, 0xffff0000, v182
	v_lshlrev_b32_e32 v86, 16, v183
	v_and_b32_e32 v87, 0xffff0000, v183
	v_pk_add_f32 v[74:75], v[74:75], v[86:87]
	v_pk_add_f32 v[72:73], v[72:73], v[84:85]
	s_nop 0
	v_cvt_pk_bf16_f32 v84, v72, v73
	v_cvt_pk_bf16_f32 v85, v74, v75
	v_mul_f32_e32 v73, v73, v73
	v_mov_b32_e32 v226, v84
	v_mov_b32_e32 v227, v85
	v_lshl_add_u64 v[234:235], v[82:83], 0, v[232:233]
	s_nop 0
	v_permlane16_swap_b32_e32 v224, v226
	v_permlane16_swap_b32_e32 v225, v227
	global_store_dwordx4 v[234:235], v[224:227], off
	v_mul_f32_e32 v75, v75, v75
	v_fmac_f32_e32 v73, v72, v72
	v_fmac_f32_e32 v75, v74, v74
	v_add_f32_e32 v72, v73, v75
	v_add_f32_e32 v72, v76, v72
	s_waitcnt vmcnt(15)
	v_permlane16_swap_b32_e32 v184, v186
	v_permlane16_swap_b32_e32 v185, v187
	v_lshlrev_b32_e32 v84, 16, v184
	v_and_b32_e32 v85, 0xffff0000, v184
	v_lshlrev_b32_e32 v86, 16, v185
	v_and_b32_e32 v87, 0xffff0000, v185
	v_pk_add_f32 v[70:71], v[70:71], v[86:87]
	v_pk_add_f32 v[68:69], v[68:69], v[84:85]
	s_nop 0
	v_cvt_pk_bf16_f32 v84, v68, v69
	v_cvt_pk_bf16_f32 v85, v70, v71
	v_mul_f32_e32 v69, v69, v69
	v_mul_f32_e32 v71, v71, v71
	v_fmac_f32_e32 v69, v68, v68
	v_fmac_f32_e32 v71, v70, v70
	v_add_f32_e32 v68, v69, v71
	v_add_f32_e32 v72, v72, v68
	v_mov_b32_e32 v228, v84
	v_mov_b32_e32 v229, v85
	s_waitcnt vmcnt(15)
	v_lshlrev_b32_e32 v68, 16, v186
	v_and_b32_e32 v69, 0xffff0000, v186
	v_lshlrev_b32_e32 v70, 16, v187
	v_and_b32_e32 v71, 0xffff0000, v187
	v_pk_add_f32 v[66:67], v[66:67], v[70:71]
	v_pk_add_f32 v[64:65], v[64:65], v[68:69]
	v_mul_f32_e32 v69, v67, v67
	v_mul_f32_e32 v68, v65, v65
	v_fmac_f32_e32 v68, v64, v64
	v_fmac_f32_e32 v69, v66, v66
	v_add_f32_e32 v68, v68, v69
	v_add_f32_e32 v68, v72, v68
	ds_swizzle_b32 v69, v68 offset:swizzle(SWAP,16)
	v_cvt_pk_bf16_f32 v64, v64, v65
	v_cvt_pk_bf16_f32 v65, v66, v67
	v_mov_b32_e32 v230, v64
	v_mov_b32_e32 v231, v65
	v_lshl_add_u64 v[234:235], v[82:83], 0, v[232:233]
	s_nop 0
	v_permlane16_swap_b32_e32 v228, v230
	v_permlane16_swap_b32_e32 v229, v231
	global_store_dwordx4 v[234:235], v[228:231], off offset:256
	s_waitcnt lgkmcnt(0)
	v_add_f32_e32 v64, v68, v69
	v_mov_b32_e32 v65, v64
	s_nop 1
	v_permlane32_swap_b32_e32 v64, v65
	s_and_saveexec_b64 s[28:29], s[4:5]
	s_cbranch_execz .LBB0_2269
	v_add_f32_e32 v66, v64, v65
	v_lshlrev_b64 v[64:65], 6, v[80:81]
	v_lshl_add_u64 v[64:65], s[2:3], 0, v[64:65]
	v_lshl_add_u64 v[64:65], s[26:27], 2, v[64:65]
	s_lshl_b32 s10, s48, 2
	v_lshl_add_u64 v[64:65], v[64:65], 0, s[10:11]
	global_store_dword v[64:65], v66, off
.LBB0_2269:
	s_or_b64 exec, exec, s[28:29]
	v_add_u32_e32 v64, 0x80, v142
	v_ashrrev_i32_e32 v65, 31, v64
	v_lshlrev_b64 v[66:67], 11, v[64:65]
	v_lshl_add_u64 v[66:67], s[8:9], 0, v[66:67]
	v_lshl_add_u64 v[66:67], v[140:141], 1, v[66:67]
	s_waitcnt vmcnt(15)
	v_permlane16_swap_b32_e32 v188, v190
	v_permlane16_swap_b32_e32 v189, v191
	v_lshlrev_b32_e32 v70, 16, v188
	v_and_b32_e32 v71, 0xffff0000, v188
	v_lshlrev_b32_e32 v68, 16, v189
	v_and_b32_e32 v69, 0xffff0000, v189
	v_pk_add_f32 v[62:63], v[62:63], v[68:69]
	v_pk_add_f32 v[60:61], v[60:61], v[70:71]
	s_nop 0
	v_cvt_pk_bf16_f32 v68, v60, v61
	v_cvt_pk_bf16_f32 v69, v62, v63
	v_mul_f32_e32 v61, v61, v61
	v_mov_b32_e32 v224, v68
	v_mov_b32_e32 v225, v69
	v_mul_f32_e32 v63, v63, v63
	v_fmac_f32_e32 v61, v60, v60
	v_fmac_f32_e32 v63, v62, v62
	v_add_f32_e32 v60, v61, v63
	s_waitcnt vmcnt(15)
	v_lshlrev_b32_e32 v68, 16, v190
	v_and_b32_e32 v69, 0xffff0000, v190
	v_lshlrev_b32_e32 v70, 16, v191
	v_and_b32_e32 v71, 0xffff0000, v191
	v_pk_add_f32 v[58:59], v[58:59], v[70:71]
	v_pk_add_f32 v[56:57], v[56:57], v[68:69]
	s_nop 0
	v_cvt_pk_bf16_f32 v68, v56, v57
	v_cvt_pk_bf16_f32 v69, v58, v59
	v_mul_f32_e32 v57, v57, v57
	v_mov_b32_e32 v226, v68
	v_mov_b32_e32 v227, v69
	v_lshl_add_u64 v[234:235], v[66:67], 0, v[232:233]
	s_nop 0
	v_permlane16_swap_b32_e32 v224, v226
	v_permlane16_swap_b32_e32 v225, v227
	global_store_dwordx4 v[234:235], v[224:227], off
	v_mul_f32_e32 v59, v59, v59
	v_fmac_f32_e32 v57, v56, v56
	v_fmac_f32_e32 v59, v58, v58
	v_add_f32_e32 v56, v57, v59
	v_add_f32_e32 v56, v60, v56
	s_waitcnt vmcnt(15)
	v_permlane16_swap_b32_e32 v192, v194
	v_permlane16_swap_b32_e32 v193, v195
	v_lshlrev_b32_e32 v68, 16, v192
	v_and_b32_e32 v69, 0xffff0000, v192
	v_lshlrev_b32_e32 v70, 16, v193
	v_and_b32_e32 v71, 0xffff0000, v193
	v_pk_add_f32 v[54:55], v[54:55], v[70:71]
	v_pk_add_f32 v[52:53], v[52:53], v[68:69]
	s_nop 0
	v_cvt_pk_bf16_f32 v68, v52, v53
	v_cvt_pk_bf16_f32 v69, v54, v55
	v_mul_f32_e32 v53, v53, v53
	v_mul_f32_e32 v55, v55, v55
	v_fmac_f32_e32 v53, v52, v52
	v_fmac_f32_e32 v55, v54, v54
	v_add_f32_e32 v52, v53, v55
	v_add_f32_e32 v56, v56, v52
	v_mov_b32_e32 v228, v68
	v_mov_b32_e32 v229, v69
	s_waitcnt vmcnt(15)
	v_lshlrev_b32_e32 v52, 16, v194
	v_and_b32_e32 v53, 0xffff0000, v194
	v_lshlrev_b32_e32 v54, 16, v195
	v_and_b32_e32 v55, 0xffff0000, v195
	v_pk_add_f32 v[50:51], v[50:51], v[54:55]
	v_pk_add_f32 v[48:49], v[48:49], v[52:53]
	v_mul_f32_e32 v53, v51, v51
	v_mul_f32_e32 v52, v49, v49
	v_fmac_f32_e32 v52, v48, v48
	v_fmac_f32_e32 v53, v50, v50
	v_add_f32_e32 v52, v52, v53
	v_add_f32_e32 v52, v56, v52
	ds_swizzle_b32 v53, v52 offset:swizzle(SWAP,16)
	v_cvt_pk_bf16_f32 v48, v48, v49
	v_cvt_pk_bf16_f32 v49, v50, v51
	v_mov_b32_e32 v230, v48
	v_mov_b32_e32 v231, v49
	v_lshl_add_u64 v[234:235], v[66:67], 0, v[232:233]
	s_nop 0
	v_permlane16_swap_b32_e32 v228, v230
	v_permlane16_swap_b32_e32 v229, v231
	global_store_dwordx4 v[234:235], v[228:231], off offset:256
	s_waitcnt lgkmcnt(0)
	v_add_f32_e32 v48, v52, v53
	v_mov_b32_e32 v49, v48
	s_nop 1
	v_permlane32_swap_b32_e32 v48, v49
	s_and_saveexec_b64 s[28:29], s[4:5]
	s_cbranch_execz .LBB0_2271
	v_add_f32_e32 v50, v48, v49
	v_lshlrev_b64 v[48:49], 6, v[64:65]
	v_lshl_add_u64 v[48:49], s[2:3], 0, v[48:49]
	v_lshl_add_u64 v[48:49], s[26:27], 2, v[48:49]
	s_lshl_b32 s10, s48, 2
	v_lshl_add_u64 v[48:49], v[48:49], 0, s[10:11]
	global_store_dword v[48:49], v50, off
.LBB0_2271:
	s_or_b64 exec, exec, s[28:29]
	v_add_u32_e32 v48, 0x90, v142
	v_ashrrev_i32_e32 v49, 31, v48
	v_lshlrev_b64 v[50:51], 11, v[48:49]
	v_lshl_add_u64 v[50:51], s[8:9], 0, v[50:51]
	v_lshl_add_u64 v[50:51], v[140:141], 1, v[50:51]
	s_waitcnt vmcnt(15)
	v_permlane16_swap_b32_e32 v196, v198
	v_permlane16_swap_b32_e32 v197, v199
	v_lshlrev_b32_e32 v54, 16, v196
	v_and_b32_e32 v55, 0xffff0000, v196
	v_lshlrev_b32_e32 v52, 16, v197
	v_and_b32_e32 v53, 0xffff0000, v197
	v_pk_add_f32 v[46:47], v[46:47], v[52:53]
	v_pk_add_f32 v[44:45], v[44:45], v[54:55]
	s_nop 0
	v_cvt_pk_bf16_f32 v52, v44, v45
	v_cvt_pk_bf16_f32 v53, v46, v47
	v_mul_f32_e32 v45, v45, v45
	v_mov_b32_e32 v224, v52
	v_mov_b32_e32 v225, v53
	v_mul_f32_e32 v47, v47, v47
	v_fmac_f32_e32 v45, v44, v44
	v_fmac_f32_e32 v47, v46, v46
	v_add_f32_e32 v44, v45, v47
	s_waitcnt vmcnt(15)
	v_lshlrev_b32_e32 v52, 16, v198
	v_and_b32_e32 v53, 0xffff0000, v198
	v_lshlrev_b32_e32 v54, 16, v199
	v_and_b32_e32 v55, 0xffff0000, v199
	v_pk_add_f32 v[42:43], v[42:43], v[54:55]
	v_pk_add_f32 v[40:41], v[40:41], v[52:53]
	s_nop 0
	v_cvt_pk_bf16_f32 v52, v40, v41
	v_cvt_pk_bf16_f32 v53, v42, v43
	v_mul_f32_e32 v41, v41, v41
	v_mov_b32_e32 v226, v52
	v_mov_b32_e32 v227, v53
	v_lshl_add_u64 v[234:235], v[50:51], 0, v[232:233]
	s_nop 0
	v_permlane16_swap_b32_e32 v224, v226
	v_permlane16_swap_b32_e32 v225, v227
	global_store_dwordx4 v[234:235], v[224:227], off
	v_mul_f32_e32 v43, v43, v43
	v_fmac_f32_e32 v41, v40, v40
	v_fmac_f32_e32 v43, v42, v42
	v_add_f32_e32 v40, v41, v43
	v_add_f32_e32 v40, v44, v40
	s_waitcnt vmcnt(15)
	v_permlane16_swap_b32_e32 v200, v202
	v_permlane16_swap_b32_e32 v201, v203
	v_lshlrev_b32_e32 v52, 16, v200
	v_and_b32_e32 v53, 0xffff0000, v200
	v_lshlrev_b32_e32 v54, 16, v201
	v_and_b32_e32 v55, 0xffff0000, v201
	v_pk_add_f32 v[38:39], v[38:39], v[54:55]
	v_pk_add_f32 v[36:37], v[36:37], v[52:53]
	s_nop 0
	v_cvt_pk_bf16_f32 v52, v36, v37
	v_cvt_pk_bf16_f32 v53, v38, v39
	v_mul_f32_e32 v37, v37, v37
	v_mul_f32_e32 v39, v39, v39
	v_fmac_f32_e32 v37, v36, v36
	v_fmac_f32_e32 v39, v38, v38
	v_add_f32_e32 v36, v37, v39
	v_add_f32_e32 v40, v40, v36
	v_mov_b32_e32 v228, v52
	v_mov_b32_e32 v229, v53
	s_waitcnt vmcnt(15)
	v_lshlrev_b32_e32 v36, 16, v202
	v_and_b32_e32 v37, 0xffff0000, v202
	v_lshlrev_b32_e32 v38, 16, v203
	v_and_b32_e32 v39, 0xffff0000, v203
	v_pk_add_f32 v[34:35], v[34:35], v[38:39]
	v_pk_add_f32 v[32:33], v[32:33], v[36:37]
	v_mul_f32_e32 v37, v35, v35
	v_mul_f32_e32 v36, v33, v33
	v_fmac_f32_e32 v36, v32, v32
	v_fmac_f32_e32 v37, v34, v34
	v_add_f32_e32 v36, v36, v37
	v_add_f32_e32 v36, v40, v36
	ds_swizzle_b32 v37, v36 offset:swizzle(SWAP,16)
	v_cvt_pk_bf16_f32 v32, v32, v33
	v_cvt_pk_bf16_f32 v33, v34, v35
	v_mov_b32_e32 v230, v32
	v_mov_b32_e32 v231, v33
	v_lshl_add_u64 v[234:235], v[50:51], 0, v[232:233]
	s_nop 0
	v_permlane16_swap_b32_e32 v228, v230
	v_permlane16_swap_b32_e32 v229, v231
	global_store_dwordx4 v[234:235], v[228:231], off offset:256
	s_waitcnt lgkmcnt(0)
	v_add_f32_e32 v32, v36, v37
	v_mov_b32_e32 v33, v32
	s_nop 1
	v_permlane32_swap_b32_e32 v32, v33
	s_and_saveexec_b64 s[28:29], s[4:5]
	s_cbranch_execz .LBB0_2273
	v_add_f32_e32 v34, v32, v33
	v_lshlrev_b64 v[32:33], 6, v[48:49]
	v_lshl_add_u64 v[32:33], s[2:3], 0, v[32:33]
	v_lshl_add_u64 v[32:33], s[26:27], 2, v[32:33]
	s_lshl_b32 s10, s48, 2
	v_lshl_add_u64 v[32:33], v[32:33], 0, s[10:11]
	global_store_dword v[32:33], v34, off
.LBB0_2273:
	s_or_b64 exec, exec, s[28:29]
	v_add_u32_e32 v32, 0xa0, v142
	v_ashrrev_i32_e32 v33, 31, v32
	v_lshlrev_b64 v[34:35], 11, v[32:33]
	v_lshl_add_u64 v[34:35], s[8:9], 0, v[34:35]
	v_lshl_add_u64 v[34:35], v[140:141], 1, v[34:35]
	s_waitcnt vmcnt(15)
	v_permlane16_swap_b32_e32 v208, v210
	v_permlane16_swap_b32_e32 v209, v211
	v_lshlrev_b32_e32 v38, 16, v208
	v_and_b32_e32 v39, 0xffff0000, v208
	v_lshlrev_b32_e32 v36, 16, v209
	v_and_b32_e32 v37, 0xffff0000, v209
	v_pk_add_f32 v[30:31], v[30:31], v[36:37]
	v_pk_add_f32 v[28:29], v[28:29], v[38:39]
	s_nop 0
	v_cvt_pk_bf16_f32 v36, v28, v29
	v_cvt_pk_bf16_f32 v37, v30, v31
	v_mul_f32_e32 v29, v29, v29
	v_mov_b32_e32 v224, v36
	v_mov_b32_e32 v225, v37
	v_mul_f32_e32 v31, v31, v31
	v_fmac_f32_e32 v29, v28, v28
	v_fmac_f32_e32 v31, v30, v30
	v_add_f32_e32 v28, v29, v31
	s_waitcnt vmcnt(15)
	v_lshlrev_b32_e32 v36, 16, v210
	v_and_b32_e32 v37, 0xffff0000, v210
	v_lshlrev_b32_e32 v38, 16, v211
	v_and_b32_e32 v39, 0xffff0000, v211
	v_pk_add_f32 v[26:27], v[26:27], v[38:39]
	v_pk_add_f32 v[24:25], v[24:25], v[36:37]
	s_nop 0
	v_cvt_pk_bf16_f32 v36, v24, v25
	v_cvt_pk_bf16_f32 v37, v26, v27
	v_mul_f32_e32 v25, v25, v25
	v_mov_b32_e32 v226, v36
	v_mov_b32_e32 v227, v37
	v_lshl_add_u64 v[234:235], v[34:35], 0, v[232:233]
	s_nop 0
	v_permlane16_swap_b32_e32 v224, v226
	v_permlane16_swap_b32_e32 v225, v227
	global_store_dwordx4 v[234:235], v[224:227], off
	v_mul_f32_e32 v27, v27, v27
	v_fmac_f32_e32 v25, v24, v24
	v_fmac_f32_e32 v27, v26, v26
	v_add_f32_e32 v24, v25, v27
	v_add_f32_e32 v24, v28, v24
	s_waitcnt vmcnt(15)
	v_permlane16_swap_b32_e32 v212, v214
	v_permlane16_swap_b32_e32 v213, v215
	v_lshlrev_b32_e32 v36, 16, v212
	v_and_b32_e32 v37, 0xffff0000, v212
	v_lshlrev_b32_e32 v38, 16, v213
	v_and_b32_e32 v39, 0xffff0000, v213
	v_pk_add_f32 v[22:23], v[22:23], v[38:39]
	v_pk_add_f32 v[20:21], v[20:21], v[36:37]
	s_nop 0
	v_cvt_pk_bf16_f32 v36, v20, v21
	v_cvt_pk_bf16_f32 v37, v22, v23
	v_mul_f32_e32 v21, v21, v21
	v_mul_f32_e32 v23, v23, v23
	v_fmac_f32_e32 v21, v20, v20
	v_fmac_f32_e32 v23, v22, v22
	v_add_f32_e32 v20, v21, v23
	v_add_f32_e32 v24, v24, v20
	v_mov_b32_e32 v228, v36
	v_mov_b32_e32 v229, v37
	s_waitcnt vmcnt(15)
	v_lshlrev_b32_e32 v20, 16, v214
	v_and_b32_e32 v21, 0xffff0000, v214
	v_lshlrev_b32_e32 v22, 16, v215
	v_and_b32_e32 v23, 0xffff0000, v215
	v_pk_add_f32 v[18:19], v[18:19], v[22:23]
	v_pk_add_f32 v[16:17], v[16:17], v[20:21]
	v_mul_f32_e32 v21, v19, v19
	v_mul_f32_e32 v20, v17, v17
	v_fmac_f32_e32 v20, v16, v16
	v_fmac_f32_e32 v21, v18, v18
	v_add_f32_e32 v20, v20, v21
	v_add_f32_e32 v20, v24, v20
	ds_swizzle_b32 v21, v20 offset:swizzle(SWAP,16)
	v_cvt_pk_bf16_f32 v16, v16, v17
	v_cvt_pk_bf16_f32 v17, v18, v19
	v_mov_b32_e32 v230, v16
	v_mov_b32_e32 v231, v17
	v_lshl_add_u64 v[234:235], v[34:35], 0, v[232:233]
	s_nop 0
	v_permlane16_swap_b32_e32 v228, v230
	v_permlane16_swap_b32_e32 v229, v231
	global_store_dwordx4 v[234:235], v[228:231], off offset:256
	s_waitcnt lgkmcnt(0)
	v_add_f32_e32 v16, v20, v21
	v_mov_b32_e32 v17, v16
	s_nop 1
	v_permlane32_swap_b32_e32 v16, v17
	s_and_saveexec_b64 s[28:29], s[4:5]
	s_cbranch_execz .LBB0_2275
	v_add_f32_e32 v18, v16, v17
	v_lshlrev_b64 v[16:17], 6, v[32:33]
	v_lshl_add_u64 v[16:17], s[2:3], 0, v[16:17]
	v_lshl_add_u64 v[16:17], s[26:27], 2, v[16:17]
	s_lshl_b32 s10, s48, 2
	v_lshl_add_u64 v[16:17], v[16:17], 0, s[10:11]
	global_store_dword v[16:17], v18, off
.LBB0_2275:
	s_or_b64 exec, exec, s[28:29]
	v_add_u32_e32 v16, 0xb0, v142
	v_ashrrev_i32_e32 v17, 31, v16
	v_lshlrev_b64 v[18:19], 11, v[16:17]
	v_lshl_add_u64 v[18:19], s[8:9], 0, v[18:19]
	v_lshl_add_u64 v[18:19], v[140:141], 1, v[18:19]
	s_waitcnt vmcnt(15)
	v_permlane16_swap_b32_e32 v216, v218
	v_permlane16_swap_b32_e32 v217, v219
	v_lshlrev_b32_e32 v22, 16, v216
	v_and_b32_e32 v23, 0xffff0000, v216
	v_lshlrev_b32_e32 v20, 16, v217
	v_and_b32_e32 v21, 0xffff0000, v217
	v_pk_add_f32 v[14:15], v[14:15], v[20:21]
	v_pk_add_f32 v[12:13], v[12:13], v[22:23]
	s_nop 0
	v_cvt_pk_bf16_f32 v20, v12, v13
	v_cvt_pk_bf16_f32 v21, v14, v15
	v_mul_f32_e32 v13, v13, v13
	v_mov_b32_e32 v224, v20
	v_mov_b32_e32 v225, v21
	v_mul_f32_e32 v15, v15, v15
	v_fmac_f32_e32 v13, v12, v12
	v_fmac_f32_e32 v15, v14, v14
	v_add_f32_e32 v12, v13, v15
	s_waitcnt vmcnt(15)
	v_lshlrev_b32_e32 v20, 16, v218
	v_and_b32_e32 v21, 0xffff0000, v218
	v_lshlrev_b32_e32 v22, 16, v219
	v_and_b32_e32 v23, 0xffff0000, v219
	v_pk_add_f32 v[10:11], v[10:11], v[22:23]
	v_pk_add_f32 v[8:9], v[8:9], v[20:21]
	s_nop 0
	v_cvt_pk_bf16_f32 v20, v8, v9
	v_cvt_pk_bf16_f32 v21, v10, v11
	v_mul_f32_e32 v9, v9, v9
	v_mov_b32_e32 v226, v20
	v_mov_b32_e32 v227, v21
	v_lshl_add_u64 v[234:235], v[18:19], 0, v[232:233]
	s_nop 0
	v_permlane16_swap_b32_e32 v224, v226
	v_permlane16_swap_b32_e32 v225, v227
	global_store_dwordx4 v[234:235], v[224:227], off
	v_mul_f32_e32 v11, v11, v11
	v_fmac_f32_e32 v9, v8, v8
	v_fmac_f32_e32 v11, v10, v10
	v_add_f32_e32 v8, v9, v11
	v_add_f32_e32 v8, v12, v8
	s_waitcnt vmcnt(15)
	v_permlane16_swap_b32_e32 v220, v222
	v_permlane16_swap_b32_e32 v221, v223
	v_lshlrev_b32_e32 v20, 16, v220
	v_and_b32_e32 v21, 0xffff0000, v220
	v_lshlrev_b32_e32 v22, 16, v221
	v_and_b32_e32 v23, 0xffff0000, v221
	v_pk_add_f32 v[6:7], v[6:7], v[22:23]
	v_pk_add_f32 v[4:5], v[4:5], v[20:21]
	s_nop 0
	v_cvt_pk_bf16_f32 v20, v4, v5
	v_cvt_pk_bf16_f32 v21, v6, v7
	v_mul_f32_e32 v5, v5, v5
	v_mul_f32_e32 v7, v7, v7
	v_fmac_f32_e32 v5, v4, v4
	v_fmac_f32_e32 v7, v6, v6
	v_add_f32_e32 v4, v5, v7
	v_add_f32_e32 v8, v8, v4
	v_mov_b32_e32 v228, v20
	v_mov_b32_e32 v229, v21
	s_waitcnt vmcnt(15)
	v_lshlrev_b32_e32 v4, 16, v222
	v_and_b32_e32 v5, 0xffff0000, v222
	v_lshlrev_b32_e32 v6, 16, v223
	v_and_b32_e32 v7, 0xffff0000, v223
	v_pk_add_f32 v[2:3], v[2:3], v[6:7]
	v_pk_add_f32 v[0:1], v[0:1], v[4:5]
	v_mul_f32_e32 v5, v3, v3
	v_mul_f32_e32 v4, v1, v1
	v_fmac_f32_e32 v4, v0, v0
	v_fmac_f32_e32 v5, v2, v2
	v_add_f32_e32 v4, v4, v5
	v_add_f32_e32 v4, v8, v4
	ds_swizzle_b32 v5, v4 offset:swizzle(SWAP,16)
	v_cvt_pk_bf16_f32 v0, v0, v1
	v_cvt_pk_bf16_f32 v1, v2, v3
	v_mov_b32_e32 v230, v0
	v_mov_b32_e32 v231, v1
	v_lshl_add_u64 v[234:235], v[18:19], 0, v[232:233]
	s_nop 0
	v_permlane16_swap_b32_e32 v228, v230
	v_permlane16_swap_b32_e32 v229, v231
	global_store_dwordx4 v[234:235], v[228:231], off offset:256
	s_waitcnt lgkmcnt(0)
	v_add_f32_e32 v0, v4, v5
	v_mov_b32_e32 v1, v0
	s_nop 1
	v_permlane32_swap_b32_e32 v0, v1
	s_and_saveexec_b64 s[28:29], s[4:5]
	s_cbranch_execz .LBB0_2277
	v_add_f32_e32 v2, v0, v1
	v_lshlrev_b64 v[0:1], 6, v[16:17]
	v_lshl_add_u64 v[0:1], s[2:3], 0, v[0:1]
	v_lshl_add_u64 v[0:1], s[26:27], 2, v[0:1]
	s_lshl_b32 s10, s48, 2
	v_lshl_add_u64 v[0:1], v[0:1], 0, s[10:11]
	global_store_dword v[0:1], v2, off

.LBB0_2755:
	v_lshl_add_u32 v142, s26, 8, v144
	v_ashrrev_i32_e32 v143, 31, v142
	v_lshl_or_b32 v140, s2, 8, v146
	v_lshlrev_b64 v[150:151], 11, v[142:143]
	v_ashrrev_i32_e32 v141, 31, v140
	v_lshl_add_u64 v[150:151], s[8:9], 0, v[150:151]
	v_lshl_add_u64 v[150:151], v[140:141], 1, v[150:151]
	s_mov_b64 s[98:99], 0x8000
	s_mov_b64 s[100:101], 0x28000
	v_bfe_u32 v232, v206, 4, 1
	v_mul_u32_u24_e32 v232, 24, v232
	v_mov_b32_e32 v233, 0
	v_lshl_add_u64 v[234:235], v[150:151], 0, v[232:233]
	global_load_dwordx4 v[156:159], v[234:235], off
	global_load_dwordx4 v[160:163], v[234:235], off offset:256
	v_lshl_add_u64 v[234:235], v[234:235], 0, s[98:99]
	global_load_dwordx4 v[164:167], v[234:235], off
	global_load_dwordx4 v[168:171], v[234:235], off offset:256
	v_lshl_add_u64 v[234:235], v[234:235], 0, s[98:99]
	global_load_dwordx4 v[172:175], v[234:235], off
	global_load_dwordx4 v[176:179], v[234:235], off offset:256
	v_lshl_add_u64 v[234:235], v[234:235], 0, s[98:99]
	global_load_dwordx4 v[180:183], v[234:235], off
	global_load_dwordx4 v[184:187], v[234:235], off offset:256
	v_lshl_add_u64 v[234:235], v[234:235], 0, s[100:101]
	global_load_dwordx4 v[188:191], v[234:235], off
	global_load_dwordx4 v[192:195], v[234:235], off offset:256
	v_lshl_add_u64 v[234:235], v[234:235], 0, s[98:99]
	global_load_dwordx4 v[196:199], v[234:235], off
	global_load_dwordx4 v[200:203], v[234:235], off offset:256
	v_lshl_add_u64 v[234:235], v[234:235], 0, s[98:99]
	global_load_dwordx4 v[208:211], v[234:235], off
	global_load_dwordx4 v[212:215], v[234:235], off offset:256
	v_lshl_add_u64 v[234:235], v[234:235], 0, s[98:99]
	global_load_dwordx4 v[216:219], v[234:235], off
	global_load_dwordx4 v[220:223], v[234:235], off offset:256
	s_lshl_b32 s26, s2, 2
	s_ashr_i32 s27, s26, 31
	s_waitcnt vmcnt(15)
	v_permlane16_swap_b32_e32 v156, v158
	v_permlane16_swap_b32_e32 v157, v159
	v_lshlrev_b32_e32 v154, 16, v156
	v_and_b32_e32 v155, 0xffff0000, v156
	v_lshlrev_b32_e32 v152, 16, v157
	v_and_b32_e32 v153, 0xffff0000, v157
	v_pk_add_f32 v[126:127], v[126:127], v[152:153]
	v_pk_add_f32 v[124:125], v[124:125], v[154:155]
	s_nop 0
	v_cvt_pk_bf16_f32 v152, v124, v125
	v_cvt_pk_bf16_f32 v153, v126, v127
	v_mul_f32_e32 v125, v125, v125
	v_mov_b32_e32 v224, v152
	v_mov_b32_e32 v225, v153
	v_mul_f32_e32 v127, v127, v127
	v_fmac_f32_e32 v125, v124, v124
	v_fmac_f32_e32 v127, v126, v126
	v_add_f32_e32 v124, v125, v127
	s_waitcnt vmcnt(15)
	v_lshlrev_b32_e32 v152, 16, v158
	v_and_b32_e32 v153, 0xffff0000, v158
	v_lshlrev_b32_e32 v154, 16, v159
	v_and_b32_e32 v155, 0xffff0000, v159
	v_pk_add_f32 v[122:123], v[122:123], v[154:155]
	v_pk_add_f32 v[120:121], v[120:121], v[152:153]
	s_nop 0
	v_cvt_pk_bf16_f32 v152, v120, v121
	v_cvt_pk_bf16_f32 v153, v122, v123
	v_mul_f32_e32 v121, v121, v121
	v_mov_b32_e32 v226, v152
	v_mov_b32_e32 v227, v153
	v_lshl_add_u64 v[234:235], v[150:151], 0, v[232:233]
	s_nop 0
	v_permlane16_swap_b32_e32 v224, v226
	v_permlane16_swap_b32_e32 v225, v227
	global_store_dwordx4 v[234:235], v[224:227], off
	v_mul_f32_e32 v123, v123, v123
	v_fmac_f32_e32 v121, v120, v120
	v_fmac_f32_e32 v123, v122, v122
	v_add_f32_e32 v120, v121, v123
	v_add_f32_e32 v120, v124, v120
	s_waitcnt vmcnt(15)
	v_permlane16_swap_b32_e32 v160, v162
	v_permlane16_swap_b32_e32 v161, v163
	v_lshlrev_b32_e32 v152, 16, v160
	v_and_b32_e32 v153, 0xffff0000, v160
	v_lshlrev_b32_e32 v154, 16, v161
	v_and_b32_e32 v155, 0xffff0000, v161
	v_pk_add_f32 v[118:119], v[118:119], v[154:155]
	v_pk_add_f32 v[116:117], v[116:117], v[152:153]
	s_nop 0
	v_cvt_pk_bf16_f32 v152, v116, v117
	v_cvt_pk_bf16_f32 v153, v118, v119
	v_mul_f32_e32 v117, v117, v117
	v_mul_f32_e32 v119, v119, v119
	v_fmac_f32_e32 v117, v116, v116
	v_fmac_f32_e32 v119, v118, v118
	v_add_f32_e32 v116, v117, v119
	v_add_f32_e32 v120, v120, v116
	v_mov_b32_e32 v228, v152
	v_mov_b32_e32 v229, v153
	s_waitcnt vmcnt(15)
	v_lshlrev_b32_e32 v116, 16, v162
	v_and_b32_e32 v117, 0xffff0000, v162
	v_lshlrev_b32_e32 v118, 16, v163
	v_and_b32_e32 v119, 0xffff0000, v163
	v_pk_add_f32 v[114:115], v[114:115], v[118:119]
	v_pk_add_f32 v[112:113], v[112:113], v[116:117]
	v_mul_f32_e32 v117, v115, v115
	v_mul_f32_e32 v116, v113, v113
	v_fmac_f32_e32 v116, v112, v112
	v_fmac_f32_e32 v117, v114, v114
	v_add_f32_e32 v116, v116, v117
	v_add_f32_e32 v116, v120, v116
	ds_swizzle_b32 v117, v116 offset:swizzle(SWAP,16)
	v_cvt_pk_bf16_f32 v112, v112, v113
	v_cvt_pk_bf16_f32 v113, v114, v115
	v_mov_b32_e32 v230, v112
	v_mov_b32_e32 v231, v113
	v_lshl_add_u64 v[234:235], v[150:151], 0, v[232:233]
	s_nop 0
	v_permlane16_swap_b32_e32 v228, v230
	v_permlane16_swap_b32_e32 v229, v231
	global_store_dwordx4 v[234:235], v[228:231], off offset:256
	s_waitcnt lgkmcnt(0)
	v_add_f32_e32 v112, v116, v117
	v_mov_b32_e32 v113, v112
	s_nop 1
	v_permlane32_swap_b32_e32 v112, v113
	s_and_saveexec_b64 s[28:29], s[4:5]
	s_cbranch_execz .LBB0_2757
	v_add_f32_e32 v114, v112, v113
	v_lshlrev_b64 v[112:113], 6, v[142:143]
	v_lshl_add_u64 v[112:113], s[10:11], 0, v[112:113]
	v_lshl_add_u64 v[112:113], s[26:27], 2, v[112:113]
	s_lshl_b32 s2, s48, 2
	v_lshl_add_u64 v[112:113], v[112:113], 0, s[2:3]
	global_store_dword v[112:113], v114, off
.LBB0_2757:
	s_or_b64 exec, exec, s[28:29]
	v_or_b32_e32 v112, 16, v142
	v_ashrrev_i32_e32 v113, 31, v112
	v_lshlrev_b64 v[114:115], 11, v[112:113]
	v_lshl_add_u64 v[114:115], s[8:9], 0, v[114:115]
	v_lshl_add_u64 v[114:115], v[140:141], 1, v[114:115]
	s_waitcnt vmcnt(15)
	v_permlane16_swap_b32_e32 v164, v166
	v_permlane16_swap_b32_e32 v165, v167
	v_lshlrev_b32_e32 v118, 16, v164
	v_and_b32_e32 v119, 0xffff0000, v164
	v_lshlrev_b32_e32 v116, 16, v165
	v_and_b32_e32 v117, 0xffff0000, v165
	v_pk_add_f32 v[110:111], v[110:111], v[116:117]
	v_pk_add_f32 v[108:109], v[108:109], v[118:119]
	s_nop 0
	v_cvt_pk_bf16_f32 v116, v108, v109
	v_cvt_pk_bf16_f32 v117, v110, v111
	v_mul_f32_e32 v109, v109, v109
	v_mov_b32_e32 v224, v116
	v_mov_b32_e32 v225, v117
	v_mul_f32_e32 v111, v111, v111
	v_fmac_f32_e32 v109, v108, v108
	v_fmac_f32_e32 v111, v110, v110
	v_add_f32_e32 v108, v109, v111
	s_waitcnt vmcnt(15)
	v_lshlrev_b32_e32 v116, 16, v166
	v_and_b32_e32 v117, 0xffff0000, v166
	v_lshlrev_b32_e32 v118, 16, v167
	v_and_b32_e32 v119, 0xffff0000, v167
	v_pk_add_f32 v[106:107], v[106:107], v[118:119]
	v_pk_add_f32 v[104:105], v[104:105], v[116:117]
	s_nop 0
	v_cvt_pk_bf16_f32 v116, v104, v105
	v_cvt_pk_bf16_f32 v117, v106, v107
	v_mul_f32_e32 v105, v105, v105
	v_mov_b32_e32 v226, v116
	v_mov_b32_e32 v227, v117
	v_lshl_add_u64 v[234:235], v[114:115], 0, v[232:233]
	s_nop 0
	v_permlane16_swap_b32_e32 v224, v226
	v_permlane16_swap_b32_e32 v225, v227
	global_store_dwordx4 v[234:235], v[224:227], off
	v_mul_f32_e32 v107, v107, v107
	v_fmac_f32_e32 v105, v104, v104
	v_fmac_f32_e32 v107, v106, v106
	v_add_f32_e32 v104, v105, v107
	v_add_f32_e32 v104, v108, v104
	s_waitcnt vmcnt(15)
	v_permlane16_swap_b32_e32 v168, v170
	v_permlane16_swap_b32_e32 v169, v171
	v_lshlrev_b32_e32 v116, 16, v168
	v_and_b32_e32 v117, 0xffff0000, v168
	v_lshlrev_b32_e32 v118, 16, v169
	v_and_b32_e32 v119, 0xffff0000, v169
	v_pk_add_f32 v[102:103], v[102:103], v[118:119]
	v_pk_add_f32 v[100:101], v[100:101], v[116:117]
	s_nop 0
	v_cvt_pk_bf16_f32 v116, v100, v101
	v_cvt_pk_bf16_f32 v117, v102, v103
	v_mul_f32_e32 v101, v101, v101
	v_mul_f32_e32 v103, v103, v103
	v_fmac_f32_e32 v101, v100, v100
	v_fmac_f32_e32 v103, v102, v102
	v_add_f32_e32 v100, v101, v103
	v_add_f32_e32 v104, v104, v100
	v_mov_b32_e32 v228, v116
	v_mov_b32_e32 v229, v117
	s_waitcnt vmcnt(15)
	v_lshlrev_b32_e32 v100, 16, v170
	v_and_b32_e32 v101, 0xffff0000, v170
	v_lshlrev_b32_e32 v102, 16, v171
	v_and_b32_e32 v103, 0xffff0000, v171
	v_pk_add_f32 v[98:99], v[98:99], v[102:103]
	v_pk_add_f32 v[96:97], v[96:97], v[100:101]
	v_mul_f32_e32 v101, v99, v99
	v_mul_f32_e32 v100, v97, v97
	v_fmac_f32_e32 v100, v96, v96
	v_fmac_f32_e32 v101, v98, v98
	v_add_f32_e32 v100, v100, v101
	v_add_f32_e32 v100, v104, v100
	ds_swizzle_b32 v101, v100 offset:swizzle(SWAP,16)
	v_cvt_pk_bf16_f32 v96, v96, v97
	v_cvt_pk_bf16_f32 v97, v98, v99
	v_mov_b32_e32 v230, v96
	v_mov_b32_e32 v231, v97
	v_lshl_add_u64 v[234:235], v[114:115], 0, v[232:233]
	s_nop 0
	v_permlane16_swap_b32_e32 v228, v230
	v_permlane16_swap_b32_e32 v229, v231
	global_store_dwordx4 v[234:235], v[228:231], off offset:256
	s_waitcnt lgkmcnt(0)
	v_add_f32_e32 v96, v100, v101
	v_mov_b32_e32 v97, v96
	s_nop 1
	v_permlane32_swap_b32_e32 v96, v97
	s_and_saveexec_b64 s[28:29], s[4:5]
	s_cbranch_execz .LBB0_2759
	v_add_f32_e32 v98, v96, v97
	v_lshlrev_b64 v[96:97], 6, v[112:113]
	v_lshl_add_u64 v[96:97], s[10:11], 0, v[96:97]
	v_lshl_add_u64 v[96:97], s[26:27], 2, v[96:97]
	s_lshl_b32 s2, s48, 2
	v_lshl_add_u64 v[96:97], v[96:97], 0, s[2:3]
	global_store_dword v[96:97], v98, off
.LBB0_2759:
	s_or_b64 exec, exec, s[28:29]
	v_or_b32_e32 v96, 32, v142
	v_ashrrev_i32_e32 v97, 31, v96
	v_lshlrev_b64 v[98:99], 11, v[96:97]
	v_lshl_add_u64 v[98:99], s[8:9], 0, v[98:99]
	v_lshl_add_u64 v[98:99], v[140:141], 1, v[98:99]
	s_waitcnt vmcnt(15)
	v_permlane16_swap_b32_e32 v172, v174
	v_permlane16_swap_b32_e32 v173, v175
	v_lshlrev_b32_e32 v102, 16, v172
	v_and_b32_e32 v103, 0xffff0000, v172
	v_lshlrev_b32_e32 v100, 16, v173
	v_and_b32_e32 v101, 0xffff0000, v173
	v_pk_add_f32 v[94:95], v[94:95], v[100:101]
	v_pk_add_f32 v[92:93], v[92:93], v[102:103]
	s_nop 0
	v_cvt_pk_bf16_f32 v100, v92, v93
	v_cvt_pk_bf16_f32 v101, v94, v95
	v_mul_f32_e32 v93, v93, v93
	v_mov_b32_e32 v224, v100
	v_mov_b32_e32 v225, v101
	v_mul_f32_e32 v95, v95, v95
	v_fmac_f32_e32 v93, v92, v92
	v_fmac_f32_e32 v95, v94, v94
	v_add_f32_e32 v92, v93, v95
	s_waitcnt vmcnt(15)
	v_lshlrev_b32_e32 v100, 16, v174
	v_and_b32_e32 v101, 0xffff0000, v174
	v_lshlrev_b32_e32 v102, 16, v175
	v_and_b32_e32 v103, 0xffff0000, v175
	v_pk_add_f32 v[90:91], v[90:91], v[102:103]
	v_pk_add_f32 v[88:89], v[88:89], v[100:101]
	s_nop 0
	v_cvt_pk_bf16_f32 v100, v88, v89
	v_cvt_pk_bf16_f32 v101, v90, v91
	v_mul_f32_e32 v89, v89, v89
	v_mov_b32_e32 v226, v100
	v_mov_b32_e32 v227, v101
	v_lshl_add_u64 v[234:235], v[98:99], 0, v[232:233]
	s_nop 0
	v_permlane16_swap_b32_e32 v224, v226
	v_permlane16_swap_b32_e32 v225, v227
	global_store_dwordx4 v[234:235], v[224:227], off
	v_mul_f32_e32 v91, v91, v91
	v_fmac_f32_e32 v89, v88, v88
	v_fmac_f32_e32 v91, v90, v90
	v_add_f32_e32 v88, v89, v91
	v_add_f32_e32 v88, v92, v88
	s_waitcnt vmcnt(15)
	v_permlane16_swap_b32_e32 v176, v178
	v_permlane16_swap_b32_e32 v177, v179
	v_lshlrev_b32_e32 v100, 16, v176
	v_and_b32_e32 v101, 0xffff0000, v176
	v_lshlrev_b32_e32 v102, 16, v177
	v_and_b32_e32 v103, 0xffff0000, v177
	v_pk_add_f32 v[86:87], v[86:87], v[102:103]
	v_pk_add_f32 v[84:85], v[84:85], v[100:101]
	s_nop 0
	v_cvt_pk_bf16_f32 v100, v84, v85
	v_cvt_pk_bf16_f32 v101, v86, v87
	v_mul_f32_e32 v85, v85, v85
	v_mul_f32_e32 v87, v87, v87
	v_fmac_f32_e32 v85, v84, v84
	v_fmac_f32_e32 v87, v86, v86
	v_add_f32_e32 v84, v85, v87
	v_add_f32_e32 v88, v88, v84
	v_mov_b32_e32 v228, v100
	v_mov_b32_e32 v229, v101
	s_waitcnt vmcnt(15)
	v_lshlrev_b32_e32 v84, 16, v178
	v_and_b32_e32 v85, 0xffff0000, v178
	v_lshlrev_b32_e32 v86, 16, v179
	v_and_b32_e32 v87, 0xffff0000, v179
	v_pk_add_f32 v[82:83], v[82:83], v[86:87]
	v_pk_add_f32 v[80:81], v[80:81], v[84:85]
	v_mul_f32_e32 v85, v83, v83
	v_mul_f32_e32 v84, v81, v81
	v_fmac_f32_e32 v84, v80, v80
	v_fmac_f32_e32 v85, v82, v82
	v_add_f32_e32 v84, v84, v85
	v_add_f32_e32 v84, v88, v84
	ds_swizzle_b32 v85, v84 offset:swizzle(SWAP,16)
	v_cvt_pk_bf16_f32 v80, v80, v81
	v_cvt_pk_bf16_f32 v81, v82, v83
	v_mov_b32_e32 v230, v80
	v_mov_b32_e32 v231, v81
	v_lshl_add_u64 v[234:235], v[98:99], 0, v[232:233]
	s_nop 0
	v_permlane16_swap_b32_e32 v228, v230
	v_permlane16_swap_b32_e32 v229, v231
	global_store_dwordx4 v[234:235], v[228:231], off offset:256
	s_waitcnt lgkmcnt(0)
	v_add_f32_e32 v80, v84, v85
	v_mov_b32_e32 v81, v80
	s_nop 1
	v_permlane32_swap_b32_e32 v80, v81
	s_and_saveexec_b64 s[28:29], s[4:5]
	s_cbranch_execz .LBB0_2761
	v_add_f32_e32 v82, v80, v81
	v_lshlrev_b64 v[80:81], 6, v[96:97]
	v_lshl_add_u64 v[80:81], s[10:11], 0, v[80:81]
	v_lshl_add_u64 v[80:81], s[26:27], 2, v[80:81]
	s_lshl_b32 s2, s48, 2
	v_lshl_add_u64 v[80:81], v[80:81], 0, s[2:3]
	global_store_dword v[80:81], v82, off
.LBB0_2761:
	s_or_b64 exec, exec, s[28:29]
	v_or_b32_e32 v80, 48, v142
	v_ashrrev_i32_e32 v81, 31, v80
	v_lshlrev_b64 v[82:83], 11, v[80:81]
	v_lshl_add_u64 v[82:83], s[8:9], 0, v[82:83]
	v_lshl_add_u64 v[82:83], v[140:141], 1, v[82:83]
	s_waitcnt vmcnt(15)
	v_permlane16_swap_b32_e32 v180, v182
	v_permlane16_swap_b32_e32 v181, v183
	v_lshlrev_b32_e32 v86, 16, v180
	v_and_b32_e32 v87, 0xffff0000, v180
	v_lshlrev_b32_e32 v84, 16, v181
	v_and_b32_e32 v85, 0xffff0000, v181
	v_pk_add_f32 v[78:79], v[78:79], v[84:85]
	v_pk_add_f32 v[76:77], v[76:77], v[86:87]
	s_nop 0
	v_cvt_pk_bf16_f32 v84, v76, v77
	v_cvt_pk_bf16_f32 v85, v78, v79
	v_mul_f32_e32 v77, v77, v77
	v_mov_b32_e32 v224, v84
	v_mov_b32_e32 v225, v85
	v_mul_f32_e32 v79, v79, v79
	v_fmac_f32_e32 v77, v76, v76
	v_fmac_f32_e32 v79, v78, v78
	v_add_f32_e32 v76, v77, v79
	s_waitcnt vmcnt(15)
	v_lshlrev_b32_e32 v84, 16, v182
	v_and_b32_e32 v85, 0xffff0000, v182
	v_lshlrev_b32_e32 v86, 16, v183
	v_and_b32_e32 v87, 0xffff0000, v183
	v_pk_add_f32 v[74:75], v[74:75], v[86:87]
	v_pk_add_f32 v[72:73], v[72:73], v[84:85]
	s_nop 0
	v_cvt_pk_bf16_f32 v84, v72, v73
	v_cvt_pk_bf16_f32 v85, v74, v75
	v_mul_f32_e32 v73, v73, v73
	v_mov_b32_e32 v226, v84
	v_mov_b32_e32 v227, v85
	v_lshl_add_u64 v[234:235], v[82:83], 0, v[232:233]
	s_nop 0
	v_permlane16_swap_b32_e32 v224, v226
	v_permlane16_swap_b32_e32 v225, v227
	global_store_dwordx4 v[234:235], v[224:227], off
	v_mul_f32_e32 v75, v75, v75
	v_fmac_f32_e32 v73, v72, v72
	v_fmac_f32_e32 v75, v74, v74
	v_add_f32_e32 v72, v73, v75
	v_add_f32_e32 v72, v76, v72
	s_waitcnt vmcnt(15)
	v_permlane16_swap_b32_e32 v184, v186
	v_permlane16_swap_b32_e32 v185, v187
	v_lshlrev_b32_e32 v84, 16, v184
	v_and_b32_e32 v85, 0xffff0000, v184
	v_lshlrev_b32_e32 v86, 16, v185
	v_and_b32_e32 v87, 0xffff0000, v185
	v_pk_add_f32 v[70:71], v[70:71], v[86:87]
	v_pk_add_f32 v[68:69], v[68:69], v[84:85]
	s_nop 0
	v_cvt_pk_bf16_f32 v84, v68, v69
	v_cvt_pk_bf16_f32 v85, v70, v71
	v_mul_f32_e32 v69, v69, v69
	v_mul_f32_e32 v71, v71, v71
	v_fmac_f32_e32 v69, v68, v68
	v_fmac_f32_e32 v71, v70, v70
	v_add_f32_e32 v68, v69, v71
	v_add_f32_e32 v72, v72, v68
	v_mov_b32_e32 v228, v84
	v_mov_b32_e32 v229, v85
	s_waitcnt vmcnt(15)
	v_lshlrev_b32_e32 v68, 16, v186
	v_and_b32_e32 v69, 0xffff0000, v186
	v_lshlrev_b32_e32 v70, 16, v187
	v_and_b32_e32 v71, 0xffff0000, v187
	v_pk_add_f32 v[66:67], v[66:67], v[70:71]
	v_pk_add_f32 v[64:65], v[64:65], v[68:69]
	v_mul_f32_e32 v69, v67, v67
	v_mul_f32_e32 v68, v65, v65
	v_fmac_f32_e32 v68, v64, v64
	v_fmac_f32_e32 v69, v66, v66
	v_add_f32_e32 v68, v68, v69
	v_add_f32_e32 v68, v72, v68
	ds_swizzle_b32 v69, v68 offset:swizzle(SWAP,16)
	v_cvt_pk_bf16_f32 v64, v64, v65
	v_cvt_pk_bf16_f32 v65, v66, v67
	v_mov_b32_e32 v230, v64
	v_mov_b32_e32 v231, v65
	v_lshl_add_u64 v[234:235], v[82:83], 0, v[232:233]
	s_nop 0
	v_permlane16_swap_b32_e32 v228, v230
	v_permlane16_swap_b32_e32 v229, v231
	global_store_dwordx4 v[234:235], v[228:231], off offset:256
	s_waitcnt lgkmcnt(0)
	v_add_f32_e32 v64, v68, v69
	v_mov_b32_e32 v65, v64
	s_nop 1
	v_permlane32_swap_b32_e32 v64, v65
	s_and_saveexec_b64 s[28:29], s[4:5]
	s_cbranch_execz .LBB0_2763
	v_add_f32_e32 v66, v64, v65
	v_lshlrev_b64 v[64:65], 6, v[80:81]
	v_lshl_add_u64 v[64:65], s[10:11], 0, v[64:65]
	v_lshl_add_u64 v[64:65], s[26:27], 2, v[64:65]
	s_lshl_b32 s2, s48, 2
	v_lshl_add_u64 v[64:65], v[64:65], 0, s[2:3]
	global_store_dword v[64:65], v66, off
.LBB0_2763:
	s_or_b64 exec, exec, s[28:29]
	v_add_u32_e32 v64, 0x80, v142
	v_ashrrev_i32_e32 v65, 31, v64
	v_lshlrev_b64 v[66:67], 11, v[64:65]
	v_lshl_add_u64 v[66:67], s[8:9], 0, v[66:67]
	v_lshl_add_u64 v[66:67], v[140:141], 1, v[66:67]
	s_waitcnt vmcnt(15)
	v_permlane16_swap_b32_e32 v188, v190
	v_permlane16_swap_b32_e32 v189, v191
	v_lshlrev_b32_e32 v70, 16, v188
	v_and_b32_e32 v71, 0xffff0000, v188
	v_lshlrev_b32_e32 v68, 16, v189
	v_and_b32_e32 v69, 0xffff0000, v189
	v_pk_add_f32 v[62:63], v[62:63], v[68:69]
	v_pk_add_f32 v[60:61], v[60:61], v[70:71]
	s_nop 0
	v_cvt_pk_bf16_f32 v68, v60, v61
	v_cvt_pk_bf16_f32 v69, v62, v63
	v_mul_f32_e32 v61, v61, v61
	v_mov_b32_e32 v224, v68
	v_mov_b32_e32 v225, v69
	v_mul_f32_e32 v63, v63, v63
	v_fmac_f32_e32 v61, v60, v60
	v_fmac_f32_e32 v63, v62, v62
	v_add_f32_e32 v60, v61, v63
	s_waitcnt vmcnt(15)
	v_lshlrev_b32_e32 v68, 16, v190
	v_and_b32_e32 v69, 0xffff0000, v190
	v_lshlrev_b32_e32 v70, 16, v191
	v_and_b32_e32 v71, 0xffff0000, v191
	v_pk_add_f32 v[58:59], v[58:59], v[70:71]
	v_pk_add_f32 v[56:57], v[56:57], v[68:69]
	s_nop 0
	v_cvt_pk_bf16_f32 v68, v56, v57
	v_cvt_pk_bf16_f32 v69, v58, v59
	v_mul_f32_e32 v57, v57, v57
	v_mov_b32_e32 v226, v68
	v_mov_b32_e32 v227, v69
	v_lshl_add_u64 v[234:235], v[66:67], 0, v[232:233]
	s_nop 0
	v_permlane16_swap_b32_e32 v224, v226
	v_permlane16_swap_b32_e32 v225, v227
	global_store_dwordx4 v[234:235], v[224:227], off
	v_mul_f32_e32 v59, v59, v59
	v_fmac_f32_e32 v57, v56, v56
	v_fmac_f32_e32 v59, v58, v58
	v_add_f32_e32 v56, v57, v59
	v_add_f32_e32 v56, v60, v56
	s_waitcnt vmcnt(15)
	v_permlane16_swap_b32_e32 v192, v194
	v_permlane16_swap_b32_e32 v193, v195
	v_lshlrev_b32_e32 v68, 16, v192
	v_and_b32_e32 v69, 0xffff0000, v192
	v_lshlrev_b32_e32 v70, 16, v193
	v_and_b32_e32 v71, 0xffff0000, v193
	v_pk_add_f32 v[54:55], v[54:55], v[70:71]
	v_pk_add_f32 v[52:53], v[52:53], v[68:69]
	s_nop 0
	v_cvt_pk_bf16_f32 v68, v52, v53
	v_cvt_pk_bf16_f32 v69, v54, v55
	v_mul_f32_e32 v53, v53, v53
	v_mul_f32_e32 v55, v55, v55
	v_fmac_f32_e32 v53, v52, v52
	v_fmac_f32_e32 v55, v54, v54
	v_add_f32_e32 v52, v53, v55
	v_add_f32_e32 v56, v56, v52
	v_mov_b32_e32 v228, v68
	v_mov_b32_e32 v229, v69
	s_waitcnt vmcnt(15)
	v_lshlrev_b32_e32 v52, 16, v194
	v_and_b32_e32 v53, 0xffff0000, v194
	v_lshlrev_b32_e32 v54, 16, v195
	v_and_b32_e32 v55, 0xffff0000, v195
	v_pk_add_f32 v[50:51], v[50:51], v[54:55]
	v_pk_add_f32 v[48:49], v[48:49], v[52:53]
	v_mul_f32_e32 v53, v51, v51
	v_mul_f32_e32 v52, v49, v49
	v_fmac_f32_e32 v52, v48, v48
	v_fmac_f32_e32 v53, v50, v50
	v_add_f32_e32 v52, v52, v53
	v_add_f32_e32 v52, v56, v52
	ds_swizzle_b32 v53, v52 offset:swizzle(SWAP,16)
	v_cvt_pk_bf16_f32 v48, v48, v49
	v_cvt_pk_bf16_f32 v49, v50, v51
	v_mov_b32_e32 v230, v48
	v_mov_b32_e32 v231, v49
	v_lshl_add_u64 v[234:235], v[66:67], 0, v[232:233]
	s_nop 0
	v_permlane16_swap_b32_e32 v228, v230
	v_permlane16_swap_b32_e32 v229, v231
	global_store_dwordx4 v[234:235], v[228:231], off offset:256
	s_waitcnt lgkmcnt(0)
	v_add_f32_e32 v48, v52, v53
	v_mov_b32_e32 v49, v48
	s_nop 1
	v_permlane32_swap_b32_e32 v48, v49
	s_and_saveexec_b64 s[28:29], s[4:5]
	s_cbranch_execz .LBB0_2765
	v_add_f32_e32 v50, v48, v49
	v_lshlrev_b64 v[48:49], 6, v[64:65]
	v_lshl_add_u64 v[48:49], s[10:11], 0, v[48:49]
	v_lshl_add_u64 v[48:49], s[26:27], 2, v[48:49]
	s_lshl_b32 s2, s48, 2
	v_lshl_add_u64 v[48:49], v[48:49], 0, s[2:3]
	global_store_dword v[48:49], v50, off
.LBB0_2765:
	s_or_b64 exec, exec, s[28:29]
	v_add_u32_e32 v48, 0x90, v142
	v_ashrrev_i32_e32 v49, 31, v48
	v_lshlrev_b64 v[50:51], 11, v[48:49]
	v_lshl_add_u64 v[50:51], s[8:9], 0, v[50:51]
	v_lshl_add_u64 v[50:51], v[140:141], 1, v[50:51]
	s_waitcnt vmcnt(15)
	v_permlane16_swap_b32_e32 v196, v198
	v_permlane16_swap_b32_e32 v197, v199
	v_lshlrev_b32_e32 v54, 16, v196
	v_and_b32_e32 v55, 0xffff0000, v196
	v_lshlrev_b32_e32 v52, 16, v197
	v_and_b32_e32 v53, 0xffff0000, v197
	v_pk_add_f32 v[46:47], v[46:47], v[52:53]
	v_pk_add_f32 v[44:45], v[44:45], v[54:55]
	s_nop 0
	v_cvt_pk_bf16_f32 v52, v44, v45
	v_cvt_pk_bf16_f32 v53, v46, v47
	v_mul_f32_e32 v45, v45, v45
	v_mov_b32_e32 v224, v52
	v_mov_b32_e32 v225, v53
	v_mul_f32_e32 v47, v47, v47
	v_fmac_f32_e32 v45, v44, v44
	v_fmac_f32_e32 v47, v46, v46
	v_add_f32_e32 v44, v45, v47
	s_waitcnt vmcnt(15)
	v_lshlrev_b32_e32 v52, 16, v198
	v_and_b32_e32 v53, 0xffff0000, v198
	v_lshlrev_b32_e32 v54, 16, v199
	v_and_b32_e32 v55, 0xffff0000, v199
	v_pk_add_f32 v[42:43], v[42:43], v[54:55]
	v_pk_add_f32 v[40:41], v[40:41], v[52:53]
	s_nop 0
	v_cvt_pk_bf16_f32 v52, v40, v41
	v_cvt_pk_bf16_f32 v53, v42, v43
	v_mul_f32_e32 v41, v41, v41
	v_mov_b32_e32 v226, v52
	v_mov_b32_e32 v227, v53
	v_lshl_add_u64 v[234:235], v[50:51], 0, v[232:233]
	s_nop 0
	v_permlane16_swap_b32_e32 v224, v226
	v_permlane16_swap_b32_e32 v225, v227
	global_store_dwordx4 v[234:235], v[224:227], off
	v_mul_f32_e32 v43, v43, v43
	v_fmac_f32_e32 v41, v40, v40
	v_fmac_f32_e32 v43, v42, v42
	v_add_f32_e32 v40, v41, v43
	v_add_f32_e32 v40, v44, v40
	s_waitcnt vmcnt(15)
	v_permlane16_swap_b32_e32 v200, v202
	v_permlane16_swap_b32_e32 v201, v203
	v_lshlrev_b32_e32 v52, 16, v200
	v_and_b32_e32 v53, 0xffff0000, v200
	v_lshlrev_b32_e32 v54, 16, v201
	v_and_b32_e32 v55, 0xffff0000, v201
	v_pk_add_f32 v[38:39], v[38:39], v[54:55]
	v_pk_add_f32 v[36:37], v[36:37], v[52:53]
	s_nop 0
	v_cvt_pk_bf16_f32 v52, v36, v37
	v_cvt_pk_bf16_f32 v53, v38, v39
	v_mul_f32_e32 v37, v37, v37
	v_mul_f32_e32 v39, v39, v39
	v_fmac_f32_e32 v37, v36, v36
	v_fmac_f32_e32 v39, v38, v38
	v_add_f32_e32 v36, v37, v39
	v_add_f32_e32 v40, v40, v36
	v_mov_b32_e32 v228, v52
	v_mov_b32_e32 v229, v53
	s_waitcnt vmcnt(15)
	v_lshlrev_b32_e32 v36, 16, v202
	v_and_b32_e32 v37, 0xffff0000, v202
	v_lshlrev_b32_e32 v38, 16, v203
	v_and_b32_e32 v39, 0xffff0000, v203
	v_pk_add_f32 v[34:35], v[34:35], v[38:39]
	v_pk_add_f32 v[32:33], v[32:33], v[36:37]
	v_mul_f32_e32 v37, v35, v35
	v_mul_f32_e32 v36, v33, v33
	v_fmac_f32_e32 v36, v32, v32
	v_fmac_f32_e32 v37, v34, v34
	v_add_f32_e32 v36, v36, v37
	v_add_f32_e32 v36, v40, v36
	ds_swizzle_b32 v37, v36 offset:swizzle(SWAP,16)
	v_cvt_pk_bf16_f32 v32, v32, v33
	v_cvt_pk_bf16_f32 v33, v34, v35
	v_mov_b32_e32 v230, v32
	v_mov_b32_e32 v231, v33
	v_lshl_add_u64 v[234:235], v[50:51], 0, v[232:233]
	s_nop 0
	v_permlane16_swap_b32_e32 v228, v230
	v_permlane16_swap_b32_e32 v229, v231
	global_store_dwordx4 v[234:235], v[228:231], off offset:256
	s_waitcnt lgkmcnt(0)
	v_add_f32_e32 v32, v36, v37
	v_mov_b32_e32 v33, v32
	s_nop 1
	v_permlane32_swap_b32_e32 v32, v33
	s_and_saveexec_b64 s[28:29], s[4:5]
	s_cbranch_execz .LBB0_2767
	v_add_f32_e32 v34, v32, v33
	v_lshlrev_b64 v[32:33], 6, v[48:49]
	v_lshl_add_u64 v[32:33], s[10:11], 0, v[32:33]
	v_lshl_add_u64 v[32:33], s[26:27], 2, v[32:33]
	s_lshl_b32 s2, s48, 2
	v_lshl_add_u64 v[32:33], v[32:33], 0, s[2:3]
	global_store_dword v[32:33], v34, off
.LBB0_2767:
	s_or_b64 exec, exec, s[28:29]
	v_add_u32_e32 v32, 0xa0, v142
	v_ashrrev_i32_e32 v33, 31, v32
	v_lshlrev_b64 v[34:35], 11, v[32:33]
	v_lshl_add_u64 v[34:35], s[8:9], 0, v[34:35]
	v_lshl_add_u64 v[34:35], v[140:141], 1, v[34:35]
	s_waitcnt vmcnt(15)
	v_permlane16_swap_b32_e32 v208, v210
	v_permlane16_swap_b32_e32 v209, v211
	v_lshlrev_b32_e32 v38, 16, v208
	v_and_b32_e32 v39, 0xffff0000, v208
	v_lshlrev_b32_e32 v36, 16, v209
	v_and_b32_e32 v37, 0xffff0000, v209
	v_pk_add_f32 v[30:31], v[30:31], v[36:37]
	v_pk_add_f32 v[28:29], v[28:29], v[38:39]
	s_nop 0
	v_cvt_pk_bf16_f32 v36, v28, v29
	v_cvt_pk_bf16_f32 v37, v30, v31
	v_mul_f32_e32 v29, v29, v29
	v_mov_b32_e32 v224, v36
	v_mov_b32_e32 v225, v37
	v_mul_f32_e32 v31, v31, v31
	v_fmac_f32_e32 v29, v28, v28
	v_fmac_f32_e32 v31, v30, v30
	v_add_f32_e32 v28, v29, v31
	s_waitcnt vmcnt(15)
	v_lshlrev_b32_e32 v36, 16, v210
	v_and_b32_e32 v37, 0xffff0000, v210
	v_lshlrev_b32_e32 v38, 16, v211
	v_and_b32_e32 v39, 0xffff0000, v211
	v_pk_add_f32 v[26:27], v[26:27], v[38:39]
	v_pk_add_f32 v[24:25], v[24:25], v[36:37]
	s_nop 0
	v_cvt_pk_bf16_f32 v36, v24, v25
	v_cvt_pk_bf16_f32 v37, v26, v27
	v_mul_f32_e32 v25, v25, v25
	v_mov_b32_e32 v226, v36
	v_mov_b32_e32 v227, v37
	v_lshl_add_u64 v[234:235], v[34:35], 0, v[232:233]
	s_nop 0
	v_permlane16_swap_b32_e32 v224, v226
	v_permlane16_swap_b32_e32 v225, v227
	global_store_dwordx4 v[234:235], v[224:227], off
	v_mul_f32_e32 v27, v27, v27
	v_fmac_f32_e32 v25, v24, v24
	v_fmac_f32_e32 v27, v26, v26
	v_add_f32_e32 v24, v25, v27
	v_add_f32_e32 v24, v28, v24
	s_waitcnt vmcnt(15)
	v_permlane16_swap_b32_e32 v212, v214
	v_permlane16_swap_b32_e32 v213, v215
	v_lshlrev_b32_e32 v36, 16, v212
	v_and_b32_e32 v37, 0xffff0000, v212
	v_lshlrev_b32_e32 v38, 16, v213
	v_and_b32_e32 v39, 0xffff0000, v213
	v_pk_add_f32 v[22:23], v[22:23], v[38:39]
	v_pk_add_f32 v[20:21], v[20:21], v[36:37]
	s_nop 0
	v_cvt_pk_bf16_f32 v36, v20, v21
	v_cvt_pk_bf16_f32 v37, v22, v23
	v_mul_f32_e32 v21, v21, v21
	v_mul_f32_e32 v23, v23, v23
	v_fmac_f32_e32 v21, v20, v20
	v_fmac_f32_e32 v23, v22, v22
	v_add_f32_e32 v20, v21, v23
	v_add_f32_e32 v24, v24, v20
	v_mov_b32_e32 v228, v36
	v_mov_b32_e32 v229, v37
	s_waitcnt vmcnt(15)
	v_lshlrev_b32_e32 v20, 16, v214
	v_and_b32_e32 v21, 0xffff0000, v214
	v_lshlrev_b32_e32 v22, 16, v215
	v_and_b32_e32 v23, 0xffff0000, v215
	v_pk_add_f32 v[18:19], v[18:19], v[22:23]
	v_pk_add_f32 v[16:17], v[16:17], v[20:21]
	v_mul_f32_e32 v21, v19, v19
	v_mul_f32_e32 v20, v17, v17
	v_fmac_f32_e32 v20, v16, v16
	v_fmac_f32_e32 v21, v18, v18
	v_add_f32_e32 v20, v20, v21
	v_add_f32_e32 v20, v24, v20
	ds_swizzle_b32 v21, v20 offset:swizzle(SWAP,16)
	v_cvt_pk_bf16_f32 v16, v16, v17
	v_cvt_pk_bf16_f32 v17, v18, v19
	v_mov_b32_e32 v230, v16
	v_mov_b32_e32 v231, v17
	v_lshl_add_u64 v[234:235], v[34:35], 0, v[232:233]
	s_nop 0
	v_permlane16_swap_b32_e32 v228, v230
	v_permlane16_swap_b32_e32 v229, v231
	global_store_dwordx4 v[234:235], v[228:231], off offset:256
	s_waitcnt lgkmcnt(0)
	v_add_f32_e32 v16, v20, v21
	v_mov_b32_e32 v17, v16
	s_nop 1
	v_permlane32_swap_b32_e32 v16, v17
	s_and_saveexec_b64 s[28:29], s[4:5]
	s_cbranch_execz .LBB0_2769
	v_add_f32_e32 v18, v16, v17
	v_lshlrev_b64 v[16:17], 6, v[32:33]
	v_lshl_add_u64 v[16:17], s[10:11], 0, v[16:17]
	v_lshl_add_u64 v[16:17], s[26:27], 2, v[16:17]
	s_lshl_b32 s2, s48, 2
	v_lshl_add_u64 v[16:17], v[16:17], 0, s[2:3]
	global_store_dword v[16:17], v18, off
.LBB0_2769:
	s_or_b64 exec, exec, s[28:29]
	v_add_u32_e32 v16, 0xb0, v142
	v_ashrrev_i32_e32 v17, 31, v16
	v_lshlrev_b64 v[18:19], 11, v[16:17]
	v_lshl_add_u64 v[18:19], s[8:9], 0, v[18:19]
	v_lshl_add_u64 v[18:19], v[140:141], 1, v[18:19]
	s_waitcnt vmcnt(15)
	v_permlane16_swap_b32_e32 v216, v218
	v_permlane16_swap_b32_e32 v217, v219
	v_lshlrev_b32_e32 v22, 16, v216
	v_and_b32_e32 v23, 0xffff0000, v216
	v_lshlrev_b32_e32 v20, 16, v217
	v_and_b32_e32 v21, 0xffff0000, v217
	v_pk_add_f32 v[14:15], v[14:15], v[20:21]
	v_pk_add_f32 v[12:13], v[12:13], v[22:23]
	s_nop 0
	v_cvt_pk_bf16_f32 v20, v12, v13
	v_cvt_pk_bf16_f32 v21, v14, v15
	v_mul_f32_e32 v13, v13, v13
	v_mov_b32_e32 v224, v20
	v_mov_b32_e32 v225, v21
	v_mul_f32_e32 v15, v15, v15
	v_fmac_f32_e32 v13, v12, v12
	v_fmac_f32_e32 v15, v14, v14
	v_add_f32_e32 v12, v13, v15
	s_waitcnt vmcnt(15)
	v_lshlrev_b32_e32 v20, 16, v218
	v_and_b32_e32 v21, 0xffff0000, v218
	v_lshlrev_b32_e32 v22, 16, v219
	v_and_b32_e32 v23, 0xffff0000, v219
	v_pk_add_f32 v[10:11], v[10:11], v[22:23]
	v_pk_add_f32 v[8:9], v[8:9], v[20:21]
	s_nop 0
	v_cvt_pk_bf16_f32 v20, v8, v9
	v_cvt_pk_bf16_f32 v21, v10, v11
	v_mul_f32_e32 v9, v9, v9
	v_mov_b32_e32 v226, v20
	v_mov_b32_e32 v227, v21
	v_lshl_add_u64 v[234:235], v[18:19], 0, v[232:233]
	s_nop 0
	v_permlane16_swap_b32_e32 v224, v226
	v_permlane16_swap_b32_e32 v225, v227
	global_store_dwordx4 v[234:235], v[224:227], off
	v_mul_f32_e32 v11, v11, v11
	v_fmac_f32_e32 v9, v8, v8
	v_fmac_f32_e32 v11, v10, v10
	v_add_f32_e32 v8, v9, v11
	v_add_f32_e32 v8, v12, v8
	s_waitcnt vmcnt(15)
	v_permlane16_swap_b32_e32 v220, v222
	v_permlane16_swap_b32_e32 v221, v223
	v_lshlrev_b32_e32 v20, 16, v220
	v_and_b32_e32 v21, 0xffff0000, v220
	v_lshlrev_b32_e32 v22, 16, v221
	v_and_b32_e32 v23, 0xffff0000, v221
	v_pk_add_f32 v[6:7], v[6:7], v[22:23]
	v_pk_add_f32 v[4:5], v[4:5], v[20:21]
	s_nop 0
	v_cvt_pk_bf16_f32 v20, v4, v5
	v_cvt_pk_bf16_f32 v21, v6, v7
	v_mul_f32_e32 v5, v5, v5
	v_mul_f32_e32 v7, v7, v7
	v_fmac_f32_e32 v5, v4, v4
	v_fmac_f32_e32 v7, v6, v6
	v_add_f32_e32 v4, v5, v7
	v_add_f32_e32 v8, v8, v4
	v_mov_b32_e32 v228, v20
	v_mov_b32_e32 v229, v21
	s_waitcnt vmcnt(15)
	v_lshlrev_b32_e32 v4, 16, v222
	v_and_b32_e32 v5, 0xffff0000, v222
	v_lshlrev_b32_e32 v6, 16, v223
	v_and_b32_e32 v7, 0xffff0000, v223
	v_pk_add_f32 v[2:3], v[2:3], v[6:7]
	v_pk_add_f32 v[0:1], v[0:1], v[4:5]
	v_mul_f32_e32 v5, v3, v3
	v_mul_f32_e32 v4, v1, v1
	v_fmac_f32_e32 v4, v0, v0
	v_fmac_f32_e32 v5, v2, v2
	v_add_f32_e32 v4, v4, v5
	v_add_f32_e32 v4, v8, v4
	ds_swizzle_b32 v5, v4 offset:swizzle(SWAP,16)
	v_cvt_pk_bf16_f32 v0, v0, v1
	v_cvt_pk_bf16_f32 v1, v2, v3
	v_mov_b32_e32 v230, v0
	v_mov_b32_e32 v231, v1
	v_lshl_add_u64 v[234:235], v[18:19], 0, v[232:233]
	s_nop 0
	v_permlane16_swap_b32_e32 v228, v230
	v_permlane16_swap_b32_e32 v229, v231
	global_store_dwordx4 v[234:235], v[228:231], off offset:256
	s_waitcnt lgkmcnt(0)
	v_add_f32_e32 v0, v4, v5
	v_mov_b32_e32 v1, v0
	s_nop 1
	v_permlane32_swap_b32_e32 v0, v1
	s_and_saveexec_b64 s[28:29], s[4:5]
	s_cbranch_execz .LBB0_2771
	v_add_f32_e32 v2, v0, v1
	v_lshlrev_b64 v[0:1], 6, v[16:17]
	v_lshl_add_u64 v[0:1], s[10:11], 0, v[0:1]
	v_lshl_add_u64 v[0:1], s[26:27], 2, v[0:1]
	s_lshl_b32 s2, s48, 2
	v_lshl_add_u64 v[0:1], v[0:1], 0, s[2:3]
	global_store_dword v[0:1], v2, off

.LBB0_2927:
	v_lshl_add_u32 v142, s26, 8, v144
	v_ashrrev_i32_e32 v143, 31, v142
	v_lshl_or_b32 v140, s2, 8, v146
	v_lshlrev_b64 v[150:151], 11, v[142:143]
	v_ashrrev_i32_e32 v141, 31, v140
	v_lshl_add_u64 v[150:151], s[10:11], 0, v[150:151]
	v_lshl_add_u64 v[150:151], v[140:141], 1, v[150:151]
	s_mov_b64 s[98:99], 0x8000
	s_mov_b64 s[100:101], 0x28000
	v_bfe_u32 v232, v206, 4, 1
	v_mul_u32_u24_e32 v232, 24, v232
	v_mov_b32_e32 v233, 0
	v_lshl_add_u64 v[234:235], v[150:151], 0, v[232:233]
	global_load_dwordx4 v[156:159], v[234:235], off
	global_load_dwordx4 v[160:163], v[234:235], off offset:256
	v_lshl_add_u64 v[234:235], v[234:235], 0, s[98:99]
	global_load_dwordx4 v[164:167], v[234:235], off
	global_load_dwordx4 v[168:171], v[234:235], off offset:256
	v_lshl_add_u64 v[234:235], v[234:235], 0, s[98:99]
	global_load_dwordx4 v[172:175], v[234:235], off
	global_load_dwordx4 v[176:179], v[234:235], off offset:256
	v_lshl_add_u64 v[234:235], v[234:235], 0, s[98:99]
	global_load_dwordx4 v[180:183], v[234:235], off
	global_load_dwordx4 v[184:187], v[234:235], off offset:256
	v_lshl_add_u64 v[234:235], v[234:235], 0, s[100:101]
	global_load_dwordx4 v[188:191], v[234:235], off
	global_load_dwordx4 v[192:195], v[234:235], off offset:256
	v_lshl_add_u64 v[234:235], v[234:235], 0, s[98:99]
	global_load_dwordx4 v[196:199], v[234:235], off
	global_load_dwordx4 v[200:203], v[234:235], off offset:256
	v_lshl_add_u64 v[234:235], v[234:235], 0, s[98:99]
	global_load_dwordx4 v[208:211], v[234:235], off
	global_load_dwordx4 v[212:215], v[234:235], off offset:256
	v_lshl_add_u64 v[234:235], v[234:235], 0, s[98:99]
	global_load_dwordx4 v[216:219], v[234:235], off
	global_load_dwordx4 v[220:223], v[234:235], off offset:256
	s_lshl_b32 s26, s2, 2
	s_ashr_i32 s27, s26, 31
	s_waitcnt vmcnt(15)
	v_permlane16_swap_b32_e32 v156, v158
	v_permlane16_swap_b32_e32 v157, v159
	v_lshlrev_b32_e32 v154, 16, v156
	v_and_b32_e32 v155, 0xffff0000, v156
	v_lshlrev_b32_e32 v152, 16, v157
	v_and_b32_e32 v153, 0xffff0000, v157
	v_pk_add_f32 v[126:127], v[126:127], v[152:153]
	v_pk_add_f32 v[124:125], v[124:125], v[154:155]
	s_nop 0
	v_cvt_pk_bf16_f32 v152, v124, v125
	v_cvt_pk_bf16_f32 v153, v126, v127
	v_mul_f32_e32 v125, v125, v125
	v_mov_b32_e32 v224, v152
	v_mov_b32_e32 v225, v153
	v_mul_f32_e32 v127, v127, v127
	v_fmac_f32_e32 v125, v124, v124
	v_fmac_f32_e32 v127, v126, v126
	v_add_f32_e32 v124, v125, v127
	s_waitcnt vmcnt(15)
	v_lshlrev_b32_e32 v152, 16, v158
	v_and_b32_e32 v153, 0xffff0000, v158
	v_lshlrev_b32_e32 v154, 16, v159
	v_and_b32_e32 v155, 0xffff0000, v159
	v_pk_add_f32 v[122:123], v[122:123], v[154:155]
	v_pk_add_f32 v[120:121], v[120:121], v[152:153]
	s_nop 0
	v_cvt_pk_bf16_f32 v152, v120, v121
	v_cvt_pk_bf16_f32 v153, v122, v123
	v_mul_f32_e32 v121, v121, v121
	v_mov_b32_e32 v226, v152
	v_mov_b32_e32 v227, v153
	v_lshl_add_u64 v[234:235], v[150:151], 0, v[232:233]
	s_nop 0
	v_permlane16_swap_b32_e32 v224, v226
	v_permlane16_swap_b32_e32 v225, v227
	global_store_dwordx4 v[234:235], v[224:227], off
	v_mul_f32_e32 v123, v123, v123
	v_fmac_f32_e32 v121, v120, v120
	v_fmac_f32_e32 v123, v122, v122
	v_add_f32_e32 v120, v121, v123
	v_add_f32_e32 v120, v124, v120
	s_waitcnt vmcnt(15)
	v_permlane16_swap_b32_e32 v160, v162
	v_permlane16_swap_b32_e32 v161, v163
	v_lshlrev_b32_e32 v152, 16, v160
	v_and_b32_e32 v153, 0xffff0000, v160
	v_lshlrev_b32_e32 v154, 16, v161
	v_and_b32_e32 v155, 0xffff0000, v161
	v_pk_add_f32 v[118:119], v[118:119], v[154:155]
	v_pk_add_f32 v[116:117], v[116:117], v[152:153]
	s_nop 0
	v_cvt_pk_bf16_f32 v152, v116, v117
	v_cvt_pk_bf16_f32 v153, v118, v119
	v_mul_f32_e32 v117, v117, v117
	v_mul_f32_e32 v119, v119, v119
	v_fmac_f32_e32 v117, v116, v116
	v_fmac_f32_e32 v119, v118, v118
	v_add_f32_e32 v116, v117, v119
	v_add_f32_e32 v120, v120, v116
	v_mov_b32_e32 v228, v152
	v_mov_b32_e32 v229, v153
	s_waitcnt vmcnt(15)
	v_lshlrev_b32_e32 v116, 16, v162
	v_and_b32_e32 v117, 0xffff0000, v162
	v_lshlrev_b32_e32 v118, 16, v163
	v_and_b32_e32 v119, 0xffff0000, v163
	v_pk_add_f32 v[114:115], v[114:115], v[118:119]
	v_pk_add_f32 v[112:113], v[112:113], v[116:117]
	v_mul_f32_e32 v117, v115, v115
	v_mul_f32_e32 v116, v113, v113
	v_fmac_f32_e32 v116, v112, v112
	v_fmac_f32_e32 v117, v114, v114
	v_add_f32_e32 v116, v116, v117
	v_add_f32_e32 v116, v120, v116
	ds_swizzle_b32 v117, v116 offset:swizzle(SWAP,16)
	v_cvt_pk_bf16_f32 v112, v112, v113
	v_cvt_pk_bf16_f32 v113, v114, v115
	v_mov_b32_e32 v230, v112
	v_mov_b32_e32 v231, v113
	v_lshl_add_u64 v[234:235], v[150:151], 0, v[232:233]
	s_nop 0
	v_permlane16_swap_b32_e32 v228, v230
	v_permlane16_swap_b32_e32 v229, v231
	global_store_dwordx4 v[234:235], v[228:231], off offset:256
	s_waitcnt lgkmcnt(0)
	v_add_f32_e32 v112, v116, v117
	v_mov_b32_e32 v113, v112
	s_nop 1
	v_permlane32_swap_b32_e32 v112, v113
	s_and_saveexec_b64 s[28:29], s[4:5]
	s_cbranch_execz .LBB0_2929
	v_add_f32_e32 v114, v112, v113
	v_lshlrev_b64 v[112:113], 6, v[142:143]
	v_lshl_add_u64 v[112:113], s[12:13], 0, v[112:113]
	v_lshl_add_u64 v[112:113], s[26:27], 2, v[112:113]
	s_lshl_b32 s2, s48, 2
	v_lshl_add_u64 v[112:113], v[112:113], 0, s[2:3]
	global_store_dword v[112:113], v114, off
.LBB0_2929:
	s_or_b64 exec, exec, s[28:29]
	v_or_b32_e32 v112, 16, v142
	v_ashrrev_i32_e32 v113, 31, v112
	v_lshlrev_b64 v[114:115], 11, v[112:113]
	v_lshl_add_u64 v[114:115], s[10:11], 0, v[114:115]
	v_lshl_add_u64 v[114:115], v[140:141], 1, v[114:115]
	s_waitcnt vmcnt(15)
	v_permlane16_swap_b32_e32 v164, v166
	v_permlane16_swap_b32_e32 v165, v167
	v_lshlrev_b32_e32 v118, 16, v164
	v_and_b32_e32 v119, 0xffff0000, v164
	v_lshlrev_b32_e32 v116, 16, v165
	v_and_b32_e32 v117, 0xffff0000, v165
	v_pk_add_f32 v[110:111], v[110:111], v[116:117]
	v_pk_add_f32 v[108:109], v[108:109], v[118:119]
	s_nop 0
	v_cvt_pk_bf16_f32 v116, v108, v109
	v_cvt_pk_bf16_f32 v117, v110, v111
	v_mul_f32_e32 v109, v109, v109
	v_mov_b32_e32 v224, v116
	v_mov_b32_e32 v225, v117
	v_mul_f32_e32 v111, v111, v111
	v_fmac_f32_e32 v109, v108, v108
	v_fmac_f32_e32 v111, v110, v110
	v_add_f32_e32 v108, v109, v111
	s_waitcnt vmcnt(15)
	v_lshlrev_b32_e32 v116, 16, v166
	v_and_b32_e32 v117, 0xffff0000, v166
	v_lshlrev_b32_e32 v118, 16, v167
	v_and_b32_e32 v119, 0xffff0000, v167
	v_pk_add_f32 v[106:107], v[106:107], v[118:119]
	v_pk_add_f32 v[104:105], v[104:105], v[116:117]
	s_nop 0
	v_cvt_pk_bf16_f32 v116, v104, v105
	v_cvt_pk_bf16_f32 v117, v106, v107
	v_mul_f32_e32 v105, v105, v105
	v_mov_b32_e32 v226, v116
	v_mov_b32_e32 v227, v117
	v_lshl_add_u64 v[234:235], v[114:115], 0, v[232:233]
	s_nop 0
	v_permlane16_swap_b32_e32 v224, v226
	v_permlane16_swap_b32_e32 v225, v227
	global_store_dwordx4 v[234:235], v[224:227], off
	v_mul_f32_e32 v107, v107, v107
	v_fmac_f32_e32 v105, v104, v104
	v_fmac_f32_e32 v107, v106, v106
	v_add_f32_e32 v104, v105, v107
	v_add_f32_e32 v104, v108, v104
	s_waitcnt vmcnt(15)
	v_permlane16_swap_b32_e32 v168, v170
	v_permlane16_swap_b32_e32 v169, v171
	v_lshlrev_b32_e32 v116, 16, v168
	v_and_b32_e32 v117, 0xffff0000, v168
	v_lshlrev_b32_e32 v118, 16, v169
	v_and_b32_e32 v119, 0xffff0000, v169
	v_pk_add_f32 v[102:103], v[102:103], v[118:119]
	v_pk_add_f32 v[100:101], v[100:101], v[116:117]
	s_nop 0
	v_cvt_pk_bf16_f32 v116, v100, v101
	v_cvt_pk_bf16_f32 v117, v102, v103
	v_mul_f32_e32 v101, v101, v101
	v_mul_f32_e32 v103, v103, v103
	v_fmac_f32_e32 v101, v100, v100
	v_fmac_f32_e32 v103, v102, v102
	v_add_f32_e32 v100, v101, v103
	v_add_f32_e32 v104, v104, v100
	v_mov_b32_e32 v228, v116
	v_mov_b32_e32 v229, v117
	s_waitcnt vmcnt(15)
	v_lshlrev_b32_e32 v100, 16, v170
	v_and_b32_e32 v101, 0xffff0000, v170
	v_lshlrev_b32_e32 v102, 16, v171
	v_and_b32_e32 v103, 0xffff0000, v171
	v_pk_add_f32 v[98:99], v[98:99], v[102:103]
	v_pk_add_f32 v[96:97], v[96:97], v[100:101]
	v_mul_f32_e32 v101, v99, v99
	v_mul_f32_e32 v100, v97, v97
	v_fmac_f32_e32 v100, v96, v96
	v_fmac_f32_e32 v101, v98, v98
	v_add_f32_e32 v100, v100, v101
	v_add_f32_e32 v100, v104, v100
	ds_swizzle_b32 v101, v100 offset:swizzle(SWAP,16)
	v_cvt_pk_bf16_f32 v96, v96, v97
	v_cvt_pk_bf16_f32 v97, v98, v99
	v_mov_b32_e32 v230, v96
	v_mov_b32_e32 v231, v97
	v_lshl_add_u64 v[234:235], v[114:115], 0, v[232:233]
	s_nop 0
	v_permlane16_swap_b32_e32 v228, v230
	v_permlane16_swap_b32_e32 v229, v231
	global_store_dwordx4 v[234:235], v[228:231], off offset:256
	s_waitcnt lgkmcnt(0)
	v_add_f32_e32 v96, v100, v101
	v_mov_b32_e32 v97, v96
	s_nop 1
	v_permlane32_swap_b32_e32 v96, v97
	s_and_saveexec_b64 s[28:29], s[4:5]
	s_cbranch_execz .LBB0_2931
	v_add_f32_e32 v98, v96, v97
	v_lshlrev_b64 v[96:97], 6, v[112:113]
	v_lshl_add_u64 v[96:97], s[12:13], 0, v[96:97]
	v_lshl_add_u64 v[96:97], s[26:27], 2, v[96:97]
	s_lshl_b32 s2, s48, 2
	v_lshl_add_u64 v[96:97], v[96:97], 0, s[2:3]
	global_store_dword v[96:97], v98, off
.LBB0_2931:
	s_or_b64 exec, exec, s[28:29]
	v_or_b32_e32 v96, 32, v142
	v_ashrrev_i32_e32 v97, 31, v96
	v_lshlrev_b64 v[98:99], 11, v[96:97]
	v_lshl_add_u64 v[98:99], s[10:11], 0, v[98:99]
	v_lshl_add_u64 v[98:99], v[140:141], 1, v[98:99]
	s_waitcnt vmcnt(15)
	v_permlane16_swap_b32_e32 v172, v174
	v_permlane16_swap_b32_e32 v173, v175
	v_lshlrev_b32_e32 v102, 16, v172
	v_and_b32_e32 v103, 0xffff0000, v172
	v_lshlrev_b32_e32 v100, 16, v173
	v_and_b32_e32 v101, 0xffff0000, v173
	v_pk_add_f32 v[94:95], v[94:95], v[100:101]
	v_pk_add_f32 v[92:93], v[92:93], v[102:103]
	s_nop 0
	v_cvt_pk_bf16_f32 v100, v92, v93
	v_cvt_pk_bf16_f32 v101, v94, v95
	v_mul_f32_e32 v93, v93, v93
	v_mov_b32_e32 v224, v100
	v_mov_b32_e32 v225, v101
	v_mul_f32_e32 v95, v95, v95
	v_fmac_f32_e32 v93, v92, v92
	v_fmac_f32_e32 v95, v94, v94
	v_add_f32_e32 v92, v93, v95
	s_waitcnt vmcnt(15)
	v_lshlrev_b32_e32 v100, 16, v174
	v_and_b32_e32 v101, 0xffff0000, v174
	v_lshlrev_b32_e32 v102, 16, v175
	v_and_b32_e32 v103, 0xffff0000, v175
	v_pk_add_f32 v[90:91], v[90:91], v[102:103]
	v_pk_add_f32 v[88:89], v[88:89], v[100:101]
	s_nop 0
	v_cvt_pk_bf16_f32 v100, v88, v89
	v_cvt_pk_bf16_f32 v101, v90, v91
	v_mul_f32_e32 v89, v89, v89
	v_mov_b32_e32 v226, v100
	v_mov_b32_e32 v227, v101
	v_lshl_add_u64 v[234:235], v[98:99], 0, v[232:233]
	s_nop 0
	v_permlane16_swap_b32_e32 v224, v226
	v_permlane16_swap_b32_e32 v225, v227
	global_store_dwordx4 v[234:235], v[224:227], off
	v_mul_f32_e32 v91, v91, v91
	v_fmac_f32_e32 v89, v88, v88
	v_fmac_f32_e32 v91, v90, v90
	v_add_f32_e32 v88, v89, v91
	v_add_f32_e32 v88, v92, v88
	s_waitcnt vmcnt(15)
	v_permlane16_swap_b32_e32 v176, v178
	v_permlane16_swap_b32_e32 v177, v179
	v_lshlrev_b32_e32 v100, 16, v176
	v_and_b32_e32 v101, 0xffff0000, v176
	v_lshlrev_b32_e32 v102, 16, v177
	v_and_b32_e32 v103, 0xffff0000, v177
	v_pk_add_f32 v[86:87], v[86:87], v[102:103]
	v_pk_add_f32 v[84:85], v[84:85], v[100:101]
	s_nop 0
	v_cvt_pk_bf16_f32 v100, v84, v85
	v_cvt_pk_bf16_f32 v101, v86, v87
	v_mul_f32_e32 v85, v85, v85
	v_mul_f32_e32 v87, v87, v87
	v_fmac_f32_e32 v85, v84, v84
	v_fmac_f32_e32 v87, v86, v86
	v_add_f32_e32 v84, v85, v87
	v_add_f32_e32 v88, v88, v84
	v_mov_b32_e32 v228, v100
	v_mov_b32_e32 v229, v101
	s_waitcnt vmcnt(15)
	v_lshlrev_b32_e32 v84, 16, v178
	v_and_b32_e32 v85, 0xffff0000, v178
	v_lshlrev_b32_e32 v86, 16, v179
	v_and_b32_e32 v87, 0xffff0000, v179
	v_pk_add_f32 v[82:83], v[82:83], v[86:87]
	v_pk_add_f32 v[80:81], v[80:81], v[84:85]
	v_mul_f32_e32 v85, v83, v83
	v_mul_f32_e32 v84, v81, v81
	v_fmac_f32_e32 v84, v80, v80
	v_fmac_f32_e32 v85, v82, v82
	v_add_f32_e32 v84, v84, v85
	v_add_f32_e32 v84, v88, v84
	ds_swizzle_b32 v85, v84 offset:swizzle(SWAP,16)
	v_cvt_pk_bf16_f32 v80, v80, v81
	v_cvt_pk_bf16_f32 v81, v82, v83
	v_mov_b32_e32 v230, v80
	v_mov_b32_e32 v231, v81
	v_lshl_add_u64 v[234:235], v[98:99], 0, v[232:233]
	s_nop 0
	v_permlane16_swap_b32_e32 v228, v230
	v_permlane16_swap_b32_e32 v229, v231
	global_store_dwordx4 v[234:235], v[228:231], off offset:256
	s_waitcnt lgkmcnt(0)
	v_add_f32_e32 v80, v84, v85
	v_mov_b32_e32 v81, v80
	s_nop 1
	v_permlane32_swap_b32_e32 v80, v81
	s_and_saveexec_b64 s[28:29], s[4:5]
	s_cbranch_execz .LBB0_2933
	v_add_f32_e32 v82, v80, v81
	v_lshlrev_b64 v[80:81], 6, v[96:97]
	v_lshl_add_u64 v[80:81], s[12:13], 0, v[80:81]
	v_lshl_add_u64 v[80:81], s[26:27], 2, v[80:81]
	s_lshl_b32 s2, s48, 2
	v_lshl_add_u64 v[80:81], v[80:81], 0, s[2:3]
	global_store_dword v[80:81], v82, off
.LBB0_2933:
	s_or_b64 exec, exec, s[28:29]
	v_or_b32_e32 v80, 48, v142
	v_ashrrev_i32_e32 v81, 31, v80
	v_lshlrev_b64 v[82:83], 11, v[80:81]
	v_lshl_add_u64 v[82:83], s[10:11], 0, v[82:83]
	v_lshl_add_u64 v[82:83], v[140:141], 1, v[82:83]
	s_waitcnt vmcnt(15)
	v_permlane16_swap_b32_e32 v180, v182
	v_permlane16_swap_b32_e32 v181, v183
	v_lshlrev_b32_e32 v86, 16, v180
	v_and_b32_e32 v87, 0xffff0000, v180
	v_lshlrev_b32_e32 v84, 16, v181
	v_and_b32_e32 v85, 0xffff0000, v181
	v_pk_add_f32 v[78:79], v[78:79], v[84:85]
	v_pk_add_f32 v[76:77], v[76:77], v[86:87]
	s_nop 0
	v_cvt_pk_bf16_f32 v84, v76, v77
	v_cvt_pk_bf16_f32 v85, v78, v79
	v_mul_f32_e32 v77, v77, v77
	v_mov_b32_e32 v224, v84
	v_mov_b32_e32 v225, v85
	v_mul_f32_e32 v79, v79, v79
	v_fmac_f32_e32 v77, v76, v76
	v_fmac_f32_e32 v79, v78, v78
	v_add_f32_e32 v76, v77, v79
	s_waitcnt vmcnt(15)
	v_lshlrev_b32_e32 v84, 16, v182
	v_and_b32_e32 v85, 0xffff0000, v182
	v_lshlrev_b32_e32 v86, 16, v183
	v_and_b32_e32 v87, 0xffff0000, v183
	v_pk_add_f32 v[74:75], v[74:75], v[86:87]
	v_pk_add_f32 v[72:73], v[72:73], v[84:85]
	s_nop 0
	v_cvt_pk_bf16_f32 v84, v72, v73
	v_cvt_pk_bf16_f32 v85, v74, v75
	v_mul_f32_e32 v73, v73, v73
	v_mov_b32_e32 v226, v84
	v_mov_b32_e32 v227, v85
	v_lshl_add_u64 v[234:235], v[82:83], 0, v[232:233]
	s_nop 0
	v_permlane16_swap_b32_e32 v224, v226
	v_permlane16_swap_b32_e32 v225, v227
	global_store_dwordx4 v[234:235], v[224:227], off
	v_mul_f32_e32 v75, v75, v75
	v_fmac_f32_e32 v73, v72, v72
	v_fmac_f32_e32 v75, v74, v74
	v_add_f32_e32 v72, v73, v75
	v_add_f32_e32 v72, v76, v72
	s_waitcnt vmcnt(15)
	v_permlane16_swap_b32_e32 v184, v186
	v_permlane16_swap_b32_e32 v185, v187
	v_lshlrev_b32_e32 v84, 16, v184
	v_and_b32_e32 v85, 0xffff0000, v184
	v_lshlrev_b32_e32 v86, 16, v185
	v_and_b32_e32 v87, 0xffff0000, v185
	v_pk_add_f32 v[70:71], v[70:71], v[86:87]
	v_pk_add_f32 v[68:69], v[68:69], v[84:85]
	s_nop 0
	v_cvt_pk_bf16_f32 v84, v68, v69
	v_cvt_pk_bf16_f32 v85, v70, v71
	v_mul_f32_e32 v69, v69, v69
	v_mul_f32_e32 v71, v71, v71
	v_fmac_f32_e32 v69, v68, v68
	v_fmac_f32_e32 v71, v70, v70
	v_add_f32_e32 v68, v69, v71
	v_add_f32_e32 v72, v72, v68
	v_mov_b32_e32 v228, v84
	v_mov_b32_e32 v229, v85
	s_waitcnt vmcnt(15)
	v_lshlrev_b32_e32 v68, 16, v186
	v_and_b32_e32 v69, 0xffff0000, v186
	v_lshlrev_b32_e32 v70, 16, v187
	v_and_b32_e32 v71, 0xffff0000, v187
	v_pk_add_f32 v[66:67], v[66:67], v[70:71]
	v_pk_add_f32 v[64:65], v[64:65], v[68:69]
	v_mul_f32_e32 v69, v67, v67
	v_mul_f32_e32 v68, v65, v65
	v_fmac_f32_e32 v68, v64, v64
	v_fmac_f32_e32 v69, v66, v66
	v_add_f32_e32 v68, v68, v69
	v_add_f32_e32 v68, v72, v68
	ds_swizzle_b32 v69, v68 offset:swizzle(SWAP,16)
	v_cvt_pk_bf16_f32 v64, v64, v65
	v_cvt_pk_bf16_f32 v65, v66, v67
	v_mov_b32_e32 v230, v64
	v_mov_b32_e32 v231, v65
	v_lshl_add_u64 v[234:235], v[82:83], 0, v[232:233]
	s_nop 0
	v_permlane16_swap_b32_e32 v228, v230
	v_permlane16_swap_b32_e32 v229, v231
	global_store_dwordx4 v[234:235], v[228:231], off offset:256
	s_waitcnt lgkmcnt(0)
	v_add_f32_e32 v64, v68, v69
	v_mov_b32_e32 v65, v64
	s_nop 1
	v_permlane32_swap_b32_e32 v64, v65
	s_and_saveexec_b64 s[28:29], s[4:5]
	s_cbranch_execz .LBB0_2935
	v_add_f32_e32 v66, v64, v65
	v_lshlrev_b64 v[64:65], 6, v[80:81]
	v_lshl_add_u64 v[64:65], s[12:13], 0, v[64:65]
	v_lshl_add_u64 v[64:65], s[26:27], 2, v[64:65]
	s_lshl_b32 s2, s48, 2
	v_lshl_add_u64 v[64:65], v[64:65], 0, s[2:3]
	global_store_dword v[64:65], v66, off
.LBB0_2935:
	s_or_b64 exec, exec, s[28:29]
	v_add_u32_e32 v64, 0x80, v142
	v_ashrrev_i32_e32 v65, 31, v64
	v_lshlrev_b64 v[66:67], 11, v[64:65]
	v_lshl_add_u64 v[66:67], s[10:11], 0, v[66:67]
	v_lshl_add_u64 v[66:67], v[140:141], 1, v[66:67]
	s_waitcnt vmcnt(15)
	v_permlane16_swap_b32_e32 v188, v190
	v_permlane16_swap_b32_e32 v189, v191
	v_lshlrev_b32_e32 v70, 16, v188
	v_and_b32_e32 v71, 0xffff0000, v188
	v_lshlrev_b32_e32 v68, 16, v189
	v_and_b32_e32 v69, 0xffff0000, v189
	v_pk_add_f32 v[62:63], v[62:63], v[68:69]
	v_pk_add_f32 v[60:61], v[60:61], v[70:71]
	s_nop 0
	v_cvt_pk_bf16_f32 v68, v60, v61
	v_cvt_pk_bf16_f32 v69, v62, v63
	v_mul_f32_e32 v61, v61, v61
	v_mov_b32_e32 v224, v68
	v_mov_b32_e32 v225, v69
	v_mul_f32_e32 v63, v63, v63
	v_fmac_f32_e32 v61, v60, v60
	v_fmac_f32_e32 v63, v62, v62
	v_add_f32_e32 v60, v61, v63
	s_waitcnt vmcnt(15)
	v_lshlrev_b32_e32 v68, 16, v190
	v_and_b32_e32 v69, 0xffff0000, v190
	v_lshlrev_b32_e32 v70, 16, v191
	v_and_b32_e32 v71, 0xffff0000, v191
	v_pk_add_f32 v[58:59], v[58:59], v[70:71]
	v_pk_add_f32 v[56:57], v[56:57], v[68:69]
	s_nop 0
	v_cvt_pk_bf16_f32 v68, v56, v57
	v_cvt_pk_bf16_f32 v69, v58, v59
	v_mul_f32_e32 v57, v57, v57
	v_mov_b32_e32 v226, v68
	v_mov_b32_e32 v227, v69
	v_lshl_add_u64 v[234:235], v[66:67], 0, v[232:233]
	s_nop 0
	v_permlane16_swap_b32_e32 v224, v226
	v_permlane16_swap_b32_e32 v225, v227
	global_store_dwordx4 v[234:235], v[224:227], off
	v_mul_f32_e32 v59, v59, v59
	v_fmac_f32_e32 v57, v56, v56
	v_fmac_f32_e32 v59, v58, v58
	v_add_f32_e32 v56, v57, v59
	v_add_f32_e32 v56, v60, v56
	s_waitcnt vmcnt(15)
	v_permlane16_swap_b32_e32 v192, v194
	v_permlane16_swap_b32_e32 v193, v195
	v_lshlrev_b32_e32 v68, 16, v192
	v_and_b32_e32 v69, 0xffff0000, v192
	v_lshlrev_b32_e32 v70, 16, v193
	v_and_b32_e32 v71, 0xffff0000, v193
	v_pk_add_f32 v[54:55], v[54:55], v[70:71]
	v_pk_add_f32 v[52:53], v[52:53], v[68:69]
	s_nop 0
	v_cvt_pk_bf16_f32 v68, v52, v53
	v_cvt_pk_bf16_f32 v69, v54, v55
	v_mul_f32_e32 v53, v53, v53
	v_mul_f32_e32 v55, v55, v55
	v_fmac_f32_e32 v53, v52, v52
	v_fmac_f32_e32 v55, v54, v54
	v_add_f32_e32 v52, v53, v55
	v_add_f32_e32 v56, v56, v52
	v_mov_b32_e32 v228, v68
	v_mov_b32_e32 v229, v69
	s_waitcnt vmcnt(15)
	v_lshlrev_b32_e32 v52, 16, v194
	v_and_b32_e32 v53, 0xffff0000, v194
	v_lshlrev_b32_e32 v54, 16, v195
	v_and_b32_e32 v55, 0xffff0000, v195
	v_pk_add_f32 v[50:51], v[50:51], v[54:55]
	v_pk_add_f32 v[48:49], v[48:49], v[52:53]
	v_mul_f32_e32 v53, v51, v51
	v_mul_f32_e32 v52, v49, v49
	v_fmac_f32_e32 v52, v48, v48
	v_fmac_f32_e32 v53, v50, v50
	v_add_f32_e32 v52, v52, v53
	v_add_f32_e32 v52, v56, v52
	ds_swizzle_b32 v53, v52 offset:swizzle(SWAP,16)
	v_cvt_pk_bf16_f32 v48, v48, v49
	v_cvt_pk_bf16_f32 v49, v50, v51
	v_mov_b32_e32 v230, v48
	v_mov_b32_e32 v231, v49
	v_lshl_add_u64 v[234:235], v[66:67], 0, v[232:233]
	s_nop 0
	v_permlane16_swap_b32_e32 v228, v230
	v_permlane16_swap_b32_e32 v229, v231
	global_store_dwordx4 v[234:235], v[228:231], off offset:256
	s_waitcnt lgkmcnt(0)
	v_add_f32_e32 v48, v52, v53
	v_mov_b32_e32 v49, v48
	s_nop 1
	v_permlane32_swap_b32_e32 v48, v49
	s_and_saveexec_b64 s[28:29], s[4:5]
	s_cbranch_execz .LBB0_2937
	v_add_f32_e32 v50, v48, v49
	v_lshlrev_b64 v[48:49], 6, v[64:65]
	v_lshl_add_u64 v[48:49], s[12:13], 0, v[48:49]
	v_lshl_add_u64 v[48:49], s[26:27], 2, v[48:49]
	s_lshl_b32 s2, s48, 2
	v_lshl_add_u64 v[48:49], v[48:49], 0, s[2:3]
	global_store_dword v[48:49], v50, off
.LBB0_2937:
	s_or_b64 exec, exec, s[28:29]
	v_add_u32_e32 v48, 0x90, v142
	v_ashrrev_i32_e32 v49, 31, v48
	v_lshlrev_b64 v[50:51], 11, v[48:49]
	v_lshl_add_u64 v[50:51], s[10:11], 0, v[50:51]
	v_lshl_add_u64 v[50:51], v[140:141], 1, v[50:51]
	s_waitcnt vmcnt(15)
	v_permlane16_swap_b32_e32 v196, v198
	v_permlane16_swap_b32_e32 v197, v199
	v_lshlrev_b32_e32 v54, 16, v196
	v_and_b32_e32 v55, 0xffff0000, v196
	v_lshlrev_b32_e32 v52, 16, v197
	v_and_b32_e32 v53, 0xffff0000, v197
	v_pk_add_f32 v[46:47], v[46:47], v[52:53]
	v_pk_add_f32 v[44:45], v[44:45], v[54:55]
	s_nop 0
	v_cvt_pk_bf16_f32 v52, v44, v45
	v_cvt_pk_bf16_f32 v53, v46, v47
	v_mul_f32_e32 v45, v45, v45
	v_mov_b32_e32 v224, v52
	v_mov_b32_e32 v225, v53
	v_mul_f32_e32 v47, v47, v47
	v_fmac_f32_e32 v45, v44, v44
	v_fmac_f32_e32 v47, v46, v46
	v_add_f32_e32 v44, v45, v47
	s_waitcnt vmcnt(15)
	v_lshlrev_b32_e32 v52, 16, v198
	v_and_b32_e32 v53, 0xffff0000, v198
	v_lshlrev_b32_e32 v54, 16, v199
	v_and_b32_e32 v55, 0xffff0000, v199
	v_pk_add_f32 v[42:43], v[42:43], v[54:55]
	v_pk_add_f32 v[40:41], v[40:41], v[52:53]
	s_nop 0
	v_cvt_pk_bf16_f32 v52, v40, v41
	v_cvt_pk_bf16_f32 v53, v42, v43
	v_mul_f32_e32 v41, v41, v41
	v_mov_b32_e32 v226, v52
	v_mov_b32_e32 v227, v53
	v_lshl_add_u64 v[234:235], v[50:51], 0, v[232:233]
	s_nop 0
	v_permlane16_swap_b32_e32 v224, v226
	v_permlane16_swap_b32_e32 v225, v227
	global_store_dwordx4 v[234:235], v[224:227], off
	v_mul_f32_e32 v43, v43, v43
	v_fmac_f32_e32 v41, v40, v40
	v_fmac_f32_e32 v43, v42, v42
	v_add_f32_e32 v40, v41, v43
	v_add_f32_e32 v40, v44, v40
	s_waitcnt vmcnt(15)
	v_permlane16_swap_b32_e32 v200, v202
	v_permlane16_swap_b32_e32 v201, v203
	v_lshlrev_b32_e32 v52, 16, v200
	v_and_b32_e32 v53, 0xffff0000, v200
	v_lshlrev_b32_e32 v54, 16, v201
	v_and_b32_e32 v55, 0xffff0000, v201
	v_pk_add_f32 v[38:39], v[38:39], v[54:55]
	v_pk_add_f32 v[36:37], v[36:37], v[52:53]
	s_nop 0
	v_cvt_pk_bf16_f32 v52, v36, v37
	v_cvt_pk_bf16_f32 v53, v38, v39
	v_mul_f32_e32 v37, v37, v37
	v_mul_f32_e32 v39, v39, v39
	v_fmac_f32_e32 v37, v36, v36
	v_fmac_f32_e32 v39, v38, v38
	v_add_f32_e32 v36, v37, v39
	v_add_f32_e32 v40, v40, v36
	v_mov_b32_e32 v228, v52
	v_mov_b32_e32 v229, v53
	s_waitcnt vmcnt(15)
	v_lshlrev_b32_e32 v36, 16, v202
	v_and_b32_e32 v37, 0xffff0000, v202
	v_lshlrev_b32_e32 v38, 16, v203
	v_and_b32_e32 v39, 0xffff0000, v203
	v_pk_add_f32 v[34:35], v[34:35], v[38:39]
	v_pk_add_f32 v[32:33], v[32:33], v[36:37]
	v_mul_f32_e32 v37, v35, v35
	v_mul_f32_e32 v36, v33, v33
	v_fmac_f32_e32 v36, v32, v32
	v_fmac_f32_e32 v37, v34, v34
	v_add_f32_e32 v36, v36, v37
	v_add_f32_e32 v36, v40, v36
	ds_swizzle_b32 v37, v36 offset:swizzle(SWAP,16)
	v_cvt_pk_bf16_f32 v32, v32, v33
	v_cvt_pk_bf16_f32 v33, v34, v35
	v_mov_b32_e32 v230, v32
	v_mov_b32_e32 v231, v33
	v_lshl_add_u64 v[234:235], v[50:51], 0, v[232:233]
	s_nop 0
	v_permlane16_swap_b32_e32 v228, v230
	v_permlane16_swap_b32_e32 v229, v231
	global_store_dwordx4 v[234:235], v[228:231], off offset:256
	s_waitcnt lgkmcnt(0)
	v_add_f32_e32 v32, v36, v37
	v_mov_b32_e32 v33, v32
	s_nop 1
	v_permlane32_swap_b32_e32 v32, v33
	s_and_saveexec_b64 s[28:29], s[4:5]
	s_cbranch_execz .LBB0_2939
	v_add_f32_e32 v34, v32, v33
	v_lshlrev_b64 v[32:33], 6, v[48:49]
	v_lshl_add_u64 v[32:33], s[12:13], 0, v[32:33]
	v_lshl_add_u64 v[32:33], s[26:27], 2, v[32:33]
	s_lshl_b32 s2, s48, 2
	v_lshl_add_u64 v[32:33], v[32:33], 0, s[2:3]
	global_store_dword v[32:33], v34, off
.LBB0_2939:
	s_or_b64 exec, exec, s[28:29]
	v_add_u32_e32 v32, 0xa0, v142
	v_ashrrev_i32_e32 v33, 31, v32
	v_lshlrev_b64 v[34:35], 11, v[32:33]
	v_lshl_add_u64 v[34:35], s[10:11], 0, v[34:35]
	v_lshl_add_u64 v[34:35], v[140:141], 1, v[34:35]
	s_waitcnt vmcnt(15)
	v_permlane16_swap_b32_e32 v208, v210
	v_permlane16_swap_b32_e32 v209, v211
	v_lshlrev_b32_e32 v38, 16, v208
	v_and_b32_e32 v39, 0xffff0000, v208
	v_lshlrev_b32_e32 v36, 16, v209
	v_and_b32_e32 v37, 0xffff0000, v209
	v_pk_add_f32 v[30:31], v[30:31], v[36:37]
	v_pk_add_f32 v[28:29], v[28:29], v[38:39]
	s_nop 0
	v_cvt_pk_bf16_f32 v36, v28, v29
	v_cvt_pk_bf16_f32 v37, v30, v31
	v_mul_f32_e32 v29, v29, v29
	v_mov_b32_e32 v224, v36
	v_mov_b32_e32 v225, v37
	v_mul_f32_e32 v31, v31, v31
	v_fmac_f32_e32 v29, v28, v28
	v_fmac_f32_e32 v31, v30, v30
	v_add_f32_e32 v28, v29, v31
	s_waitcnt vmcnt(15)
	v_lshlrev_b32_e32 v36, 16, v210
	v_and_b32_e32 v37, 0xffff0000, v210
	v_lshlrev_b32_e32 v38, 16, v211
	v_and_b32_e32 v39, 0xffff0000, v211
	v_pk_add_f32 v[26:27], v[26:27], v[38:39]
	v_pk_add_f32 v[24:25], v[24:25], v[36:37]
	s_nop 0
	v_cvt_pk_bf16_f32 v36, v24, v25
	v_cvt_pk_bf16_f32 v37, v26, v27
	v_mul_f32_e32 v25, v25, v25
	v_mov_b32_e32 v226, v36
	v_mov_b32_e32 v227, v37
	v_lshl_add_u64 v[234:235], v[34:35], 0, v[232:233]
	s_nop 0
	v_permlane16_swap_b32_e32 v224, v226
	v_permlane16_swap_b32_e32 v225, v227
	global_store_dwordx4 v[234:235], v[224:227], off
	v_mul_f32_e32 v27, v27, v27
	v_fmac_f32_e32 v25, v24, v24
	v_fmac_f32_e32 v27, v26, v26
	v_add_f32_e32 v24, v25, v27
	v_add_f32_e32 v24, v28, v24
	s_waitcnt vmcnt(15)
	v_permlane16_swap_b32_e32 v212, v214
	v_permlane16_swap_b32_e32 v213, v215
	v_lshlrev_b32_e32 v36, 16, v212
	v_and_b32_e32 v37, 0xffff0000, v212
	v_lshlrev_b32_e32 v38, 16, v213
	v_and_b32_e32 v39, 0xffff0000, v213
	v_pk_add_f32 v[22:23], v[22:23], v[38:39]
	v_pk_add_f32 v[20:21], v[20:21], v[36:37]
	s_nop 0
	v_cvt_pk_bf16_f32 v36, v20, v21
	v_cvt_pk_bf16_f32 v37, v22, v23
	v_mul_f32_e32 v21, v21, v21
	v_mul_f32_e32 v23, v23, v23
	v_fmac_f32_e32 v21, v20, v20
	v_fmac_f32_e32 v23, v22, v22
	v_add_f32_e32 v20, v21, v23
	v_add_f32_e32 v24, v24, v20
	v_mov_b32_e32 v228, v36
	v_mov_b32_e32 v229, v37
	s_waitcnt vmcnt(15)
	v_lshlrev_b32_e32 v20, 16, v214
	v_and_b32_e32 v21, 0xffff0000, v214
	v_lshlrev_b32_e32 v22, 16, v215
	v_and_b32_e32 v23, 0xffff0000, v215
	v_pk_add_f32 v[18:19], v[18:19], v[22:23]
	v_pk_add_f32 v[16:17], v[16:17], v[20:21]
	v_mul_f32_e32 v21, v19, v19
	v_mul_f32_e32 v20, v17, v17
	v_fmac_f32_e32 v20, v16, v16
	v_fmac_f32_e32 v21, v18, v18
	v_add_f32_e32 v20, v20, v21
	v_add_f32_e32 v20, v24, v20
	ds_swizzle_b32 v21, v20 offset:swizzle(SWAP,16)
	v_cvt_pk_bf16_f32 v16, v16, v17
	v_cvt_pk_bf16_f32 v17, v18, v19
	v_mov_b32_e32 v230, v16
	v_mov_b32_e32 v231, v17
	v_lshl_add_u64 v[234:235], v[34:35], 0, v[232:233]
	s_nop 0
	v_permlane16_swap_b32_e32 v228, v230
	v_permlane16_swap_b32_e32 v229, v231
	global_store_dwordx4 v[234:235], v[228:231], off offset:256
	s_waitcnt lgkmcnt(0)
	v_add_f32_e32 v16, v20, v21
	v_mov_b32_e32 v17, v16
	s_nop 1
	v_permlane32_swap_b32_e32 v16, v17
	s_and_saveexec_b64 s[28:29], s[4:5]
	s_cbranch_execz .LBB0_2941
	v_add_f32_e32 v18, v16, v17
	v_lshlrev_b64 v[16:17], 6, v[32:33]
	v_lshl_add_u64 v[16:17], s[12:13], 0, v[16:17]
	v_lshl_add_u64 v[16:17], s[26:27], 2, v[16:17]
	s_lshl_b32 s2, s48, 2
	v_lshl_add_u64 v[16:17], v[16:17], 0, s[2:3]
	global_store_dword v[16:17], v18, off
.LBB0_2941:
	s_or_b64 exec, exec, s[28:29]
	v_add_u32_e32 v16, 0xb0, v142
	v_ashrrev_i32_e32 v17, 31, v16
	v_lshlrev_b64 v[18:19], 11, v[16:17]
	v_lshl_add_u64 v[18:19], s[10:11], 0, v[18:19]
	v_lshl_add_u64 v[18:19], v[140:141], 1, v[18:19]
	s_waitcnt vmcnt(15)
	v_permlane16_swap_b32_e32 v216, v218
	v_permlane16_swap_b32_e32 v217, v219
	v_lshlrev_b32_e32 v22, 16, v216
	v_and_b32_e32 v23, 0xffff0000, v216
	v_lshlrev_b32_e32 v20, 16, v217
	v_and_b32_e32 v21, 0xffff0000, v217
	v_pk_add_f32 v[14:15], v[14:15], v[20:21]
	v_pk_add_f32 v[12:13], v[12:13], v[22:23]
	s_nop 0
	v_cvt_pk_bf16_f32 v20, v12, v13
	v_cvt_pk_bf16_f32 v21, v14, v15
	v_mul_f32_e32 v13, v13, v13
	v_mov_b32_e32 v224, v20
	v_mov_b32_e32 v225, v21
	v_mul_f32_e32 v15, v15, v15
	v_fmac_f32_e32 v13, v12, v12
	v_fmac_f32_e32 v15, v14, v14
	v_add_f32_e32 v12, v13, v15
	s_waitcnt vmcnt(15)
	v_lshlrev_b32_e32 v20, 16, v218
	v_and_b32_e32 v21, 0xffff0000, v218
	v_lshlrev_b32_e32 v22, 16, v219
	v_and_b32_e32 v23, 0xffff0000, v219
	v_pk_add_f32 v[10:11], v[10:11], v[22:23]
	v_pk_add_f32 v[8:9], v[8:9], v[20:21]
	s_nop 0
	v_cvt_pk_bf16_f32 v20, v8, v9
	v_cvt_pk_bf16_f32 v21, v10, v11
	v_mul_f32_e32 v9, v9, v9
	v_mov_b32_e32 v226, v20
	v_mov_b32_e32 v227, v21
	v_lshl_add_u64 v[234:235], v[18:19], 0, v[232:233]
	s_nop 0
	v_permlane16_swap_b32_e32 v224, v226
	v_permlane16_swap_b32_e32 v225, v227
	global_store_dwordx4 v[234:235], v[224:227], off
	v_mul_f32_e32 v11, v11, v11
	v_fmac_f32_e32 v9, v8, v8
	v_fmac_f32_e32 v11, v10, v10
	v_add_f32_e32 v8, v9, v11
	v_add_f32_e32 v8, v12, v8
	s_waitcnt vmcnt(15)
	v_permlane16_swap_b32_e32 v220, v222
	v_permlane16_swap_b32_e32 v221, v223
	v_lshlrev_b32_e32 v20, 16, v220
	v_and_b32_e32 v21, 0xffff0000, v220
	v_lshlrev_b32_e32 v22, 16, v221
	v_and_b32_e32 v23, 0xffff0000, v221
	v_pk_add_f32 v[6:7], v[6:7], v[22:23]
	v_pk_add_f32 v[4:5], v[4:5], v[20:21]
	s_nop 0
	v_cvt_pk_bf16_f32 v20, v4, v5
	v_cvt_pk_bf16_f32 v21, v6, v7
	v_mul_f32_e32 v5, v5, v5
	v_mul_f32_e32 v7, v7, v7
	v_fmac_f32_e32 v5, v4, v4
	v_fmac_f32_e32 v7, v6, v6
	v_add_f32_e32 v4, v5, v7
	v_add_f32_e32 v8, v8, v4
	v_mov_b32_e32 v228, v20
	v_mov_b32_e32 v229, v21
	s_waitcnt vmcnt(15)
	v_lshlrev_b32_e32 v4, 16, v222
	v_and_b32_e32 v5, 0xffff0000, v222
	v_lshlrev_b32_e32 v6, 16, v223
	v_and_b32_e32 v7, 0xffff0000, v223
	v_pk_add_f32 v[2:3], v[2:3], v[6:7]
	v_pk_add_f32 v[0:1], v[0:1], v[4:5]
	v_mul_f32_e32 v5, v3, v3
	v_mul_f32_e32 v4, v1, v1
	v_fmac_f32_e32 v4, v0, v0
	v_fmac_f32_e32 v5, v2, v2
	v_add_f32_e32 v4, v4, v5
	v_add_f32_e32 v4, v8, v4
	ds_swizzle_b32 v5, v4 offset:swizzle(SWAP,16)
	v_cvt_pk_bf16_f32 v0, v0, v1
	v_cvt_pk_bf16_f32 v1, v2, v3
	v_mov_b32_e32 v230, v0
	v_mov_b32_e32 v231, v1
	v_lshl_add_u64 v[234:235], v[18:19], 0, v[232:233]
	s_nop 0
	v_permlane16_swap_b32_e32 v228, v230
	v_permlane16_swap_b32_e32 v229, v231
	global_store_dwordx4 v[234:235], v[228:231], off offset:256
	s_waitcnt lgkmcnt(0)
	v_add_f32_e32 v0, v4, v5
	v_mov_b32_e32 v1, v0
	s_nop 1
	v_permlane32_swap_b32_e32 v0, v1
	s_and_saveexec_b64 s[28:29], s[4:5]
	s_cbranch_execz .LBB0_2943
	v_add_f32_e32 v2, v0, v1
	v_lshlrev_b64 v[0:1], 6, v[16:17]
	v_lshl_add_u64 v[0:1], s[12:13], 0, v[0:1]
	v_lshl_add_u64 v[0:1], s[26:27], 2, v[0:1]
	s_lshl_b32 s2, s48, 2
	v_lshl_add_u64 v[0:1], v[0:1], 0, s[2:3]
	global_store_dword v[0:1], v2, off
